# FFN-up epilogues: per-row rms scales computed once per workgroup row panel and kept in 8 VGPRs; later tiles skip the reload+reduce+1/sqrt chain (fast epilogue copy)
# speedup vs baseline: 1.0678x; 1.0216x over previous
; #define PG8_STAGE(bufoff, gbase, voff) do { _Pragma("unroll") for (int _i = 0; _i < 2; ++_i) \
;         __builtin_amdgcn_global_load_lds((const unsigned*)((const char*)(gbase) + (voff)[_i]), (PG8_LAS unsigned*)(lds + (bufoff) + ldsw + _i * 8192), 16, 0, 0); } while (0)
; #define PG8_WAIT_V(n) asm volatile("s_waitcnt vmcnt(" #n ")" ::: "memory")
; #define PG8_BAR __builtin_amdgcn_s_barrier()
; template <class Epi, class Sched, bool ALIGN_EPI = false, bool SP2 = false>
; __device__ __forceinline__ void gemm_phase(PG8_LAS unsigned char* lds, const Gemm g, const Sched& S, const Epi& E) {
;     ...
;     Unit cur, nxt; int ui = 0;
;     if (!S.next(0, cur)) return;
;     f32x4 acc[2][2][4][2];
; #pragma unroll
;     for (int a = 0; a < 2; ++a)
; #pragma unroll
;         for (int b = 0; b < 2; ++b)
; #pragma unroll
;             for (int m = 0; m < 4; ++m)
; #pragma unroll
;                 for (int n = 0; n < 2; ++n) acc[a][b][m][n] = (f32x4){0.f, 0.f, 0.f, 0.f};
;     bf16x8 At[4][2], B0[2][2], B1[2][2];
;     const char* cA = (const char*)g.A + (size_t)cur.pm * tstep; const char* cB = (const char*)g.Bt + (size_t)cur.pn * tstep;
;     S.a_ready(cur);
;     if constexpr (SP2) {
;         PG8_STAGE(PG8_SB(0, 0), cB, voffB); PG8_STAGE(PG8_SB(0, 1), cB + hstep, voffB); PG8_STAGE(PG8_SA(0, 0), cA, voffA); PG8_STAGE(PG8_SA(0, 1), cA + hstep, voffA);
;         if (wr == 1) PG8_BAR;
;         PG8_WAIT_V(2); PG8_BAR;
;         PG8_STAGE(PG8_SB(1, 0), cB + kstep, voffB); PG8_STAGE(PG8_SA(1, 0), cA + kstep, voffA); PG8_STAGE(PG8_SB(1, 1), cB + hstep + kstep, voffB);
;         PG8_WAIT_V(6); PG8_BAR;
; __global__ void __launch_bounds__(NTHR, 2) fwd_kernel(Args args) {
;     ...
;     if (IN(1)) {
;         pg8::Gemm g{actA, (const bf16_t*)(ws + WS_W13A), T_, 2 * FF_, D_}; pg8::StaticOrder S; S.init(T_, 2 * FF_, C.G, C.bid);
;         EpiSwiGLU E{hid, ssqA};
;         pg8::gemm_phase<EpiSwiGLU, pg8::StaticOrder, true, true>(C.lds, g, S, E);
.LBB0_242:
	s_mov_b32 s100, -1
	v_readlane_b32 s0, v254, 1
	v_readlane_b32 s1, v254, 2
	s_load_dwordx16 s[8:23], s[0:1], 0x80
	s_cmp_lt_i32 s76, 2
	s_cselect_b64 s[0:1], -1, 0
	s_waitcnt lgkmcnt(0)
	v_writelane_b32 v254, s8, 42
	s_nop 1
	v_writelane_b32 v254, s9, 43
	v_writelane_b32 v254, s10, 44
	v_writelane_b32 v254, s11, 45
	v_writelane_b32 v254, s12, 46
	v_writelane_b32 v254, s13, 47
	v_writelane_b32 v254, s14, 48
	v_writelane_b32 v254, s15, 49
	v_writelane_b32 v254, s16, 50
	v_writelane_b32 v254, s17, 51
	v_writelane_b32 v254, s18, 52
	v_writelane_b32 v254, s19, 53
	v_writelane_b32 v254, s20, 54
	v_writelane_b32 v254, s21, 55
	v_writelane_b32 v254, s22, 56
	v_writelane_b32 v254, s23, 57
	s_and_b64 s[10:11], s[0:1], s[6:7]
	s_andn2_b64 vcc, exec, s[10:11]
	s_cbranch_vccnz .LBB0_415
	s_cmpk_gt_i32 s94, 0x57f
	v_readfirstlane_b32 s7, v0
	s_cbranch_scc1 .LBB0_259
	v_lshrrev_b32_e32 v1, 5, v0
	v_lshrrev_b32_e32 v3, 1, v0
	v_and_b32_e32 v1, 4, v1
	v_bfe_u32 v2, v0, 2, 2
	v_and_b32_e32 v3, 24, v3
	v_or3_b32 v1, v1, v2, v3
	v_lshlrev_b32_e32 v2, 4, v0
	v_or_b32_e32 v10, 0x2000, v2
	v_lshrrev_b32_e32 v3, 7, v10
	s_movk_i32 s3, 0x60
	s_add_u32 s0, s26, 0x9800000
	v_and_or_b32 v4, v3, s3, v1
	v_bfe_u32 v13, v0, 2, 4
	s_movk_i32 s3, 0x70
	s_addc_u32 s1, s27, 0
	v_and_or_b32 v3, v3, s3, v13
	s_ashr_i32 s3, s94, 31
	s_lshr_b32 s4, s3, 29
	s_add_i32 s4, s94, s4
	s_lshr_b32 s14, s7, 6
	s_ashr_i32 s5, s4, 3
	s_and_b32 s4, s4, -8
	s_lshr_b32 s16, s7, 8
	s_lshl_b32 s2, s14, 10
	s_sub_i32 s6, s94, s4
	s_cmp_lt_i32 s6, 0
	s_movk_i32 s4, 0xb1
	s_cselect_b32 s8, s4, 0xb0
	s_mul_i32 s6, s6, s8
	s_add_i32 s6, s6, s5
	s_mul_hi_i32 s5, s6, 0x2e8ba2e9
	s_lshr_b32 s8, s5, 31
	s_ashr_i32 s5, s5, 5
	s_add_i32 s5, s5, s8
	s_lshl_b32 s8, s5, 3
	s_mulk_i32 s5, 0xb0
	s_sub_i32 s5, s6, s5
	s_sext_i32_i16 s6, s5
	s_bfe_u32 s6, s6, 0x3001c
	s_add_i32 s9, s5, s6
	s_sext_i32_i16 s6, s9
	s_and_b32 s9, s9, 0xfff8
	s_sub_i32 s5, s5, s9
	s_sext_i32_i16 s5, s5
	v_and_b32_e32 v5, 32, v0
	s_lshr_b32 s6, s6, 3
	s_add_i32 s8, s8, s5
	v_bitop3_b32 v11, v2, v5, 48 bitop3:0x6c
	v_and_b32_e32 v12, 64, v0
	s_ashr_i32 s9, s8, 31
	s_bfe_i64 s[18:19], s[6:7], 0x100000
	v_or_b32_e32 v2, v11, v12
	s_lshl_b64 s[12:13], s[8:9], 19
	s_lshl_b64 s[18:19], s[18:19], 19
	v_lshl_or_b32 v132, v3, 11, v2
	v_lshrrev_b32_e32 v3, 3, v0
	s_add_u32 s42, s0, s18
	v_and_or_b32 v1, v3, 32, v1
	s_addc_u32 s43, s1, s19
	s_add_i32 s5, s2, 0
	v_lshl_or_b32 v134, v1, 11, v2
	s_add_i32 m0, s5, 0x10000
	v_lshl_or_b32 v130, v4, 11, v2
	global_load_lds_dwordx4 v134, s[42:43]
	s_add_i32 m0, s5, 0x12000
	s_add_u32 s18, s42, 0x40000
	global_load_lds_dwordx4 v130, s[42:43]
	s_addc_u32 s19, s43, 0
	s_add_i32 m0, s5, 0x14000
	v_and_or_b32 v1, v3, 48, v13
	global_load_lds_dwordx4 v134, s[18:19]
	s_add_i32 m0, s5, 0x16000
	v_lshl_or_b32 v136, v1, 11, v2
	global_load_lds_dwordx4 v130, s[18:19]
	v_readlane_b32 s18, v254, 22
	v_readlane_b32 s19, v254, 23
	s_add_u32 s40, s18, s12
	s_addc_u32 s41, s19, s13
	s_add_i32 s28, s5, 0x2000
	s_mov_b32 m0, s5
	s_add_u32 s12, s40, 0x40000
	global_load_lds_dwordx4 v136, s[40:41]
	s_mov_b32 m0, s28
	s_addc_u32 s13, s41, 0
	s_add_i32 s29, s5, 0x4000
	global_load_lds_dwordx4 v132, s[40:41]
	s_mov_b32 m0, s29
	s_add_i32 s30, s5, 0x6000
	global_load_lds_dwordx4 v136, s[12:13]
	s_mov_b32 m0, s30
	v_mov_b32_e32 v135, 0
	global_load_lds_dwordx4 v132, s[12:13]
	v_mov_b32_e32 v131, v135
	v_mov_b32_e32 v137, v135
	v_mov_b32_e32 v133, v135
	s_cmp_eq_u32 s16, 1
	s_mov_b32 s31, 0
	v_lshl_add_u64 v[8:9], s[42:43], 0, v[134:135]
	v_lshl_add_u64 v[6:7], s[42:43], 0, v[130:131]
	v_lshl_add_u64 v[2:3], s[40:41], 0, v[136:137]
	s_cselect_b64 s[12:13], -1, 0
	s_cmp_lg_u32 s16, 1
	v_lshl_add_u64 v[4:5], s[40:41], 0, v[132:133]
	s_cbranch_scc1 .LBB0_246
	s_barrier

; __device__ __forceinline__ float frcp(float x) { return __builtin_amdgcn_rcpf(x); }
; __device__ __forceinline__ float row_rstd_q(const float* ssq, int row, int fq) {
;     const f32x4 a = ((const f32x4*)(ssq + (size_t)row * 16))[fq];
;     float s = (a[0] + a[1]) + (a[2] + a[3]);
;     s += __shfl_xor(s, 16); s += __shfl_xor(s, 32);
;     return 1.0f / sqrtf(s * (1.0f / 1024.0f) + 1e-6f);
;     __device__ __forceinline__ void operator()(const f32x4 (&acc)[2][2][4][2], const Unit& u, int wr, int wc, int fr, int fq) const {
;         const int row0 = u.pm * 256 + wr * 64 + fr, col0 = u.pn * 128 + wc * 32 + 8 * fq;
; #pragma unroll
;         for (int ai = 0; ai < 2; ++ai)
; #pragma unroll
;             for (int m = 0; m < 4; ++m) {
;                 const int row = row0 + ai * 128 + m * 16; const float rs = row_rstd_q(ssq, row, fq);
;                 float h[8];
; #pragma unroll
;                 for (int n = 0; n < 2; ++n) {
;                     const f32x4 a = acc[ai][0][m][n] * rs, b = acc[ai][1][m][n] * rs;
; #pragma unroll
;                     for (int j = 0; j < 4; ++j) h[4 * n + j] = a[j] * frcp(1.0f + __expf(-a[j])) * b[j];
.LBB0_255:
	s_cmp_eq_u32 s100, s8
	s_cbranch_scc1 .Lmy_p1_fast
	s_mov_b32 s100, s8
	v_lshl_add_u32 v152, s8, 8, v1
	v_ashrrev_i32_e32 v153, 31, v152
	v_lshlrev_b64 v[148:149], 6, v[152:153]
	v_lshl_add_u64 v[148:149], v[138:139], 0, v[148:149]
	global_load_dwordx4 v[162:165], v[148:149], off
	global_load_dwordx4 v[194:197], v[148:149], off offset:1024
	global_load_dwordx4 v[198:201], v[148:149], off offset:2048
	global_load_dwordx4 v[202:205], v[148:149], off offset:3072
	s_mov_b64 s[98:99], 0x2000
	v_lshl_add_u64 v[222:223], v[148:149], 0, s[98:99]
	global_load_dwordx4 v[206:209], v[222:223], off
	global_load_dwordx4 v[210:213], v[222:223], off offset:1024
	global_load_dwordx4 v[214:217], v[222:223], off offset:2048
	global_load_dwordx4 v[218:221], v[222:223], off offset:3072
	v_and_b32_e32 v153, 64, v159
	v_xor_b32_e32 v151, 16, v159
	v_add_u32_e32 v169, 64, v153
	v_cmp_lt_i32_e32 vcc, v151, v169
	v_xor_b32_e32 v168, 32, v159
	v_mov_b64_e32 v[148:149], s[26:27]
	v_cndmask_b32_e32 v151, v159, v151, vcc
	v_lshlrev_b32_e32 v153, 2, v151
	v_cmp_lt_i32_e32 vcc, v168, v169
	v_lshl_or_b32 v150, s9, 7, v155
	v_ashrrev_i32_e32 v151, 31, v150
	v_lshlrev_b64 v[150:151], 1, v[150:151]
	s_waitcnt vmcnt(0)
	v_mov_b32_e32 v166, v163
	v_mov_b32_e32 v167, v164
	v_mov_b32_e32 v163, v165
	v_pk_add_f32 v[162:163], v[166:167], v[162:163]
	v_or_b32_e32 v166, 16, v152
	v_add_f32_e32 v163, v162, v163
	ds_bpermute_b32 v164, v153, v163
	v_cndmask_b32_e32 v162, v159, v168, vcc
	v_lshlrev_b32_e32 v162, 2, v162
	s_waitcnt lgkmcnt(0)
	v_add_f32_e32 v163, v163, v164
	ds_bpermute_b32 v167, v162, v163
	v_mad_i64_i32 v[164:165], s[8:9], v152, s48, v[148:149]
	v_lshl_add_u64 v[164:165], v[164:165], 0, v[150:151]
	s_waitcnt lgkmcnt(0)
	v_add_f32_e32 v163, v163, v167
	v_fmamk_f32 v163, v163, 0x3a800000, v160
	v_mul_f32_e32 v167, 0x4f800000, v163
	v_cmp_gt_f32_e32 vcc, s47, v163
	s_nop 1
	v_cndmask_b32_e32 v163, v163, v167, vcc
	v_sqrt_f32_e32 v170, v163
	v_ashrrev_i32_e32 v167, 31, v166
	v_lshlrev_b64 v[168:169], 6, v[166:167]
	v_lshl_add_u64 v[168:169], v[138:139], 0, v[168:169]
	v_add_u32_e32 v167, -1, v170
	v_add_u32_e32 v171, 1, v170
	v_fma_f32 v172, -v167, v170, v163
	v_fma_f32 v173, -v171, v170, v163
	v_cmp_ge_f32_e64 s[8:9], 0, v172
	s_nop 1
	v_cndmask_b32_e64 v167, v170, v167, s[8:9]
	v_cmp_lt_f32_e64 s[8:9], 0, v173
	s_nop 1
	v_cndmask_b32_e64 v167, v167, v171, s[8:9]
	v_mul_f32_e32 v170, 0x37800000, v167
	v_cndmask_b32_e32 v167, v167, v170, vcc
	v_cmp_class_f32_e32 vcc, v163, v161
	s_nop 1
	v_cndmask_b32_e32 v163, v167, v163, vcc
	v_div_scale_f32 v167, s[8:9], v163, v163, 1.0
	v_rcp_f32_e32 v170, v167
	v_div_scale_f32 v171, vcc, 1.0, v163, 1.0
	v_fma_f32 v172, -v167, v170, 1.0
	v_fmac_f32_e32 v170, v172, v170
	v_mul_f32_e32 v172, v171, v170
	v_fma_f32 v173, -v167, v172, v171
	v_fmac_f32_e32 v172, v173, v170
	v_fma_f32 v167, -v167, v172, v171
	v_div_fmas_f32 v167, v167, v170, v172
	v_div_fixup_f32 v170, v167, v163, 1.0
	v_mov_b32_e32 v232, v170
	v_pk_mul_f32 v[126:127], v[126:127], v[170:171] op_sel_hi:[1,0]
	v_pk_mul_f32 v[128:129], v[128:129], v[170:171] op_sel_hi:[1,0]
	v_pk_mul_f32 v[122:123], v[122:123], v[170:171] op_sel_hi:[1,0]
	v_pk_mul_f32 v[124:125], v[124:125], v[170:171] op_sel_hi:[1,0]
	v_pk_mul_f32 v[118:119], v[118:119], v[170:171] op_sel_hi:[1,0]
	v_pk_mul_f32 v[120:121], v[120:121], v[170:171] op_sel_hi:[1,0]
	v_pk_mul_f32 v[114:115], v[114:115], v[170:171] op_sel_hi:[1,0]
	v_pk_mul_f32 v[116:117], v[116:117], v[170:171] op_sel_hi:[1,0]
	v_mul_f32_e32 v163, 0xbfb8aa3b, v126
	v_mul_f32_e32 v167, 0xbfb8aa3b, v127
	v_mul_f32_e32 v170, 0xbfb8aa3b, v128
	v_mul_f32_e32 v171, 0xbfb8aa3b, v129
	v_mul_f32_e32 v172, 0xbfb8aa3b, v122
	v_mul_f32_e32 v173, 0xbfb8aa3b, v123
	v_mul_f32_e32 v174, 0xbfb8aa3b, v124
	v_mul_f32_e32 v175, 0xbfb8aa3b, v125
	v_exp_f32_e32 v163, v163
	v_exp_f32_e32 v167, v167
	v_exp_f32_e32 v170, v170
	v_exp_f32_e32 v171, v171
	v_exp_f32_e32 v172, v172
	v_exp_f32_e32 v173, v173
	v_exp_f32_e32 v174, v174
	v_exp_f32_e32 v175, v175
	v_add_f32_e32 v163, 1.0, v163
	v_add_f32_e32 v167, 1.0, v167
	v_add_f32_e32 v176, 1.0, v170
	v_add_f32_e32 v177, 1.0, v171
	v_add_f32_e32 v178, 1.0, v172
	v_add_f32_e32 v179, 1.0, v173
	v_add_f32_e32 v180, 1.0, v174
	v_add_f32_e32 v181, 1.0, v175
	v_rcp_f32_e32 v170, v163
	v_rcp_f32_e32 v171, v167
	v_rcp_f32_e32 v172, v176
	v_rcp_f32_e32 v173, v177
	v_rcp_f32_e32 v174, v178
	v_rcp_f32_e32 v175, v179
	v_rcp_f32_e32 v176, v180
	v_rcp_f32_e32 v177, v181
	v_pk_mul_f32 v[126:127], v[126:127], v[170:171]
	v_pk_mul_f32 v[128:129], v[128:129], v[172:173]
	v_pk_mul_f32 v[122:123], v[122:123], v[174:175]
	v_pk_mul_f32 v[124:125], v[124:125], v[176:177]
	v_pk_mul_f32 v[118:119], v[118:119], v[126:127]
	v_pk_mul_f32 v[120:121], v[120:121], v[128:129]
	v_pk_mul_f32 v[122:123], v[114:115], v[122:123]
	v_pk_mul_f32 v[124:125], v[116:117], v[124:125]
	v_cvt_pk_bf16_f32 v114, v118, v119
	v_cvt_pk_bf16_f32 v115, v120, v121
	v_cvt_pk_bf16_f32 v116, v122, v123
	v_cvt_pk_bf16_f32 v117, v124, v125
	global_store_dwordx4 v[164:165], v[114:117], off
	s_nop 1
	v_mov_b32_e32 v114, v194
	v_mov_b32_e32 v115, v195
	v_mov_b32_e32 v116, v196
	v_mov_b32_e32 v117, v197
	v_mov_b32_e32 v118, v115
	v_mov_b32_e32 v119, v116
	v_mov_b32_e32 v115, v117
	v_pk_add_f32 v[114:115], v[118:119], v[114:115]
	v_mad_i64_i32 v[116:117], s[8:9], v166, s48, v[148:149]
	v_add_f32_e32 v114, v114, v115
	ds_bpermute_b32 v115, v153, v114
	v_lshl_add_u64 v[116:117], v[116:117], 0, v[150:151]
	s_waitcnt lgkmcnt(0)
	v_add_f32_e32 v115, v114, v115
	ds_bpermute_b32 v118, v162, v115
	v_or_b32_e32 v114, 32, v152
	s_waitcnt lgkmcnt(0)
; __device__ __forceinline__ unsigned pk2(float lo, float hi) { const f32x2 v = {lo, hi}; const bf16x2_t b = __builtin_convertvector(v, bf16x2_t); return __builtin_bit_cast(unsigned, b); }
; __device__ __forceinline__ float frcp(float x) { return __builtin_amdgcn_rcpf(x); }
; __device__ __forceinline__ float row_rstd_q(const float* ssq, int row, int fq) {
;     const f32x4 a = ((const f32x4*)(ssq + (size_t)row * 16))[fq];
;     float s = (a[0] + a[1]) + (a[2] + a[3]);
;     s += __shfl_xor(s, 16); s += __shfl_xor(s, 32);
;     return 1.0f / sqrtf(s * (1.0f / 1024.0f) + 1e-6f);
;     __device__ __forceinline__ void operator()(const f32x4 (&acc)[2][2][4][2], const Unit& u, int wr, int wc, int fr, int fq) const {
;         const int row0 = u.pm * 256 + wr * 64 + fr, col0 = u.pn * 128 + wc * 32 + 8 * fq;
; #pragma unroll
;         for (int ai = 0; ai < 2; ++ai)
; #pragma unroll
;             for (int m = 0; m < 4; ++m) {
;                 const int row = row0 + ai * 128 + m * 16; const float rs = row_rstd_q(ssq, row, fq);
;                 float h[8];
; #pragma unroll
;                 for (int n = 0; n < 2; ++n) {
;                     const f32x4 a = acc[ai][0][m][n] * rs, b = acc[ai][1][m][n] * rs;
; #pragma unroll
;                     for (int j = 0; j < 4; ++j) h[4 * n + j] = a[j] * frcp(1.0f + __expf(-a[j])) * b[j];
;                 }
;                 u32x4 w; w.x = pk2(h[0], h[1]); w.y = pk2(h[2], h[3]); w.z = pk2(h[4], h[5]); w.w = pk2(h[6], h[7]);
;                 *(u32x4*)(O + (size_t)row * FF_ + col0) = w;
	v_add_f32_e32 v115, v115, v118
	v_fmamk_f32 v115, v115, 0x3a800000, v160
	v_mul_f32_e32 v118, 0x4f800000, v115
	v_cmp_gt_f32_e32 vcc, s47, v115
	s_nop 1
	v_cndmask_b32_e32 v120, v115, v118, vcc
	v_sqrt_f32_e32 v121, v120
	v_ashrrev_i32_e32 v115, 31, v114
	v_lshlrev_b64 v[118:119], 6, v[114:115]
	v_lshl_add_u64 v[118:119], v[138:139], 0, v[118:119]
	v_add_u32_e32 v115, -1, v121
	v_add_u32_e32 v122, 1, v121
	v_fma_f32 v123, -v115, v121, v120
	v_fma_f32 v124, -v122, v121, v120
	v_cmp_ge_f32_e64 s[8:9], 0, v123
	s_nop 1
	v_cndmask_b32_e64 v115, v121, v115, s[8:9]
	v_cmp_lt_f32_e64 s[8:9], 0, v124
	s_nop 1
	v_cndmask_b32_e64 v115, v115, v122, s[8:9]
	v_mul_f32_e32 v121, 0x37800000, v115
	v_cndmask_b32_e32 v115, v115, v121, vcc
	v_cmp_class_f32_e32 vcc, v120, v161
	s_nop 1
	v_cndmask_b32_e32 v115, v115, v120, vcc
	v_div_scale_f32 v120, s[8:9], v115, v115, 1.0
	v_rcp_f32_e32 v121, v120
	v_div_scale_f32 v122, vcc, 1.0, v115, 1.0
	v_fma_f32 v123, -v120, v121, 1.0
	v_fmac_f32_e32 v121, v123, v121
	v_mul_f32_e32 v123, v122, v121
	v_fma_f32 v124, -v120, v123, v122
	v_fmac_f32_e32 v123, v124, v121
	v_fma_f32 v120, -v120, v123, v122
	v_div_fmas_f32 v120, v120, v121, v123
	v_div_fixup_f32 v120, v120, v115, 1.0
	v_mov_b32_e32 v233, v120
	v_pk_mul_f32 v[110:111], v[110:111], v[120:121] op_sel_hi:[1,0]
	v_pk_mul_f32 v[112:113], v[112:113], v[120:121] op_sel_hi:[1,0]
	v_pk_mul_f32 v[106:107], v[106:107], v[120:121] op_sel_hi:[1,0]
	v_pk_mul_f32 v[108:109], v[108:109], v[120:121] op_sel_hi:[1,0]
	v_pk_mul_f32 v[102:103], v[102:103], v[120:121] op_sel_hi:[1,0]
	v_pk_mul_f32 v[104:105], v[104:105], v[120:121] op_sel_hi:[1,0]
	v_pk_mul_f32 v[98:99], v[98:99], v[120:121] op_sel_hi:[1,0]
	v_pk_mul_f32 v[100:101], v[100:101], v[120:121] op_sel_hi:[1,0]
	v_mul_f32_e32 v115, 0xbfb8aa3b, v110
	v_mul_f32_e32 v120, 0xbfb8aa3b, v111
	v_mul_f32_e32 v121, 0xbfb8aa3b, v112
	v_mul_f32_e32 v122, 0xbfb8aa3b, v113
	v_mul_f32_e32 v123, 0xbfb8aa3b, v106
	v_mul_f32_e32 v124, 0xbfb8aa3b, v107
	v_mul_f32_e32 v125, 0xbfb8aa3b, v108
	v_mul_f32_e32 v126, 0xbfb8aa3b, v109
	v_exp_f32_e32 v115, v115
	v_exp_f32_e32 v120, v120
	v_exp_f32_e32 v121, v121
	v_exp_f32_e32 v122, v122
	v_exp_f32_e32 v123, v123
	v_exp_f32_e32 v124, v124
	v_exp_f32_e32 v125, v125
	v_exp_f32_e32 v126, v126
	v_add_f32_e32 v115, 1.0, v115
	v_add_f32_e32 v127, 1.0, v120
	v_add_f32_e32 v128, 1.0, v121
	v_add_f32_e32 v129, 1.0, v122
	v_add_f32_e32 v163, 1.0, v123
	v_add_f32_e32 v164, 1.0, v124
	v_add_f32_e32 v165, 1.0, v125
	v_add_f32_e32 v166, 1.0, v126
	v_rcp_f32_e32 v120, v115
	v_rcp_f32_e32 v121, v127
	v_rcp_f32_e32 v122, v128
	v_rcp_f32_e32 v123, v129
	v_rcp_f32_e32 v124, v163
	v_rcp_f32_e32 v125, v164
	v_rcp_f32_e32 v126, v165
	v_rcp_f32_e32 v127, v166
	v_pk_mul_f32 v[110:111], v[110:111], v[120:121]
	v_pk_mul_f32 v[112:113], v[112:113], v[122:123]
	v_pk_mul_f32 v[106:107], v[106:107], v[124:125]
	v_pk_mul_f32 v[108:109], v[108:109], v[126:127]
	v_pk_mul_f32 v[102:103], v[102:103], v[110:111]
	v_pk_mul_f32 v[104:105], v[104:105], v[112:113]
	v_pk_mul_f32 v[106:107], v[98:99], v[106:107]
	v_pk_mul_f32 v[108:109], v[100:101], v[108:109]
	v_cvt_pk_bf16_f32 v98, v102, v103
	v_cvt_pk_bf16_f32 v99, v104, v105
	v_cvt_pk_bf16_f32 v100, v106, v107
	v_cvt_pk_bf16_f32 v101, v108, v109
	global_store_dwordx4 v[116:117], v[98:101], off
	s_nop 1
	v_mov_b32_e32 v98, v198
	v_mov_b32_e32 v99, v199
	v_mov_b32_e32 v100, v200
	v_mov_b32_e32 v101, v201
	v_mov_b32_e32 v102, v99
	v_mov_b32_e32 v103, v100
	v_mov_b32_e32 v99, v101
	v_pk_add_f32 v[98:99], v[102:103], v[98:99]
	v_mad_i64_i32 v[100:101], s[8:9], v114, s48, v[148:149]
	v_add_f32_e32 v98, v98, v99
	ds_bpermute_b32 v99, v153, v98
	v_lshl_add_u64 v[100:101], v[100:101], 0, v[150:151]
	s_waitcnt lgkmcnt(0)
	v_add_f32_e32 v99, v98, v99
	ds_bpermute_b32 v102, v162, v99
	v_or_b32_e32 v98, 48, v152
	s_waitcnt lgkmcnt(0)
	v_add_f32_e32 v99, v99, v102
	v_fmamk_f32 v99, v99, 0x3a800000, v160
	v_mul_f32_e32 v102, 0x4f800000, v99
	v_cmp_gt_f32_e32 vcc, s47, v99
	s_nop 1
	v_cndmask_b32_e32 v104, v99, v102, vcc
	v_sqrt_f32_e32 v105, v104
	v_ashrrev_i32_e32 v99, 31, v98
	v_lshlrev_b64 v[102:103], 6, v[98:99]
	v_lshl_add_u64 v[102:103], v[138:139], 0, v[102:103]
	v_add_u32_e32 v99, -1, v105
	v_add_u32_e32 v106, 1, v105
	v_fma_f32 v107, -v99, v105, v104
	v_fma_f32 v108, -v106, v105, v104
	v_cmp_ge_f32_e64 s[8:9], 0, v107
	s_nop 1
	v_cndmask_b32_e64 v99, v105, v99, s[8:9]
	v_cmp_lt_f32_e64 s[8:9], 0, v108
	s_nop 1
	v_cndmask_b32_e64 v99, v99, v106, s[8:9]
	v_mul_f32_e32 v105, 0x37800000, v99
	v_cndmask_b32_e32 v99, v99, v105, vcc
	v_cmp_class_f32_e32 vcc, v104, v161
	s_nop 1
	v_cndmask_b32_e32 v99, v99, v104, vcc
	v_div_scale_f32 v104, s[8:9], v99, v99, 1.0
	v_rcp_f32_e32 v105, v104
	v_div_scale_f32 v106, vcc, 1.0, v99, 1.0
	v_fma_f32 v107, -v104, v105, 1.0
	v_fmac_f32_e32 v105, v107, v105
	v_mul_f32_e32 v107, v106, v105
	v_fma_f32 v108, -v104, v107, v106
	v_fmac_f32_e32 v107, v108, v105
	v_fma_f32 v104, -v104, v107, v106
	v_div_fmas_f32 v104, v104, v105, v107
	v_div_fixup_f32 v104, v104, v99, 1.0
	v_mov_b32_e32 v234, v104
	v_pk_mul_f32 v[94:95], v[94:95], v[104:105] op_sel_hi:[1,0]
	v_pk_mul_f32 v[96:97], v[96:97], v[104:105] op_sel_hi:[1,0]
	v_pk_mul_f32 v[90:91], v[90:91], v[104:105] op_sel_hi:[1,0]
	v_pk_mul_f32 v[92:93], v[92:93], v[104:105] op_sel_hi:[1,0]
	v_pk_mul_f32 v[86:87], v[86:87], v[104:105] op_sel_hi:[1,0]
	v_pk_mul_f32 v[88:89], v[88:89], v[104:105] op_sel_hi:[1,0]
	v_pk_mul_f32 v[82:83], v[82:83], v[104:105] op_sel_hi:[1,0]
	v_pk_mul_f32 v[84:85], v[84:85], v[104:105] op_sel_hi:[1,0]
	v_mul_f32_e32 v99, 0xbfb8aa3b, v94
	v_mul_f32_e32 v104, 0xbfb8aa3b, v95
; __device__ __forceinline__ unsigned pk2(float lo, float hi) { const f32x2 v = {lo, hi}; const bf16x2_t b = __builtin_convertvector(v, bf16x2_t); return __builtin_bit_cast(unsigned, b); }
; __device__ __forceinline__ float frcp(float x) { return __builtin_amdgcn_rcpf(x); }
; __device__ __forceinline__ float row_rstd_q(const float* ssq, int row, int fq) {
;     const f32x4 a = ((const f32x4*)(ssq + (size_t)row * 16))[fq];
;     float s = (a[0] + a[1]) + (a[2] + a[3]);
;     s += __shfl_xor(s, 16); s += __shfl_xor(s, 32);
;     return 1.0f / sqrtf(s * (1.0f / 1024.0f) + 1e-6f);
;     __device__ __forceinline__ void operator()(const f32x4 (&acc)[2][2][4][2], const Unit& u, int wr, int wc, int fr, int fq) const {
;         const int row0 = u.pm * 256 + wr * 64 + fr, col0 = u.pn * 128 + wc * 32 + 8 * fq;
; #pragma unroll
;         for (int ai = 0; ai < 2; ++ai)
; #pragma unroll
;             for (int m = 0; m < 4; ++m) {
;                 const int row = row0 + ai * 128 + m * 16; const float rs = row_rstd_q(ssq, row, fq);
;                 float h[8];
; #pragma unroll
;                 for (int n = 0; n < 2; ++n) {
;                     const f32x4 a = acc[ai][0][m][n] * rs, b = acc[ai][1][m][n] * rs;
; #pragma unroll
;                     for (int j = 0; j < 4; ++j) h[4 * n + j] = a[j] * frcp(1.0f + __expf(-a[j])) * b[j];
;                 }
;                 u32x4 w; w.x = pk2(h[0], h[1]); w.y = pk2(h[2], h[3]); w.z = pk2(h[4], h[5]); w.w = pk2(h[6], h[7]);
;                 *(u32x4*)(O + (size_t)row * FF_ + col0) = w;
	v_mul_f32_e32 v105, 0xbfb8aa3b, v96
	v_mul_f32_e32 v106, 0xbfb8aa3b, v97
	v_mul_f32_e32 v107, 0xbfb8aa3b, v90
	v_mul_f32_e32 v108, 0xbfb8aa3b, v91
	v_mul_f32_e32 v109, 0xbfb8aa3b, v92
	v_mul_f32_e32 v110, 0xbfb8aa3b, v93
	v_exp_f32_e32 v99, v99
	v_exp_f32_e32 v104, v104
	v_exp_f32_e32 v105, v105
	v_exp_f32_e32 v106, v106
	v_exp_f32_e32 v107, v107
	v_exp_f32_e32 v108, v108
	v_exp_f32_e32 v109, v109
	v_exp_f32_e32 v110, v110
	v_add_f32_e32 v99, 1.0, v99
	v_add_f32_e32 v111, 1.0, v104
	v_add_f32_e32 v112, 1.0, v105
	v_add_f32_e32 v113, 1.0, v106
	v_add_f32_e32 v114, 1.0, v107
	v_add_f32_e32 v115, 1.0, v108
	v_add_f32_e32 v116, 1.0, v109
	v_add_f32_e32 v117, 1.0, v110
	v_rcp_f32_e32 v104, v99
	v_rcp_f32_e32 v105, v111
	v_rcp_f32_e32 v106, v112
	v_rcp_f32_e32 v107, v113
	v_rcp_f32_e32 v108, v114
	v_rcp_f32_e32 v109, v115
	v_rcp_f32_e32 v110, v116
	v_rcp_f32_e32 v111, v117
	v_pk_mul_f32 v[94:95], v[94:95], v[104:105]
	v_pk_mul_f32 v[96:97], v[96:97], v[106:107]
	v_pk_mul_f32 v[90:91], v[90:91], v[108:109]
	v_pk_mul_f32 v[92:93], v[92:93], v[110:111]
	v_pk_mul_f32 v[86:87], v[86:87], v[94:95]
	v_pk_mul_f32 v[88:89], v[88:89], v[96:97]
	v_pk_mul_f32 v[90:91], v[82:83], v[90:91]
	v_pk_mul_f32 v[92:93], v[84:85], v[92:93]
	v_cvt_pk_bf16_f32 v82, v86, v87
	v_cvt_pk_bf16_f32 v83, v88, v89
	v_cvt_pk_bf16_f32 v84, v90, v91
	v_cvt_pk_bf16_f32 v85, v92, v93
	global_store_dwordx4 v[100:101], v[82:85], off
	s_nop 1
	v_mov_b32_e32 v82, v202
	v_mov_b32_e32 v83, v203
	v_mov_b32_e32 v84, v204
	v_mov_b32_e32 v85, v205
	v_mov_b32_e32 v86, v83
	v_mov_b32_e32 v87, v84
	v_mov_b32_e32 v83, v85
	v_pk_add_f32 v[82:83], v[86:87], v[82:83]
	v_mad_i64_i32 v[84:85], s[8:9], v98, s48, v[148:149]
	v_add_f32_e32 v82, v82, v83
	ds_bpermute_b32 v83, v153, v82
	v_lshl_add_u64 v[84:85], v[84:85], 0, v[150:151]
	s_waitcnt lgkmcnt(0)
	v_add_f32_e32 v83, v82, v83
	ds_bpermute_b32 v86, v162, v83
	v_add_u32_e32 v82, 0x80, v152
	s_waitcnt lgkmcnt(0)
	v_add_f32_e32 v83, v83, v86
	v_fmamk_f32 v83, v83, 0x3a800000, v160
	v_mul_f32_e32 v86, 0x4f800000, v83
	v_cmp_gt_f32_e32 vcc, s47, v83
	s_nop 1
	v_cndmask_b32_e32 v88, v83, v86, vcc
	v_sqrt_f32_e32 v89, v88
	v_ashrrev_i32_e32 v83, 31, v82
	v_lshlrev_b64 v[86:87], 6, v[82:83]
	v_lshl_add_u64 v[86:87], v[138:139], 0, v[86:87]
	v_add_u32_e32 v83, -1, v89
	v_add_u32_e32 v90, 1, v89
	v_fma_f32 v91, -v83, v89, v88
	v_fma_f32 v92, -v90, v89, v88
	v_cmp_ge_f32_e64 s[8:9], 0, v91
	s_nop 1
	v_cndmask_b32_e64 v83, v89, v83, s[8:9]
	v_cmp_lt_f32_e64 s[8:9], 0, v92
	s_nop 1
	v_cndmask_b32_e64 v83, v83, v90, s[8:9]
	v_mul_f32_e32 v89, 0x37800000, v83
	v_cndmask_b32_e32 v83, v83, v89, vcc
	v_cmp_class_f32_e32 vcc, v88, v161
	s_nop 1
	v_cndmask_b32_e32 v83, v83, v88, vcc
	v_div_scale_f32 v88, s[8:9], v83, v83, 1.0
	v_rcp_f32_e32 v89, v88
	v_div_scale_f32 v90, vcc, 1.0, v83, 1.0
	v_fma_f32 v91, -v88, v89, 1.0
	v_fmac_f32_e32 v89, v91, v89
	v_mul_f32_e32 v91, v90, v89
	v_fma_f32 v92, -v88, v91, v90
	v_fmac_f32_e32 v91, v92, v89
	v_fma_f32 v88, -v88, v91, v90
	v_div_fmas_f32 v88, v88, v89, v91
	v_div_fixup_f32 v88, v88, v83, 1.0
	v_mov_b32_e32 v235, v88
	v_pk_mul_f32 v[78:79], v[78:79], v[88:89] op_sel_hi:[1,0]
	v_pk_mul_f32 v[80:81], v[80:81], v[88:89] op_sel_hi:[1,0]
	v_pk_mul_f32 v[74:75], v[74:75], v[88:89] op_sel_hi:[1,0]
	v_pk_mul_f32 v[76:77], v[76:77], v[88:89] op_sel_hi:[1,0]
	v_pk_mul_f32 v[70:71], v[70:71], v[88:89] op_sel_hi:[1,0]
	v_pk_mul_f32 v[72:73], v[72:73], v[88:89] op_sel_hi:[1,0]
	v_pk_mul_f32 v[66:67], v[66:67], v[88:89] op_sel_hi:[1,0]
	v_pk_mul_f32 v[68:69], v[68:69], v[88:89] op_sel_hi:[1,0]
	v_mul_f32_e32 v83, 0xbfb8aa3b, v78
	v_mul_f32_e32 v88, 0xbfb8aa3b, v79
	v_mul_f32_e32 v89, 0xbfb8aa3b, v80
	v_mul_f32_e32 v90, 0xbfb8aa3b, v81
	v_mul_f32_e32 v91, 0xbfb8aa3b, v74
	v_mul_f32_e32 v92, 0xbfb8aa3b, v75
	v_mul_f32_e32 v93, 0xbfb8aa3b, v76
	v_mul_f32_e32 v94, 0xbfb8aa3b, v77
	v_exp_f32_e32 v83, v83
	v_exp_f32_e32 v88, v88
	v_exp_f32_e32 v89, v89
	v_exp_f32_e32 v90, v90
	v_exp_f32_e32 v91, v91
	v_exp_f32_e32 v92, v92
	v_exp_f32_e32 v93, v93
	v_exp_f32_e32 v94, v94
	v_add_f32_e32 v83, 1.0, v83
	v_add_f32_e32 v95, 1.0, v88
	v_add_f32_e32 v96, 1.0, v89
	v_add_f32_e32 v97, 1.0, v90
	v_add_f32_e32 v98, 1.0, v91
	v_add_f32_e32 v99, 1.0, v92
	v_add_f32_e32 v100, 1.0, v93
	v_add_f32_e32 v101, 1.0, v94
	v_rcp_f32_e32 v88, v83
	v_rcp_f32_e32 v89, v95
	v_rcp_f32_e32 v90, v96
	v_rcp_f32_e32 v91, v97
	v_rcp_f32_e32 v92, v98
	v_rcp_f32_e32 v93, v99
	v_rcp_f32_e32 v94, v100
	v_rcp_f32_e32 v95, v101
	v_pk_mul_f32 v[78:79], v[78:79], v[88:89]
	v_pk_mul_f32 v[80:81], v[80:81], v[90:91]
	v_pk_mul_f32 v[74:75], v[74:75], v[92:93]
	v_pk_mul_f32 v[76:77], v[76:77], v[94:95]
	v_pk_mul_f32 v[70:71], v[70:71], v[78:79]
	v_pk_mul_f32 v[72:73], v[72:73], v[80:81]
	v_pk_mul_f32 v[74:75], v[66:67], v[74:75]
	v_pk_mul_f32 v[76:77], v[68:69], v[76:77]
	v_cvt_pk_bf16_f32 v66, v70, v71
	v_cvt_pk_bf16_f32 v67, v72, v73
	v_cvt_pk_bf16_f32 v68, v74, v75
	v_cvt_pk_bf16_f32 v69, v76, v77
	global_store_dwordx4 v[84:85], v[66:69], off
	s_nop 1
	v_mov_b32_e32 v66, v206
	v_mov_b32_e32 v67, v207
	v_mov_b32_e32 v68, v208
	v_mov_b32_e32 v69, v209
	v_mov_b32_e32 v70, v67
	v_mov_b32_e32 v71, v68
	v_mov_b32_e32 v67, v69
	v_pk_add_f32 v[66:67], v[70:71], v[66:67]
	v_mad_i64_i32 v[68:69], s[8:9], v82, s48, v[148:149]
	v_add_f32_e32 v66, v66, v67
	ds_bpermute_b32 v67, v153, v66
	v_lshl_add_u64 v[68:69], v[68:69], 0, v[150:151]
	s_waitcnt lgkmcnt(0)
	v_add_f32_e32 v67, v66, v67
	ds_bpermute_b32 v70, v162, v67
	v_add_u32_e32 v66, 0x90, v152
	s_waitcnt lgkmcnt(0)
; __device__ __forceinline__ unsigned pk2(float lo, float hi) { const f32x2 v = {lo, hi}; const bf16x2_t b = __builtin_convertvector(v, bf16x2_t); return __builtin_bit_cast(unsigned, b); }
; __device__ __forceinline__ float frcp(float x) { return __builtin_amdgcn_rcpf(x); }
; __device__ __forceinline__ float row_rstd_q(const float* ssq, int row, int fq) {
;     const f32x4 a = ((const f32x4*)(ssq + (size_t)row * 16))[fq];
;     float s = (a[0] + a[1]) + (a[2] + a[3]);
;     s += __shfl_xor(s, 16); s += __shfl_xor(s, 32);
;     return 1.0f / sqrtf(s * (1.0f / 1024.0f) + 1e-6f);
;     __device__ __forceinline__ void operator()(const f32x4 (&acc)[2][2][4][2], const Unit& u, int wr, int wc, int fr, int fq) const {
;         const int row0 = u.pm * 256 + wr * 64 + fr, col0 = u.pn * 128 + wc * 32 + 8 * fq;
; #pragma unroll
;         for (int ai = 0; ai < 2; ++ai)
; #pragma unroll
;             for (int m = 0; m < 4; ++m) {
;                 const int row = row0 + ai * 128 + m * 16; const float rs = row_rstd_q(ssq, row, fq);
;                 float h[8];
; #pragma unroll
;                 for (int n = 0; n < 2; ++n) {
;                     const f32x4 a = acc[ai][0][m][n] * rs, b = acc[ai][1][m][n] * rs;
; #pragma unroll
;                     for (int j = 0; j < 4; ++j) h[4 * n + j] = a[j] * frcp(1.0f + __expf(-a[j])) * b[j];
;                 }
;                 u32x4 w; w.x = pk2(h[0], h[1]); w.y = pk2(h[2], h[3]); w.z = pk2(h[4], h[5]); w.w = pk2(h[6], h[7]);
;                 *(u32x4*)(O + (size_t)row * FF_ + col0) = w;
	v_add_f32_e32 v67, v67, v70
	v_fmamk_f32 v67, v67, 0x3a800000, v160
	v_mul_f32_e32 v70, 0x4f800000, v67
	v_cmp_gt_f32_e32 vcc, s47, v67
	s_nop 1
	v_cndmask_b32_e32 v72, v67, v70, vcc
	v_sqrt_f32_e32 v73, v72
	v_ashrrev_i32_e32 v67, 31, v66
	v_lshlrev_b64 v[70:71], 6, v[66:67]
	v_lshl_add_u64 v[70:71], v[138:139], 0, v[70:71]
	v_add_u32_e32 v67, -1, v73
	v_add_u32_e32 v74, 1, v73
	v_fma_f32 v75, -v67, v73, v72
	v_fma_f32 v76, -v74, v73, v72
	v_cmp_ge_f32_e64 s[8:9], 0, v75
	s_nop 1
	v_cndmask_b32_e64 v67, v73, v67, s[8:9]
	v_cmp_lt_f32_e64 s[8:9], 0, v76
	s_nop 1
	v_cndmask_b32_e64 v67, v67, v74, s[8:9]
	v_mul_f32_e32 v73, 0x37800000, v67
	v_cndmask_b32_e32 v67, v67, v73, vcc
	v_cmp_class_f32_e32 vcc, v72, v161
	s_nop 1
	v_cndmask_b32_e32 v67, v67, v72, vcc
	v_div_scale_f32 v72, s[8:9], v67, v67, 1.0
	v_rcp_f32_e32 v73, v72
	v_div_scale_f32 v74, vcc, 1.0, v67, 1.0
	v_fma_f32 v75, -v72, v73, 1.0
	v_fmac_f32_e32 v73, v75, v73
	v_mul_f32_e32 v75, v74, v73
	v_fma_f32 v76, -v72, v75, v74
	v_fmac_f32_e32 v75, v76, v73
	v_fma_f32 v72, -v72, v75, v74
	v_div_fmas_f32 v72, v72, v73, v75
	v_div_fixup_f32 v72, v72, v67, 1.0
	v_mov_b32_e32 v236, v72
	v_pk_mul_f32 v[62:63], v[62:63], v[72:73] op_sel_hi:[1,0]
	v_pk_mul_f32 v[64:65], v[64:65], v[72:73] op_sel_hi:[1,0]
	v_pk_mul_f32 v[58:59], v[58:59], v[72:73] op_sel_hi:[1,0]
	v_pk_mul_f32 v[60:61], v[60:61], v[72:73] op_sel_hi:[1,0]
	v_pk_mul_f32 v[54:55], v[54:55], v[72:73] op_sel_hi:[1,0]
	v_pk_mul_f32 v[56:57], v[56:57], v[72:73] op_sel_hi:[1,0]
	v_pk_mul_f32 v[50:51], v[50:51], v[72:73] op_sel_hi:[1,0]
	v_pk_mul_f32 v[52:53], v[52:53], v[72:73] op_sel_hi:[1,0]
	v_mul_f32_e32 v67, 0xbfb8aa3b, v62
	v_mul_f32_e32 v72, 0xbfb8aa3b, v63
	v_mul_f32_e32 v73, 0xbfb8aa3b, v64
	v_mul_f32_e32 v74, 0xbfb8aa3b, v65
	v_mul_f32_e32 v75, 0xbfb8aa3b, v58
	v_mul_f32_e32 v76, 0xbfb8aa3b, v59
	v_mul_f32_e32 v77, 0xbfb8aa3b, v60
	v_mul_f32_e32 v78, 0xbfb8aa3b, v61
	v_exp_f32_e32 v67, v67
	v_exp_f32_e32 v72, v72
	v_exp_f32_e32 v73, v73
	v_exp_f32_e32 v74, v74
	v_exp_f32_e32 v75, v75
	v_exp_f32_e32 v76, v76
	v_exp_f32_e32 v77, v77
	v_exp_f32_e32 v78, v78
	v_add_f32_e32 v67, 1.0, v67
	v_add_f32_e32 v79, 1.0, v72
	v_add_f32_e32 v80, 1.0, v73
	v_add_f32_e32 v81, 1.0, v74
	v_add_f32_e32 v82, 1.0, v75
	v_add_f32_e32 v83, 1.0, v76
	v_add_f32_e32 v84, 1.0, v77
	v_add_f32_e32 v85, 1.0, v78
	v_rcp_f32_e32 v72, v67
	v_rcp_f32_e32 v73, v79
	v_rcp_f32_e32 v74, v80
	v_rcp_f32_e32 v75, v81
	v_rcp_f32_e32 v76, v82
	v_rcp_f32_e32 v77, v83
	v_rcp_f32_e32 v78, v84
	v_rcp_f32_e32 v79, v85
	v_pk_mul_f32 v[62:63], v[62:63], v[72:73]
	v_pk_mul_f32 v[64:65], v[64:65], v[74:75]
	v_pk_mul_f32 v[58:59], v[58:59], v[76:77]
	v_pk_mul_f32 v[60:61], v[60:61], v[78:79]
	v_pk_mul_f32 v[54:55], v[54:55], v[62:63]
	v_pk_mul_f32 v[56:57], v[56:57], v[64:65]
	v_pk_mul_f32 v[58:59], v[50:51], v[58:59]
	v_pk_mul_f32 v[60:61], v[52:53], v[60:61]
	v_cvt_pk_bf16_f32 v50, v54, v55
	v_cvt_pk_bf16_f32 v51, v56, v57
	v_cvt_pk_bf16_f32 v52, v58, v59
	v_cvt_pk_bf16_f32 v53, v60, v61
	global_store_dwordx4 v[68:69], v[50:53], off
	s_nop 1
	v_mov_b32_e32 v50, v210
	v_mov_b32_e32 v51, v211
	v_mov_b32_e32 v52, v212
	v_mov_b32_e32 v53, v213
	v_mov_b32_e32 v54, v51
	v_mov_b32_e32 v55, v52
	v_mov_b32_e32 v51, v53
	v_pk_add_f32 v[50:51], v[54:55], v[50:51]
	v_mad_i64_i32 v[52:53], s[8:9], v66, s48, v[148:149]
	v_add_f32_e32 v50, v50, v51
	ds_bpermute_b32 v51, v153, v50
	v_lshl_add_u64 v[52:53], v[52:53], 0, v[150:151]
	s_waitcnt lgkmcnt(0)
	v_add_f32_e32 v51, v50, v51
	ds_bpermute_b32 v54, v162, v51
	v_add_u32_e32 v50, 0xa0, v152
	s_waitcnt lgkmcnt(0)
	v_add_f32_e32 v51, v51, v54
	v_fmamk_f32 v51, v51, 0x3a800000, v160
	v_mul_f32_e32 v54, 0x4f800000, v51
	v_cmp_gt_f32_e32 vcc, s47, v51
	s_nop 1
	v_cndmask_b32_e32 v56, v51, v54, vcc
	v_sqrt_f32_e32 v57, v56
	v_ashrrev_i32_e32 v51, 31, v50
	v_lshlrev_b64 v[54:55], 6, v[50:51]
	v_lshl_add_u64 v[54:55], v[138:139], 0, v[54:55]
	v_add_u32_e32 v51, -1, v57
	v_add_u32_e32 v58, 1, v57
	v_fma_f32 v59, -v51, v57, v56
	v_fma_f32 v60, -v58, v57, v56
	v_cmp_ge_f32_e64 s[8:9], 0, v59
	s_nop 1
	v_cndmask_b32_e64 v51, v57, v51, s[8:9]
	v_cmp_lt_f32_e64 s[8:9], 0, v60
	s_nop 1
	v_cndmask_b32_e64 v51, v51, v58, s[8:9]
	v_mul_f32_e32 v57, 0x37800000, v51
	v_cndmask_b32_e32 v51, v51, v57, vcc
	v_cmp_class_f32_e32 vcc, v56, v161
	s_nop 1
	v_cndmask_b32_e32 v51, v51, v56, vcc
	v_div_scale_f32 v56, s[8:9], v51, v51, 1.0
	v_rcp_f32_e32 v57, v56
	v_div_scale_f32 v58, vcc, 1.0, v51, 1.0
	v_fma_f32 v59, -v56, v57, 1.0
	v_fmac_f32_e32 v57, v59, v57
	v_mul_f32_e32 v59, v58, v57
	v_fma_f32 v60, -v56, v59, v58
	v_fmac_f32_e32 v59, v60, v57
	v_fma_f32 v56, -v56, v59, v58
	v_div_fmas_f32 v56, v56, v57, v59
	v_div_fixup_f32 v56, v56, v51, 1.0
	v_mov_b32_e32 v237, v56
	v_pk_mul_f32 v[46:47], v[46:47], v[56:57] op_sel_hi:[1,0]
	v_pk_mul_f32 v[48:49], v[48:49], v[56:57] op_sel_hi:[1,0]
	v_pk_mul_f32 v[42:43], v[42:43], v[56:57] op_sel_hi:[1,0]
	v_pk_mul_f32 v[44:45], v[44:45], v[56:57] op_sel_hi:[1,0]
	v_pk_mul_f32 v[38:39], v[38:39], v[56:57] op_sel_hi:[1,0]
	v_pk_mul_f32 v[40:41], v[40:41], v[56:57] op_sel_hi:[1,0]
	v_pk_mul_f32 v[34:35], v[34:35], v[56:57] op_sel_hi:[1,0]
	v_pk_mul_f32 v[36:37], v[36:37], v[56:57] op_sel_hi:[1,0]
	v_mul_f32_e32 v51, 0xbfb8aa3b, v46
	v_mul_f32_e32 v56, 0xbfb8aa3b, v47
	v_mul_f32_e32 v57, 0xbfb8aa3b, v48
	v_mul_f32_e32 v58, 0xbfb8aa3b, v49
	v_mul_f32_e32 v59, 0xbfb8aa3b, v42
	v_mul_f32_e32 v60, 0xbfb8aa3b, v43
	v_mul_f32_e32 v61, 0xbfb8aa3b, v44
	v_mul_f32_e32 v62, 0xbfb8aa3b, v45
	v_exp_f32_e32 v51, v51
	v_exp_f32_e32 v56, v56
	v_exp_f32_e32 v57, v57
	v_exp_f32_e32 v58, v58
	v_exp_f32_e32 v59, v59
	v_exp_f32_e32 v60, v60
	v_exp_f32_e32 v61, v61
	v_exp_f32_e32 v62, v62
	v_add_f32_e32 v51, 1.0, v51
	v_add_f32_e32 v63, 1.0, v56
	v_add_f32_e32 v64, 1.0, v57
	v_add_f32_e32 v65, 1.0, v58
	v_add_f32_e32 v66, 1.0, v59
	v_add_f32_e32 v67, 1.0, v60
	v_add_f32_e32 v68, 1.0, v61
	v_add_f32_e32 v69, 1.0, v62
	v_rcp_f32_e32 v56, v51
	v_rcp_f32_e32 v57, v63
	v_rcp_f32_e32 v58, v64
	v_rcp_f32_e32 v59, v65
	v_rcp_f32_e32 v60, v66
	v_rcp_f32_e32 v61, v67
	v_rcp_f32_e32 v62, v68
	v_rcp_f32_e32 v63, v69
	v_pk_mul_f32 v[46:47], v[46:47], v[56:57]
	v_pk_mul_f32 v[48:49], v[48:49], v[58:59]
	v_pk_mul_f32 v[42:43], v[42:43], v[60:61]
	v_pk_mul_f32 v[44:45], v[44:45], v[62:63]
	v_pk_mul_f32 v[38:39], v[38:39], v[46:47]
	v_pk_mul_f32 v[40:41], v[40:41], v[48:49]
	v_pk_mul_f32 v[42:43], v[34:35], v[42:43]
	v_pk_mul_f32 v[44:45], v[36:37], v[44:45]
	v_cvt_pk_bf16_f32 v34, v38, v39
	v_cvt_pk_bf16_f32 v35, v40, v41
	v_cvt_pk_bf16_f32 v36, v42, v43
	v_cvt_pk_bf16_f32 v37, v44, v45
	global_store_dwordx4 v[52:53], v[34:37], off
	s_nop 1
	v_mov_b32_e32 v34, v214
	v_mov_b32_e32 v35, v215
	v_mov_b32_e32 v36, v216
	v_mov_b32_e32 v37, v217
	v_mov_b32_e32 v38, v35
	v_mov_b32_e32 v39, v36
	v_mov_b32_e32 v35, v37
	v_pk_add_f32 v[34:35], v[38:39], v[34:35]
	v_mad_i64_i32 v[36:37], s[8:9], v50, s48, v[148:149]
	v_add_f32_e32 v34, v34, v35
	ds_bpermute_b32 v35, v153, v34
	v_lshl_add_u64 v[36:37], v[36:37], 0, v[150:151]
	s_waitcnt lgkmcnt(0)
; __device__ __forceinline__ unsigned pk2(float lo, float hi) { const f32x2 v = {lo, hi}; const bf16x2_t b = __builtin_convertvector(v, bf16x2_t); return __builtin_bit_cast(unsigned, b); }
; __device__ __forceinline__ float frcp(float x) { return __builtin_amdgcn_rcpf(x); }
; __device__ __forceinline__ float row_rstd_q(const float* ssq, int row, int fq) {
;     const f32x4 a = ((const f32x4*)(ssq + (size_t)row * 16))[fq];
;     float s = (a[0] + a[1]) + (a[2] + a[3]);
;     s += __shfl_xor(s, 16); s += __shfl_xor(s, 32);
;     return 1.0f / sqrtf(s * (1.0f / 1024.0f) + 1e-6f);
;     __device__ __forceinline__ void operator()(const f32x4 (&acc)[2][2][4][2], const Unit& u, int wr, int wc, int fr, int fq) const {
;         const int row0 = u.pm * 256 + wr * 64 + fr, col0 = u.pn * 128 + wc * 32 + 8 * fq;
; #pragma unroll
;         for (int ai = 0; ai < 2; ++ai)
; #pragma unroll
;             for (int m = 0; m < 4; ++m) {
;                 const int row = row0 + ai * 128 + m * 16; const float rs = row_rstd_q(ssq, row, fq);
;                 float h[8];
; #pragma unroll
;                 for (int n = 0; n < 2; ++n) {
;                     const f32x4 a = acc[ai][0][m][n] * rs, b = acc[ai][1][m][n] * rs;
; #pragma unroll
;                     for (int j = 0; j < 4; ++j) h[4 * n + j] = a[j] * frcp(1.0f + __expf(-a[j])) * b[j];
;                 }
;                 u32x4 w; w.x = pk2(h[0], h[1]); w.y = pk2(h[2], h[3]); w.z = pk2(h[4], h[5]); w.w = pk2(h[6], h[7]);
;                 *(u32x4*)(O + (size_t)row * FF_ + col0) = w;
	v_add_f32_e32 v35, v34, v35
	ds_bpermute_b32 v38, v162, v35
	v_add_u32_e32 v34, 0xb0, v152
	s_waitcnt lgkmcnt(0)
	v_add_f32_e32 v35, v35, v38
	v_fmamk_f32 v35, v35, 0x3a800000, v160
	v_mul_f32_e32 v38, 0x4f800000, v35
	v_cmp_gt_f32_e32 vcc, s47, v35
	s_nop 1
	v_cndmask_b32_e32 v40, v35, v38, vcc
	v_sqrt_f32_e32 v41, v40
	v_ashrrev_i32_e32 v35, 31, v34
	v_lshlrev_b64 v[38:39], 6, v[34:35]
	v_lshl_add_u64 v[38:39], v[138:139], 0, v[38:39]
	v_add_u32_e32 v35, -1, v41
	v_add_u32_e32 v42, 1, v41
	v_fma_f32 v43, -v35, v41, v40
	v_fma_f32 v44, -v42, v41, v40
	v_cmp_ge_f32_e64 s[8:9], 0, v43
	s_nop 1
	v_cndmask_b32_e64 v35, v41, v35, s[8:9]
	v_cmp_lt_f32_e64 s[8:9], 0, v44
	s_nop 1
	v_cndmask_b32_e64 v35, v35, v42, s[8:9]
	v_mul_f32_e32 v41, 0x37800000, v35
	v_cndmask_b32_e32 v35, v35, v41, vcc
	v_cmp_class_f32_e32 vcc, v40, v161
	s_nop 1
	v_cndmask_b32_e32 v35, v35, v40, vcc
	v_div_scale_f32 v40, s[8:9], v35, v35, 1.0
	v_rcp_f32_e32 v41, v40
	v_div_scale_f32 v42, vcc, 1.0, v35, 1.0
	v_fma_f32 v43, -v40, v41, 1.0
	v_fmac_f32_e32 v41, v43, v41
	v_mul_f32_e32 v43, v42, v41
	v_fma_f32 v44, -v40, v43, v42
	v_fmac_f32_e32 v43, v44, v41
	v_fma_f32 v40, -v40, v43, v42
	v_div_fmas_f32 v40, v40, v41, v43
	v_div_fixup_f32 v40, v40, v35, 1.0
	v_mov_b32_e32 v238, v40
	v_pk_mul_f32 v[30:31], v[30:31], v[40:41] op_sel_hi:[1,0]
	v_pk_mul_f32 v[32:33], v[32:33], v[40:41] op_sel_hi:[1,0]
	v_pk_mul_f32 v[26:27], v[26:27], v[40:41] op_sel_hi:[1,0]
	v_pk_mul_f32 v[28:29], v[28:29], v[40:41] op_sel_hi:[1,0]
	v_pk_mul_f32 v[22:23], v[22:23], v[40:41] op_sel_hi:[1,0]
	v_pk_mul_f32 v[24:25], v[24:25], v[40:41] op_sel_hi:[1,0]
	v_pk_mul_f32 v[18:19], v[18:19], v[40:41] op_sel_hi:[1,0]
	v_pk_mul_f32 v[20:21], v[20:21], v[40:41] op_sel_hi:[1,0]
	v_mul_f32_e32 v35, 0xbfb8aa3b, v30
	v_mul_f32_e32 v40, 0xbfb8aa3b, v31
	v_mul_f32_e32 v41, 0xbfb8aa3b, v32
	v_mul_f32_e32 v42, 0xbfb8aa3b, v33
	v_mul_f32_e32 v43, 0xbfb8aa3b, v26
	v_mul_f32_e32 v44, 0xbfb8aa3b, v27
	v_mul_f32_e32 v45, 0xbfb8aa3b, v28
	v_mul_f32_e32 v46, 0xbfb8aa3b, v29
	v_exp_f32_e32 v35, v35
	v_exp_f32_e32 v40, v40
	v_exp_f32_e32 v41, v41
	v_exp_f32_e32 v42, v42
	v_exp_f32_e32 v43, v43
	v_exp_f32_e32 v44, v44
	v_exp_f32_e32 v45, v45
	v_exp_f32_e32 v46, v46
	v_add_f32_e32 v35, 1.0, v35
	v_add_f32_e32 v47, 1.0, v40
	v_add_f32_e32 v48, 1.0, v41
	v_add_f32_e32 v49, 1.0, v42
	v_add_f32_e32 v50, 1.0, v43
	v_add_f32_e32 v51, 1.0, v44
	v_add_f32_e32 v52, 1.0, v45
	v_add_f32_e32 v53, 1.0, v46
	v_rcp_f32_e32 v40, v35
	v_rcp_f32_e32 v41, v47
	v_rcp_f32_e32 v42, v48
	v_rcp_f32_e32 v43, v49
	v_rcp_f32_e32 v44, v50
	v_rcp_f32_e32 v45, v51
	v_rcp_f32_e32 v46, v52
	v_rcp_f32_e32 v47, v53
	v_pk_mul_f32 v[30:31], v[30:31], v[40:41]
	v_pk_mul_f32 v[32:33], v[32:33], v[42:43]
	v_pk_mul_f32 v[26:27], v[26:27], v[44:45]
	v_pk_mul_f32 v[28:29], v[28:29], v[46:47]
	v_pk_mul_f32 v[22:23], v[22:23], v[30:31]
	v_pk_mul_f32 v[24:25], v[24:25], v[32:33]
	v_pk_mul_f32 v[26:27], v[18:19], v[26:27]
	v_pk_mul_f32 v[28:29], v[20:21], v[28:29]
	v_cvt_pk_bf16_f32 v18, v22, v23
	v_cvt_pk_bf16_f32 v19, v24, v25
	v_cvt_pk_bf16_f32 v20, v26, v27
	v_cvt_pk_bf16_f32 v21, v28, v29
	global_store_dwordx4 v[36:37], v[18:21], off
	s_nop 1
	v_mov_b32_e32 v18, v218
	v_mov_b32_e32 v19, v219
	v_mov_b32_e32 v20, v220
	v_mov_b32_e32 v21, v221
	v_mov_b32_e32 v22, v19
	v_mov_b32_e32 v23, v20
	v_mov_b32_e32 v19, v21
	v_pk_add_f32 v[18:19], v[22:23], v[18:19]
	s_nop 0
	v_add_f32_e32 v18, v18, v19
	ds_bpermute_b32 v19, v153, v18
	s_waitcnt lgkmcnt(0)
	v_add_f32_e32 v18, v18, v19
	ds_bpermute_b32 v19, v162, v18
	s_waitcnt lgkmcnt(0)
	v_add_f32_e32 v18, v18, v19
	v_fmamk_f32 v18, v18, 0x3a800000, v160
	v_mul_f32_e32 v19, 0x4f800000, v18
	v_cmp_gt_f32_e32 vcc, s47, v18
	s_nop 1
	v_cndmask_b32_e32 v20, v18, v19, vcc
	v_sqrt_f32_e32 v21, v20
	v_mad_i64_i32 v[18:19], s[8:9], v34, s48, v[148:149]
	v_lshl_add_u64 v[18:19], v[18:19], 0, v[150:151]
	v_add_u32_e32 v22, -1, v21
	v_add_u32_e32 v23, 1, v21
	v_fma_f32 v24, -v22, v21, v20
	v_fma_f32 v25, -v23, v21, v20
	v_cmp_ge_f32_e64 s[8:9], 0, v24
	s_nop 1
	v_cndmask_b32_e64 v21, v21, v22, s[8:9]
	v_cmp_lt_f32_e64 s[8:9], 0, v25
	s_nop 1
	v_cndmask_b32_e64 v21, v21, v23, s[8:9]
	v_mul_f32_e32 v22, 0x37800000, v21
	v_cndmask_b32_e32 v21, v21, v22, vcc
	v_cmp_class_f32_e32 vcc, v20, v161
	s_nop 1
	v_cndmask_b32_e32 v20, v21, v20, vcc
	v_div_scale_f32 v21, s[8:9], v20, v20, 1.0
	v_rcp_f32_e32 v22, v21
	v_div_scale_f32 v23, vcc, 1.0, v20, 1.0
	v_fma_f32 v24, -v21, v22, 1.0
	v_fmac_f32_e32 v22, v24, v22
	v_mul_f32_e32 v24, v23, v22
	v_fma_f32 v25, -v21, v24, v23
	v_fmac_f32_e32 v24, v25, v22
	v_fma_f32 v21, -v21, v24, v23
	v_div_fmas_f32 v21, v21, v22, v24
	v_div_fixup_f32 v20, v21, v20, 1.0
	v_mov_b32_e32 v239, v20
	v_pk_mul_f32 v[14:15], v[14:15], v[20:21] op_sel_hi:[1,0]
	v_pk_mul_f32 v[16:17], v[16:17], v[20:21] op_sel_hi:[1,0]
	v_pk_mul_f32 v[10:11], v[10:11], v[20:21] op_sel_hi:[1,0]
	v_pk_mul_f32 v[12:13], v[12:13], v[20:21] op_sel_hi:[1,0]
	v_pk_mul_f32 v[6:7], v[6:7], v[20:21] op_sel_hi:[1,0]
	v_pk_mul_f32 v[8:9], v[8:9], v[20:21] op_sel_hi:[1,0]
	v_pk_mul_f32 v[2:3], v[2:3], v[20:21] op_sel_hi:[1,0]
	v_pk_mul_f32 v[4:5], v[4:5], v[20:21] op_sel_hi:[1,0]
	v_mul_f32_e32 v20, 0xbfb8aa3b, v14
	v_mul_f32_e32 v21, 0xbfb8aa3b, v15
	v_mul_f32_e32 v22, 0xbfb8aa3b, v16
	v_mul_f32_e32 v23, 0xbfb8aa3b, v17
	v_mul_f32_e32 v24, 0xbfb8aa3b, v10
	v_mul_f32_e32 v25, 0xbfb8aa3b, v11
	v_mul_f32_e32 v26, 0xbfb8aa3b, v12
	v_mul_f32_e32 v27, 0xbfb8aa3b, v13
	v_exp_f32_e32 v20, v20
	v_exp_f32_e32 v21, v21
	v_exp_f32_e32 v22, v22
	v_exp_f32_e32 v23, v23
	v_exp_f32_e32 v24, v24
	v_exp_f32_e32 v25, v25
	v_exp_f32_e32 v26, v26
	v_exp_f32_e32 v27, v27
	v_add_f32_e32 v20, 1.0, v20
	v_add_f32_e32 v21, 1.0, v21
	v_add_f32_e32 v22, 1.0, v22
	v_add_f32_e32 v23, 1.0, v23
	v_add_f32_e32 v24, 1.0, v24
	v_add_f32_e32 v25, 1.0, v25
	v_add_f32_e32 v26, 1.0, v26
	v_add_f32_e32 v27, 1.0, v27
	v_rcp_f32_e32 v20, v20
	v_rcp_f32_e32 v21, v21
	v_rcp_f32_e32 v22, v22
	v_rcp_f32_e32 v23, v23
	v_rcp_f32_e32 v24, v24
	v_rcp_f32_e32 v25, v25
	v_rcp_f32_e32 v26, v26
	v_rcp_f32_e32 v27, v27
	v_pk_mul_f32 v[14:15], v[14:15], v[20:21]
	v_pk_mul_f32 v[16:17], v[16:17], v[22:23]
	v_pk_mul_f32 v[10:11], v[10:11], v[24:25]
	v_pk_mul_f32 v[12:13], v[12:13], v[26:27]
	v_pk_mul_f32 v[6:7], v[6:7], v[14:15]
	v_pk_mul_f32 v[8:9], v[8:9], v[16:17]
	v_pk_mul_f32 v[10:11], v[2:3], v[10:11]
	v_pk_mul_f32 v[12:13], v[4:5], v[12:13]
	s_andn2_b64 vcc, exec, s[6:7]
	v_cvt_pk_bf16_f32 v2, v6, v7
	v_cvt_pk_bf16_f32 v3, v8, v9
	v_cvt_pk_bf16_f32 v4, v10, v11
	v_cvt_pk_bf16_f32 v5, v12, v13
	s_mov_b64 s[6:7], -1
	global_store_dwordx4 v[18:19], v[2:5], off
	s_branch .Lmy_p1_join
; __device__ __forceinline__ unsigned pk2(float lo, float hi) { const f32x2 v = {lo, hi}; const bf16x2_t b = __builtin_convertvector(v, bf16x2_t); return __builtin_bit_cast(unsigned, b); }
; __device__ __forceinline__ float frcp(float x) { return __builtin_amdgcn_rcpf(x); }
;     __device__ __forceinline__ void operator()(const f32x4 (&acc)[2][2][4][2], const Unit& u, int wr, int wc, int fr, int fq) const {
;         const int row0 = u.pm * 256 + wr * 64 + fr, col0 = u.pn * 128 + wc * 32 + 8 * fq;
; #pragma unroll
;         for (int ai = 0; ai < 2; ++ai)
; #pragma unroll
;             for (int m = 0; m < 4; ++m) {
;                 const int row = row0 + ai * 128 + m * 16; const float rs = row_rstd_q(ssq, row, fq);
;                 float h[8];
; #pragma unroll
;                 for (int n = 0; n < 2; ++n) {
;                     const f32x4 a = acc[ai][0][m][n] * rs, b = acc[ai][1][m][n] * rs;
; #pragma unroll
;                     for (int j = 0; j < 4; ++j) h[4 * n + j] = a[j] * frcp(1.0f + __expf(-a[j])) * b[j];
;                 }
;                 u32x4 w; w.x = pk2(h[0], h[1]); w.y = pk2(h[2], h[3]); w.z = pk2(h[4], h[5]); w.w = pk2(h[6], h[7]);
;                 *(u32x4*)(O + (size_t)row * FF_ + col0) = w;
.Lmy_p1_fast:
	v_lshl_add_u32 v152, s8, 8, v1
	v_mov_b64_e32 v[148:149], s[26:27]
	v_lshl_or_b32 v150, s9, 7, v155
	v_ashrrev_i32_e32 v151, 31, v150
	v_lshlrev_b64 v[150:151], 1, v[150:151]
	v_or_b32_e32 v166, 16, v152
	s_waitcnt lgkmcnt(0)
	v_mad_i64_i32 v[164:165], s[8:9], v152, s48, v[148:149]
	v_lshl_add_u64 v[164:165], v[164:165], 0, v[150:151]
	s_waitcnt lgkmcnt(0)
	s_nop 1
	s_nop 1
	s_nop 1
	s_nop 1
	v_mov_b32_e32 v170, v232
	v_pk_mul_f32 v[126:127], v[126:127], v[170:171] op_sel_hi:[1,0]
	v_pk_mul_f32 v[128:129], v[128:129], v[170:171] op_sel_hi:[1,0]
	v_pk_mul_f32 v[122:123], v[122:123], v[170:171] op_sel_hi:[1,0]
	v_pk_mul_f32 v[124:125], v[124:125], v[170:171] op_sel_hi:[1,0]
	v_pk_mul_f32 v[118:119], v[118:119], v[170:171] op_sel_hi:[1,0]
	v_pk_mul_f32 v[120:121], v[120:121], v[170:171] op_sel_hi:[1,0]
	v_pk_mul_f32 v[114:115], v[114:115], v[170:171] op_sel_hi:[1,0]
	v_pk_mul_f32 v[116:117], v[116:117], v[170:171] op_sel_hi:[1,0]
	v_mul_f32_e32 v163, 0xbfb8aa3b, v126
	v_mul_f32_e32 v167, 0xbfb8aa3b, v127
	v_mul_f32_e32 v170, 0xbfb8aa3b, v128
	v_mul_f32_e32 v171, 0xbfb8aa3b, v129
	v_mul_f32_e32 v172, 0xbfb8aa3b, v122
	v_mul_f32_e32 v173, 0xbfb8aa3b, v123
	v_mul_f32_e32 v174, 0xbfb8aa3b, v124
	v_mul_f32_e32 v175, 0xbfb8aa3b, v125
	v_exp_f32_e32 v163, v163
	v_exp_f32_e32 v167, v167
	v_exp_f32_e32 v170, v170
	v_exp_f32_e32 v171, v171
	v_exp_f32_e32 v172, v172
	v_exp_f32_e32 v173, v173
	v_exp_f32_e32 v174, v174
	v_exp_f32_e32 v175, v175
	v_add_f32_e32 v163, 1.0, v163
	v_add_f32_e32 v167, 1.0, v167
	v_add_f32_e32 v176, 1.0, v170
	v_add_f32_e32 v177, 1.0, v171
	v_add_f32_e32 v178, 1.0, v172
	v_add_f32_e32 v179, 1.0, v173
	v_add_f32_e32 v180, 1.0, v174
	v_add_f32_e32 v181, 1.0, v175
	v_rcp_f32_e32 v170, v163
	v_rcp_f32_e32 v171, v167
	v_rcp_f32_e32 v172, v176
	v_rcp_f32_e32 v173, v177
	v_rcp_f32_e32 v174, v178
	v_rcp_f32_e32 v175, v179
	v_rcp_f32_e32 v176, v180
	v_rcp_f32_e32 v177, v181
	v_pk_mul_f32 v[126:127], v[126:127], v[170:171]
	v_pk_mul_f32 v[128:129], v[128:129], v[172:173]
	v_pk_mul_f32 v[122:123], v[122:123], v[174:175]
	v_pk_mul_f32 v[124:125], v[124:125], v[176:177]
	v_pk_mul_f32 v[118:119], v[118:119], v[126:127]
	v_pk_mul_f32 v[120:121], v[120:121], v[128:129]
	v_pk_mul_f32 v[122:123], v[114:115], v[122:123]
	v_pk_mul_f32 v[124:125], v[116:117], v[124:125]
	v_cvt_pk_bf16_f32 v114, v118, v119
	v_cvt_pk_bf16_f32 v115, v120, v121
	v_cvt_pk_bf16_f32 v116, v122, v123
	v_cvt_pk_bf16_f32 v117, v124, v125
	global_store_dwordx4 v[164:165], v[114:117], off
	s_nop 1
	v_mad_i64_i32 v[116:117], s[8:9], v166, s48, v[148:149]
	v_lshl_add_u64 v[116:117], v[116:117], 0, v[150:151]
	s_waitcnt lgkmcnt(0)
	v_or_b32_e32 v114, 32, v152
	s_waitcnt lgkmcnt(0)
	s_nop 1
	s_nop 1
	s_nop 1
	s_nop 1
	v_mov_b32_e32 v120, v233
	v_pk_mul_f32 v[110:111], v[110:111], v[120:121] op_sel_hi:[1,0]
	v_pk_mul_f32 v[112:113], v[112:113], v[120:121] op_sel_hi:[1,0]
	v_pk_mul_f32 v[106:107], v[106:107], v[120:121] op_sel_hi:[1,0]
	v_pk_mul_f32 v[108:109], v[108:109], v[120:121] op_sel_hi:[1,0]
	v_pk_mul_f32 v[102:103], v[102:103], v[120:121] op_sel_hi:[1,0]
	v_pk_mul_f32 v[104:105], v[104:105], v[120:121] op_sel_hi:[1,0]
	v_pk_mul_f32 v[98:99], v[98:99], v[120:121] op_sel_hi:[1,0]
	v_pk_mul_f32 v[100:101], v[100:101], v[120:121] op_sel_hi:[1,0]
	v_mul_f32_e32 v115, 0xbfb8aa3b, v110
	v_mul_f32_e32 v120, 0xbfb8aa3b, v111
	v_mul_f32_e32 v121, 0xbfb8aa3b, v112
	v_mul_f32_e32 v122, 0xbfb8aa3b, v113
	v_mul_f32_e32 v123, 0xbfb8aa3b, v106
	v_mul_f32_e32 v124, 0xbfb8aa3b, v107
	v_mul_f32_e32 v125, 0xbfb8aa3b, v108
	v_mul_f32_e32 v126, 0xbfb8aa3b, v109
	v_exp_f32_e32 v115, v115
	v_exp_f32_e32 v120, v120
	v_exp_f32_e32 v121, v121
	v_exp_f32_e32 v122, v122
	v_exp_f32_e32 v123, v123
	v_exp_f32_e32 v124, v124
	v_exp_f32_e32 v125, v125
	v_exp_f32_e32 v126, v126
	v_add_f32_e32 v115, 1.0, v115
	v_add_f32_e32 v127, 1.0, v120
	v_add_f32_e32 v128, 1.0, v121
	v_add_f32_e32 v129, 1.0, v122
	v_add_f32_e32 v163, 1.0, v123
	v_add_f32_e32 v164, 1.0, v124
	v_add_f32_e32 v165, 1.0, v125
	v_add_f32_e32 v166, 1.0, v126
	v_rcp_f32_e32 v120, v115
	v_rcp_f32_e32 v121, v127
	v_rcp_f32_e32 v122, v128
	v_rcp_f32_e32 v123, v129
	v_rcp_f32_e32 v124, v163
	v_rcp_f32_e32 v125, v164
	v_rcp_f32_e32 v126, v165
	v_rcp_f32_e32 v127, v166
	v_pk_mul_f32 v[110:111], v[110:111], v[120:121]
	v_pk_mul_f32 v[112:113], v[112:113], v[122:123]
	v_pk_mul_f32 v[106:107], v[106:107], v[124:125]
	v_pk_mul_f32 v[108:109], v[108:109], v[126:127]
	v_pk_mul_f32 v[102:103], v[102:103], v[110:111]
	v_pk_mul_f32 v[104:105], v[104:105], v[112:113]
	v_pk_mul_f32 v[106:107], v[98:99], v[106:107]
	v_pk_mul_f32 v[108:109], v[100:101], v[108:109]
	v_cvt_pk_bf16_f32 v98, v102, v103
	v_cvt_pk_bf16_f32 v99, v104, v105
	v_cvt_pk_bf16_f32 v100, v106, v107
	v_cvt_pk_bf16_f32 v101, v108, v109
	global_store_dwordx4 v[116:117], v[98:101], off
	s_nop 1
	v_mad_i64_i32 v[100:101], s[8:9], v114, s48, v[148:149]
	v_lshl_add_u64 v[100:101], v[100:101], 0, v[150:151]
	s_waitcnt lgkmcnt(0)
	v_or_b32_e32 v98, 48, v152
	s_waitcnt lgkmcnt(0)
; __device__ __forceinline__ unsigned pk2(float lo, float hi) { const f32x2 v = {lo, hi}; const bf16x2_t b = __builtin_convertvector(v, bf16x2_t); return __builtin_bit_cast(unsigned, b); }
; __device__ __forceinline__ float frcp(float x) { return __builtin_amdgcn_rcpf(x); }
;     __device__ __forceinline__ void operator()(const f32x4 (&acc)[2][2][4][2], const Unit& u, int wr, int wc, int fr, int fq) const {
;         const int row0 = u.pm * 256 + wr * 64 + fr, col0 = u.pn * 128 + wc * 32 + 8 * fq;
; #pragma unroll
;         for (int ai = 0; ai < 2; ++ai)
; #pragma unroll
;             for (int m = 0; m < 4; ++m) {
;                 const int row = row0 + ai * 128 + m * 16; const float rs = row_rstd_q(ssq, row, fq);
;                 float h[8];
; #pragma unroll
;                 for (int n = 0; n < 2; ++n) {
;                     const f32x4 a = acc[ai][0][m][n] * rs, b = acc[ai][1][m][n] * rs;
; #pragma unroll
;                     for (int j = 0; j < 4; ++j) h[4 * n + j] = a[j] * frcp(1.0f + __expf(-a[j])) * b[j];
;                 }
;                 u32x4 w; w.x = pk2(h[0], h[1]); w.y = pk2(h[2], h[3]); w.z = pk2(h[4], h[5]); w.w = pk2(h[6], h[7]);
;                 *(u32x4*)(O + (size_t)row * FF_ + col0) = w;
	s_nop 1
	s_nop 1
	s_nop 1
	s_nop 1
	v_mov_b32_e32 v104, v234
	v_pk_mul_f32 v[94:95], v[94:95], v[104:105] op_sel_hi:[1,0]
	v_pk_mul_f32 v[96:97], v[96:97], v[104:105] op_sel_hi:[1,0]
	v_pk_mul_f32 v[90:91], v[90:91], v[104:105] op_sel_hi:[1,0]
	v_pk_mul_f32 v[92:93], v[92:93], v[104:105] op_sel_hi:[1,0]
	v_pk_mul_f32 v[86:87], v[86:87], v[104:105] op_sel_hi:[1,0]
	v_pk_mul_f32 v[88:89], v[88:89], v[104:105] op_sel_hi:[1,0]
	v_pk_mul_f32 v[82:83], v[82:83], v[104:105] op_sel_hi:[1,0]
	v_pk_mul_f32 v[84:85], v[84:85], v[104:105] op_sel_hi:[1,0]
	v_mul_f32_e32 v99, 0xbfb8aa3b, v94
	v_mul_f32_e32 v104, 0xbfb8aa3b, v95
	v_mul_f32_e32 v105, 0xbfb8aa3b, v96
	v_mul_f32_e32 v106, 0xbfb8aa3b, v97
	v_mul_f32_e32 v107, 0xbfb8aa3b, v90
	v_mul_f32_e32 v108, 0xbfb8aa3b, v91
	v_mul_f32_e32 v109, 0xbfb8aa3b, v92
	v_mul_f32_e32 v110, 0xbfb8aa3b, v93
	v_exp_f32_e32 v99, v99
	v_exp_f32_e32 v104, v104
	v_exp_f32_e32 v105, v105
	v_exp_f32_e32 v106, v106
	v_exp_f32_e32 v107, v107
	v_exp_f32_e32 v108, v108
	v_exp_f32_e32 v109, v109
	v_exp_f32_e32 v110, v110
	v_add_f32_e32 v99, 1.0, v99
	v_add_f32_e32 v111, 1.0, v104
	v_add_f32_e32 v112, 1.0, v105
	v_add_f32_e32 v113, 1.0, v106
	v_add_f32_e32 v114, 1.0, v107
	v_add_f32_e32 v115, 1.0, v108
	v_add_f32_e32 v116, 1.0, v109
	v_add_f32_e32 v117, 1.0, v110
	v_rcp_f32_e32 v104, v99
	v_rcp_f32_e32 v105, v111
	v_rcp_f32_e32 v106, v112
	v_rcp_f32_e32 v107, v113
	v_rcp_f32_e32 v108, v114
	v_rcp_f32_e32 v109, v115
	v_rcp_f32_e32 v110, v116
	v_rcp_f32_e32 v111, v117
	v_pk_mul_f32 v[94:95], v[94:95], v[104:105]
	v_pk_mul_f32 v[96:97], v[96:97], v[106:107]
	v_pk_mul_f32 v[90:91], v[90:91], v[108:109]
	v_pk_mul_f32 v[92:93], v[92:93], v[110:111]
	v_pk_mul_f32 v[86:87], v[86:87], v[94:95]
	v_pk_mul_f32 v[88:89], v[88:89], v[96:97]
	v_pk_mul_f32 v[90:91], v[82:83], v[90:91]
	v_pk_mul_f32 v[92:93], v[84:85], v[92:93]
	v_cvt_pk_bf16_f32 v82, v86, v87
	v_cvt_pk_bf16_f32 v83, v88, v89
	v_cvt_pk_bf16_f32 v84, v90, v91
	v_cvt_pk_bf16_f32 v85, v92, v93
	global_store_dwordx4 v[100:101], v[82:85], off
	s_nop 1
	v_mad_i64_i32 v[84:85], s[8:9], v98, s48, v[148:149]
	v_lshl_add_u64 v[84:85], v[84:85], 0, v[150:151]
	s_waitcnt lgkmcnt(0)
	v_add_u32_e32 v82, 0x80, v152
	s_waitcnt lgkmcnt(0)
	s_nop 1
	s_nop 1
	s_nop 1
	s_nop 1
	v_mov_b32_e32 v88, v235
	v_pk_mul_f32 v[78:79], v[78:79], v[88:89] op_sel_hi:[1,0]
	v_pk_mul_f32 v[80:81], v[80:81], v[88:89] op_sel_hi:[1,0]
	v_pk_mul_f32 v[74:75], v[74:75], v[88:89] op_sel_hi:[1,0]
	v_pk_mul_f32 v[76:77], v[76:77], v[88:89] op_sel_hi:[1,0]
	v_pk_mul_f32 v[70:71], v[70:71], v[88:89] op_sel_hi:[1,0]
	v_pk_mul_f32 v[72:73], v[72:73], v[88:89] op_sel_hi:[1,0]
	v_pk_mul_f32 v[66:67], v[66:67], v[88:89] op_sel_hi:[1,0]
	v_pk_mul_f32 v[68:69], v[68:69], v[88:89] op_sel_hi:[1,0]
	v_mul_f32_e32 v83, 0xbfb8aa3b, v78
	v_mul_f32_e32 v88, 0xbfb8aa3b, v79
	v_mul_f32_e32 v89, 0xbfb8aa3b, v80
	v_mul_f32_e32 v90, 0xbfb8aa3b, v81
	v_mul_f32_e32 v91, 0xbfb8aa3b, v74
	v_mul_f32_e32 v92, 0xbfb8aa3b, v75
	v_mul_f32_e32 v93, 0xbfb8aa3b, v76
	v_mul_f32_e32 v94, 0xbfb8aa3b, v77
	v_exp_f32_e32 v83, v83
	v_exp_f32_e32 v88, v88
	v_exp_f32_e32 v89, v89
	v_exp_f32_e32 v90, v90
	v_exp_f32_e32 v91, v91
	v_exp_f32_e32 v92, v92
	v_exp_f32_e32 v93, v93
	v_exp_f32_e32 v94, v94
	v_add_f32_e32 v83, 1.0, v83
	v_add_f32_e32 v95, 1.0, v88
	v_add_f32_e32 v96, 1.0, v89
	v_add_f32_e32 v97, 1.0, v90
	v_add_f32_e32 v98, 1.0, v91
	v_add_f32_e32 v99, 1.0, v92
	v_add_f32_e32 v100, 1.0, v93
	v_add_f32_e32 v101, 1.0, v94
	v_rcp_f32_e32 v88, v83
	v_rcp_f32_e32 v89, v95
	v_rcp_f32_e32 v90, v96
	v_rcp_f32_e32 v91, v97
	v_rcp_f32_e32 v92, v98
	v_rcp_f32_e32 v93, v99
	v_rcp_f32_e32 v94, v100
	v_rcp_f32_e32 v95, v101
	v_pk_mul_f32 v[78:79], v[78:79], v[88:89]
	v_pk_mul_f32 v[80:81], v[80:81], v[90:91]
	v_pk_mul_f32 v[74:75], v[74:75], v[92:93]
	v_pk_mul_f32 v[76:77], v[76:77], v[94:95]
	v_pk_mul_f32 v[70:71], v[70:71], v[78:79]
	v_pk_mul_f32 v[72:73], v[72:73], v[80:81]
	v_pk_mul_f32 v[74:75], v[66:67], v[74:75]
	v_pk_mul_f32 v[76:77], v[68:69], v[76:77]
	v_cvt_pk_bf16_f32 v66, v70, v71
	v_cvt_pk_bf16_f32 v67, v72, v73
	v_cvt_pk_bf16_f32 v68, v74, v75
	v_cvt_pk_bf16_f32 v69, v76, v77
	global_store_dwordx4 v[84:85], v[66:69], off
	s_nop 1
	v_mad_i64_i32 v[68:69], s[8:9], v82, s48, v[148:149]
	v_lshl_add_u64 v[68:69], v[68:69], 0, v[150:151]
	s_waitcnt lgkmcnt(0)
	v_add_u32_e32 v66, 0x90, v152
	s_waitcnt lgkmcnt(0)
	s_nop 1
	s_nop 1
	s_nop 1
	s_nop 1
	v_mov_b32_e32 v72, v236
	v_pk_mul_f32 v[62:63], v[62:63], v[72:73] op_sel_hi:[1,0]
	v_pk_mul_f32 v[64:65], v[64:65], v[72:73] op_sel_hi:[1,0]
	v_pk_mul_f32 v[58:59], v[58:59], v[72:73] op_sel_hi:[1,0]
	v_pk_mul_f32 v[60:61], v[60:61], v[72:73] op_sel_hi:[1,0]
	v_pk_mul_f32 v[54:55], v[54:55], v[72:73] op_sel_hi:[1,0]
	v_pk_mul_f32 v[56:57], v[56:57], v[72:73] op_sel_hi:[1,0]
	v_pk_mul_f32 v[50:51], v[50:51], v[72:73] op_sel_hi:[1,0]
	v_pk_mul_f32 v[52:53], v[52:53], v[72:73] op_sel_hi:[1,0]
	v_mul_f32_e32 v67, 0xbfb8aa3b, v62
	v_mul_f32_e32 v72, 0xbfb8aa3b, v63
	v_mul_f32_e32 v73, 0xbfb8aa3b, v64
	v_mul_f32_e32 v74, 0xbfb8aa3b, v65
	v_mul_f32_e32 v75, 0xbfb8aa3b, v58
	v_mul_f32_e32 v76, 0xbfb8aa3b, v59
	v_mul_f32_e32 v77, 0xbfb8aa3b, v60
	v_mul_f32_e32 v78, 0xbfb8aa3b, v61
	v_exp_f32_e32 v67, v67
	v_exp_f32_e32 v72, v72
	v_exp_f32_e32 v73, v73
	v_exp_f32_e32 v74, v74
	v_exp_f32_e32 v75, v75
	v_exp_f32_e32 v76, v76
	v_exp_f32_e32 v77, v77
	v_exp_f32_e32 v78, v78
	v_add_f32_e32 v67, 1.0, v67
	v_add_f32_e32 v79, 1.0, v72
	v_add_f32_e32 v80, 1.0, v73
	v_add_f32_e32 v81, 1.0, v74
	v_add_f32_e32 v82, 1.0, v75
	v_add_f32_e32 v83, 1.0, v76
	v_add_f32_e32 v84, 1.0, v77
	v_add_f32_e32 v85, 1.0, v78
	v_rcp_f32_e32 v72, v67
	v_rcp_f32_e32 v73, v79
	v_rcp_f32_e32 v74, v80
	v_rcp_f32_e32 v75, v81
	v_rcp_f32_e32 v76, v82
	v_rcp_f32_e32 v77, v83
	v_rcp_f32_e32 v78, v84
	v_rcp_f32_e32 v79, v85
	v_pk_mul_f32 v[62:63], v[62:63], v[72:73]
	v_pk_mul_f32 v[64:65], v[64:65], v[74:75]
	v_pk_mul_f32 v[58:59], v[58:59], v[76:77]
	v_pk_mul_f32 v[60:61], v[60:61], v[78:79]
	v_pk_mul_f32 v[54:55], v[54:55], v[62:63]
	v_pk_mul_f32 v[56:57], v[56:57], v[64:65]
	v_pk_mul_f32 v[58:59], v[50:51], v[58:59]
	v_pk_mul_f32 v[60:61], v[52:53], v[60:61]
	v_cvt_pk_bf16_f32 v50, v54, v55
	v_cvt_pk_bf16_f32 v51, v56, v57
	v_cvt_pk_bf16_f32 v52, v58, v59
	v_cvt_pk_bf16_f32 v53, v60, v61
	global_store_dwordx4 v[68:69], v[50:53], off
	s_nop 1
	v_mad_i64_i32 v[52:53], s[8:9], v66, s48, v[148:149]
	v_lshl_add_u64 v[52:53], v[52:53], 0, v[150:151]
	s_waitcnt lgkmcnt(0)
; __device__ __forceinline__ unsigned pk2(float lo, float hi) { const f32x2 v = {lo, hi}; const bf16x2_t b = __builtin_convertvector(v, bf16x2_t); return __builtin_bit_cast(unsigned, b); }
; __device__ __forceinline__ float frcp(float x) { return __builtin_amdgcn_rcpf(x); }
;     __device__ __forceinline__ void operator()(const f32x4 (&acc)[2][2][4][2], const Unit& u, int wr, int wc, int fr, int fq) const {
;         const int row0 = u.pm * 256 + wr * 64 + fr, col0 = u.pn * 128 + wc * 32 + 8 * fq;
; #pragma unroll
;         for (int ai = 0; ai < 2; ++ai)
; #pragma unroll
;             for (int m = 0; m < 4; ++m) {
;                 const int row = row0 + ai * 128 + m * 16; const float rs = row_rstd_q(ssq, row, fq);
;                 float h[8];
; #pragma unroll
;                 for (int n = 0; n < 2; ++n) {
;                     const f32x4 a = acc[ai][0][m][n] * rs, b = acc[ai][1][m][n] * rs;
; #pragma unroll
;                     for (int j = 0; j < 4; ++j) h[4 * n + j] = a[j] * frcp(1.0f + __expf(-a[j])) * b[j];
;                 }
;                 u32x4 w; w.x = pk2(h[0], h[1]); w.y = pk2(h[2], h[3]); w.z = pk2(h[4], h[5]); w.w = pk2(h[6], h[7]);
;                 *(u32x4*)(O + (size_t)row * FF_ + col0) = w;
	v_add_u32_e32 v50, 0xa0, v152
	s_waitcnt lgkmcnt(0)
	s_nop 1
	s_nop 1
	s_nop 1
	s_nop 1
	v_mov_b32_e32 v56, v237
	v_pk_mul_f32 v[46:47], v[46:47], v[56:57] op_sel_hi:[1,0]
	v_pk_mul_f32 v[48:49], v[48:49], v[56:57] op_sel_hi:[1,0]
	v_pk_mul_f32 v[42:43], v[42:43], v[56:57] op_sel_hi:[1,0]
	v_pk_mul_f32 v[44:45], v[44:45], v[56:57] op_sel_hi:[1,0]
	v_pk_mul_f32 v[38:39], v[38:39], v[56:57] op_sel_hi:[1,0]
	v_pk_mul_f32 v[40:41], v[40:41], v[56:57] op_sel_hi:[1,0]
	v_pk_mul_f32 v[34:35], v[34:35], v[56:57] op_sel_hi:[1,0]
	v_pk_mul_f32 v[36:37], v[36:37], v[56:57] op_sel_hi:[1,0]
	v_mul_f32_e32 v51, 0xbfb8aa3b, v46
	v_mul_f32_e32 v56, 0xbfb8aa3b, v47
	v_mul_f32_e32 v57, 0xbfb8aa3b, v48
	v_mul_f32_e32 v58, 0xbfb8aa3b, v49
	v_mul_f32_e32 v59, 0xbfb8aa3b, v42
	v_mul_f32_e32 v60, 0xbfb8aa3b, v43
	v_mul_f32_e32 v61, 0xbfb8aa3b, v44
	v_mul_f32_e32 v62, 0xbfb8aa3b, v45
	v_exp_f32_e32 v51, v51
	v_exp_f32_e32 v56, v56
	v_exp_f32_e32 v57, v57
	v_exp_f32_e32 v58, v58
	v_exp_f32_e32 v59, v59
	v_exp_f32_e32 v60, v60
	v_exp_f32_e32 v61, v61
	v_exp_f32_e32 v62, v62
	v_add_f32_e32 v51, 1.0, v51
	v_add_f32_e32 v63, 1.0, v56
	v_add_f32_e32 v64, 1.0, v57
	v_add_f32_e32 v65, 1.0, v58
	v_add_f32_e32 v66, 1.0, v59
	v_add_f32_e32 v67, 1.0, v60
	v_add_f32_e32 v68, 1.0, v61
	v_add_f32_e32 v69, 1.0, v62
	v_rcp_f32_e32 v56, v51
	v_rcp_f32_e32 v57, v63
	v_rcp_f32_e32 v58, v64
	v_rcp_f32_e32 v59, v65
	v_rcp_f32_e32 v60, v66
	v_rcp_f32_e32 v61, v67
	v_rcp_f32_e32 v62, v68
	v_rcp_f32_e32 v63, v69
	v_pk_mul_f32 v[46:47], v[46:47], v[56:57]
	v_pk_mul_f32 v[48:49], v[48:49], v[58:59]
	v_pk_mul_f32 v[42:43], v[42:43], v[60:61]
	v_pk_mul_f32 v[44:45], v[44:45], v[62:63]
	v_pk_mul_f32 v[38:39], v[38:39], v[46:47]
	v_pk_mul_f32 v[40:41], v[40:41], v[48:49]
	v_pk_mul_f32 v[42:43], v[34:35], v[42:43]
	v_pk_mul_f32 v[44:45], v[36:37], v[44:45]
	v_cvt_pk_bf16_f32 v34, v38, v39
	v_cvt_pk_bf16_f32 v35, v40, v41
	v_cvt_pk_bf16_f32 v36, v42, v43
	v_cvt_pk_bf16_f32 v37, v44, v45
	global_store_dwordx4 v[52:53], v[34:37], off
	s_nop 1
	v_mad_i64_i32 v[36:37], s[8:9], v50, s48, v[148:149]
	v_lshl_add_u64 v[36:37], v[36:37], 0, v[150:151]
	s_waitcnt lgkmcnt(0)
	v_add_u32_e32 v34, 0xb0, v152
	s_waitcnt lgkmcnt(0)
	s_nop 1
	s_nop 1
	s_nop 1
	s_nop 1
	v_mov_b32_e32 v40, v238
	v_pk_mul_f32 v[30:31], v[30:31], v[40:41] op_sel_hi:[1,0]
	v_pk_mul_f32 v[32:33], v[32:33], v[40:41] op_sel_hi:[1,0]
	v_pk_mul_f32 v[26:27], v[26:27], v[40:41] op_sel_hi:[1,0]
	v_pk_mul_f32 v[28:29], v[28:29], v[40:41] op_sel_hi:[1,0]
	v_pk_mul_f32 v[22:23], v[22:23], v[40:41] op_sel_hi:[1,0]
	v_pk_mul_f32 v[24:25], v[24:25], v[40:41] op_sel_hi:[1,0]
	v_pk_mul_f32 v[18:19], v[18:19], v[40:41] op_sel_hi:[1,0]
	v_pk_mul_f32 v[20:21], v[20:21], v[40:41] op_sel_hi:[1,0]
	v_mul_f32_e32 v35, 0xbfb8aa3b, v30
	v_mul_f32_e32 v40, 0xbfb8aa3b, v31
	v_mul_f32_e32 v41, 0xbfb8aa3b, v32
	v_mul_f32_e32 v42, 0xbfb8aa3b, v33
	v_mul_f32_e32 v43, 0xbfb8aa3b, v26
	v_mul_f32_e32 v44, 0xbfb8aa3b, v27
	v_mul_f32_e32 v45, 0xbfb8aa3b, v28
	v_mul_f32_e32 v46, 0xbfb8aa3b, v29
	v_exp_f32_e32 v35, v35
	v_exp_f32_e32 v40, v40
	v_exp_f32_e32 v41, v41
	v_exp_f32_e32 v42, v42
	v_exp_f32_e32 v43, v43
	v_exp_f32_e32 v44, v44
	v_exp_f32_e32 v45, v45
	v_exp_f32_e32 v46, v46
	v_add_f32_e32 v35, 1.0, v35
	v_add_f32_e32 v47, 1.0, v40
	v_add_f32_e32 v48, 1.0, v41
	v_add_f32_e32 v49, 1.0, v42
	v_add_f32_e32 v50, 1.0, v43
	v_add_f32_e32 v51, 1.0, v44
	v_add_f32_e32 v52, 1.0, v45
	v_add_f32_e32 v53, 1.0, v46
	v_rcp_f32_e32 v40, v35
	v_rcp_f32_e32 v41, v47
	v_rcp_f32_e32 v42, v48
	v_rcp_f32_e32 v43, v49
	v_rcp_f32_e32 v44, v50
	v_rcp_f32_e32 v45, v51
	v_rcp_f32_e32 v46, v52
	v_rcp_f32_e32 v47, v53
	v_pk_mul_f32 v[30:31], v[30:31], v[40:41]
	v_pk_mul_f32 v[32:33], v[32:33], v[42:43]
	v_pk_mul_f32 v[26:27], v[26:27], v[44:45]
	v_pk_mul_f32 v[28:29], v[28:29], v[46:47]
	v_pk_mul_f32 v[22:23], v[22:23], v[30:31]
	v_pk_mul_f32 v[24:25], v[24:25], v[32:33]
	v_pk_mul_f32 v[26:27], v[18:19], v[26:27]
	v_pk_mul_f32 v[28:29], v[20:21], v[28:29]
	v_cvt_pk_bf16_f32 v18, v22, v23
	v_cvt_pk_bf16_f32 v19, v24, v25
	v_cvt_pk_bf16_f32 v20, v26, v27
	v_cvt_pk_bf16_f32 v21, v28, v29
	global_store_dwordx4 v[36:37], v[18:21], off
	s_nop 1
	s_nop 0
	s_waitcnt lgkmcnt(0)
	s_waitcnt lgkmcnt(0)
	s_nop 1
	v_mad_i64_i32 v[18:19], s[8:9], v34, s48, v[148:149]
	v_lshl_add_u64 v[18:19], v[18:19], 0, v[150:151]
	s_nop 1
	s_nop 1
	s_nop 1
	v_mov_b32_e32 v20, v239
	v_pk_mul_f32 v[14:15], v[14:15], v[20:21] op_sel_hi:[1,0]
	v_pk_mul_f32 v[16:17], v[16:17], v[20:21] op_sel_hi:[1,0]
	v_pk_mul_f32 v[10:11], v[10:11], v[20:21] op_sel_hi:[1,0]
	v_pk_mul_f32 v[12:13], v[12:13], v[20:21] op_sel_hi:[1,0]
	v_pk_mul_f32 v[6:7], v[6:7], v[20:21] op_sel_hi:[1,0]
	v_pk_mul_f32 v[8:9], v[8:9], v[20:21] op_sel_hi:[1,0]
	v_pk_mul_f32 v[2:3], v[2:3], v[20:21] op_sel_hi:[1,0]
	v_pk_mul_f32 v[4:5], v[4:5], v[20:21] op_sel_hi:[1,0]
	v_mul_f32_e32 v20, 0xbfb8aa3b, v14
	v_mul_f32_e32 v21, 0xbfb8aa3b, v15
	v_mul_f32_e32 v22, 0xbfb8aa3b, v16
	v_mul_f32_e32 v23, 0xbfb8aa3b, v17
	v_mul_f32_e32 v24, 0xbfb8aa3b, v10
	v_mul_f32_e32 v25, 0xbfb8aa3b, v11
	v_mul_f32_e32 v26, 0xbfb8aa3b, v12
	v_mul_f32_e32 v27, 0xbfb8aa3b, v13
	v_exp_f32_e32 v20, v20
	v_exp_f32_e32 v21, v21
	v_exp_f32_e32 v22, v22
	v_exp_f32_e32 v23, v23
	v_exp_f32_e32 v24, v24
	v_exp_f32_e32 v25, v25
	v_exp_f32_e32 v26, v26
	v_exp_f32_e32 v27, v27
	v_add_f32_e32 v20, 1.0, v20
	v_add_f32_e32 v21, 1.0, v21
	v_add_f32_e32 v22, 1.0, v22
	v_add_f32_e32 v23, 1.0, v23
	v_add_f32_e32 v24, 1.0, v24
	v_add_f32_e32 v25, 1.0, v25
	v_add_f32_e32 v26, 1.0, v26
	v_add_f32_e32 v27, 1.0, v27
	v_rcp_f32_e32 v20, v20
	v_rcp_f32_e32 v21, v21
	v_rcp_f32_e32 v22, v22
	v_rcp_f32_e32 v23, v23
	v_rcp_f32_e32 v24, v24
	v_rcp_f32_e32 v25, v25
	v_rcp_f32_e32 v26, v26
	v_rcp_f32_e32 v27, v27
	v_pk_mul_f32 v[14:15], v[14:15], v[20:21]
	v_pk_mul_f32 v[16:17], v[16:17], v[22:23]
	v_pk_mul_f32 v[10:11], v[10:11], v[24:25]
	v_pk_mul_f32 v[12:13], v[12:13], v[26:27]
	v_pk_mul_f32 v[6:7], v[6:7], v[14:15]
	v_pk_mul_f32 v[8:9], v[8:9], v[16:17]
	v_pk_mul_f32 v[10:11], v[2:3], v[10:11]
	v_pk_mul_f32 v[12:13], v[4:5], v[12:13]
	s_andn2_b64 vcc, exec, s[6:7]
	v_cvt_pk_bf16_f32 v2, v6, v7
	v_cvt_pk_bf16_f32 v3, v8, v9
	v_cvt_pk_bf16_f32 v4, v10, v11
	v_cvt_pk_bf16_f32 v5, v12, v13
	s_mov_b64 s[6:7], -1
	global_store_dwordx4 v[18:19], v[2:5], off
	s_nop 1
.Lmy_p1_join:
	s_cbranch_vccnz .LBB0_248
	s_andn2_b64 vcc, exec, s[12:13]
	s_cbranch_vccnz .LBB0_247
	s_barrier
	s_branch .LBB0_247

; #define PG8_STAGE(bufoff, gbase, voff) do { _Pragma("unroll") for (int _i = 0; _i < 2; ++_i) \
;         __builtin_amdgcn_global_load_lds((const unsigned*)((const char*)(gbase) + (voff)[_i]), (PG8_LAS unsigned*)(lds + (bufoff) + ldsw + _i * 8192), 16, 0, 0); } while (0)
; #define PG8_WAIT_V(n) asm volatile("s_waitcnt vmcnt(" #n ")" ::: "memory")
; #define PG8_BAR __builtin_amdgcn_s_barrier()
; template <class Epi, class Sched, bool ALIGN_EPI = false, bool SP2 = false>
; __device__ __forceinline__ void gemm_phase(PG8_LAS unsigned char* lds, const Gemm g, const Sched& S, const Epi& E) {
;     ...
;     Unit cur, nxt; int ui = 0;
;     if (!S.next(0, cur)) return;
;     f32x4 acc[2][2][4][2];
; #pragma unroll
;     for (int a = 0; a < 2; ++a)
; #pragma unroll
;         for (int b = 0; b < 2; ++b)
; #pragma unroll
;             for (int m = 0; m < 4; ++m)
; #pragma unroll
;                 for (int n = 0; n < 2; ++n) acc[a][b][m][n] = (f32x4){0.f, 0.f, 0.f, 0.f};
;     bf16x8 At[4][2], B0[2][2], B1[2][2];
;     const char* cA = (const char*)g.A + (size_t)cur.pm * tstep; const char* cB = (const char*)g.Bt + (size_t)cur.pn * tstep;
;     S.a_ready(cur);
;     if constexpr (SP2) {
;         PG8_STAGE(PG8_SB(0, 0), cB, voffB); PG8_STAGE(PG8_SB(0, 1), cB + hstep, voffB); PG8_STAGE(PG8_SA(0, 0), cA, voffA); PG8_STAGE(PG8_SA(0, 1), cA + hstep, voffA);
;         if (wr == 1) PG8_BAR;
;         PG8_WAIT_V(2); PG8_BAR;
;         PG8_STAGE(PG8_SB(1, 0), cB + kstep, voffB); PG8_STAGE(PG8_SA(1, 0), cA + kstep, voffA); PG8_STAGE(PG8_SB(1, 1), cB + hstep + kstep, voffB);
;         PG8_WAIT_V(6); PG8_BAR;
; __global__ void __launch_bounds__(NTHR, 2) fwd_kernel(Args args) {
;     ...
;     if (IN(9)) {
;         pg8::Gemm g{actB, (const bf16_t*)(ws + WS_W13B), T_, 2 * FF_, D_}; pg8::StaticOrder S; S.init(T_, 2 * FF_, C.G, C.bid);
;         EpiSwiGLU E{hid, ssqA};
;         pg8::gemm_phase<EpiSwiGLU, pg8::StaticOrder, true, true>(C.lds, g, S, E);
.LBB0_1352:
	s_mov_b32 s100, -1
	s_cmp_lt_i32 s76, 10
	s_cselect_b64 s[2:3], -1, 0
	s_waitcnt lgkmcnt(0)
	s_and_b64 s[8:9], s[2:3], s[0:1]
	s_andn2_b64 vcc, exec, s[8:9]
	s_cbranch_vccnz .LBB0_1533
	s_cmpk_gt_i32 s94, 0x57f
	v_readfirstlane_b32 s1, v0
	s_cbranch_scc1 .LBB0_1369
	v_lshrrev_b32_e32 v1, 5, v0
	v_lshrrev_b32_e32 v3, 1, v0
	v_and_b32_e32 v1, 4, v1
	v_bfe_u32 v2, v0, 2, 2
	v_and_b32_e32 v3, 24, v3
	v_or3_b32 v1, v1, v2, v3
	v_lshlrev_b32_e32 v2, 4, v0
	v_or_b32_e32 v10, 0x2000, v2
	s_add_u32 s2, s26, 0x9800000
	v_lshrrev_b32_e32 v3, 7, v10
	s_movk_i32 s0, 0x60
	s_addc_u32 s3, s27, 0
	v_and_or_b32 v4, v3, s0, v1
	v_bfe_u32 v13, v0, 2, 4
	s_movk_i32 s0, 0x70
	s_ashr_i32 s5, s94, 31
	v_and_or_b32 v3, v3, s0, v13
	s_lshr_b32 s0, s5, 29
	s_add_i32 s0, s94, s0
	s_lshr_b32 s12, s1, 6
	s_ashr_i32 s6, s0, 3
	s_and_b32 s0, s0, -8
	s_lshr_b32 s37, s1, 8
	s_lshl_b32 s4, s12, 10
	s_sub_i32 s0, s94, s0
	s_cmp_lt_i32 s0, 0
	s_movk_i32 s28, 0xb1
	s_cselect_b32 s7, s28, 0xb0
	s_mul_i32 s0, s0, s7
	s_add_i32 s0, s0, s6
	s_mul_hi_i32 s6, s0, 0x2e8ba2e9
	s_lshr_b32 s7, s6, 31
	s_ashr_i32 s6, s6, 5
	s_add_i32 s6, s6, s7
	s_lshl_b32 s7, s6, 3
	s_mulk_i32 s6, 0xb0
	s_sub_i32 s6, s0, s6
	s_sext_i32_i16 s0, s6
	s_bfe_u32 s0, s0, 0x3001c
	s_add_i32 s10, s6, s0
	s_sext_i32_i16 s0, s10
	s_and_b32 s10, s10, 0xfff8
	s_sub_i32 s6, s6, s10
	s_sext_i32_i16 s6, s6
	v_and_b32_e32 v5, 32, v0
	s_lshr_b32 s0, s0, 3
	s_add_i32 s6, s7, s6
	v_bitop3_b32 v11, v2, v5, 48 bitop3:0x6c
	v_and_b32_e32 v12, 64, v0
	s_ashr_i32 s7, s6, 31
	s_bfe_i64 s[30:31], s[0:1], 0x100000
	v_or_b32_e32 v2, v11, v12
	s_lshl_b64 s[10:11], s[6:7], 19
	s_lshl_b64 s[30:31], s[30:31], 19
	s_waitcnt vmcnt(0)
	v_lshl_or_b32 v132, v3, 11, v2
	v_lshrrev_b32_e32 v3, 3, v0
	s_add_u32 s54, s2, s30
	v_and_or_b32 v1, v3, 32, v1
	s_addc_u32 s55, s3, s31
	s_add_i32 s29, s4, 0
	v_lshl_or_b32 v134, v1, 11, v2
	s_add_i32 m0, s29, 0x10000
	v_lshl_or_b32 v130, v4, 11, v2
	global_load_lds_dwordx4 v134, s[54:55]
	s_add_i32 m0, s29, 0x12000
	s_add_u32 s30, s54, 0x40000
	global_load_lds_dwordx4 v130, s[54:55]
	s_addc_u32 s31, s55, 0
	s_add_i32 m0, s29, 0x14000
	v_and_or_b32 v1, v3, 48, v13
	global_load_lds_dwordx4 v134, s[30:31]
	s_add_i32 m0, s29, 0x16000
	s_add_u32 s52, s84, s10
	global_load_lds_dwordx4 v130, s[30:31]
	s_addc_u32 s53, s85, s11
	s_add_i32 s30, s29, 0x2000
	v_lshl_or_b32 v136, v1, 11, v2
	s_mov_b32 m0, s29
	s_add_u32 s10, s52, 0x40000
	global_load_lds_dwordx4 v136, s[52:53]
	s_mov_b32 m0, s30
	s_addc_u32 s11, s53, 0
	s_add_i32 s31, s29, 0x4000
	global_load_lds_dwordx4 v132, s[52:53]
	s_mov_b32 m0, s31
	s_add_i32 s33, s29, 0x6000
	global_load_lds_dwordx4 v136, s[10:11]
	s_mov_b32 m0, s33
	v_mov_b32_e32 v135, 0
	global_load_lds_dwordx4 v132, s[10:11]
	v_mov_b32_e32 v131, v135
	v_mov_b32_e32 v137, v135
	v_mov_b32_e32 v133, v135
	s_cmp_eq_u32 s37, 1
	s_mov_b32 s34, 0
	v_lshl_add_u64 v[8:9], s[54:55], 0, v[134:135]
	v_lshl_add_u64 v[6:7], s[54:55], 0, v[130:131]
	v_lshl_add_u64 v[2:3], s[52:53], 0, v[136:137]
	s_cselect_b64 s[10:11], -1, 0
	s_cmp_lg_u32 s37, 1
	v_lshl_add_u64 v[4:5], s[52:53], 0, v[132:133]
	s_cbranch_scc1 .LBB0_1356
	s_barrier

; __device__ __forceinline__ unsigned pk2(float lo, float hi) { const f32x2 v = {lo, hi}; const bf16x2_t b = __builtin_convertvector(v, bf16x2_t); return __builtin_bit_cast(unsigned, b); }
; __device__ __forceinline__ float row_rstd_q(const float* ssq, int row, int fq) {
;     const f32x4 a = ((const f32x4*)(ssq + (size_t)row * 16))[fq];
;     float s = (a[0] + a[1]) + (a[2] + a[3]);
;     s += __shfl_xor(s, 16); s += __shfl_xor(s, 32);
;     return 1.0f / sqrtf(s * (1.0f / 1024.0f) + 1e-6f);
; }
; __device__ __forceinline__ float frcp(float x) { return __builtin_amdgcn_rcpf(x); }
; __device__ __forceinline__ float gelu_erf(float v) {
;     const float av = fabsf(v), t = frcp(av * 0.2316418882f + 1.0f);
;     float qq = t * 0.5307027145f + (-0.7265760135f); qq = qq * t + 0.7107068705f; qq = qq * t + (-0.142248368f); qq = qq * t + 0.127414796f; qq = qq * t;
;     const float e = __builtin_amdgcn_exp2f((v * v) * (-0.72134752044f));
;     const float m = v * (qq * e);
;     return v < 0.f ? m : v - m;
; }
; __device__ __forceinline__ float sigmoidf_(float x) { return frcp(1.0f + __expf(-x)); }
; __device__ __forceinline__ float tanhf_(float x) { return 1.0f - 2.0f * frcp(1.0f + __expf(2.0f * x)); }
;     __device__ __forceinline__ void operator()(const f32x4 (&acc)[2][2][4][2], const Unit& u, int wr, int wc, int fr, int fq) const {
;         const int row0 = u.pm * 256 + wr * 64 + fr, col0 = u.pn * 128 + wc * 32 + 8 * fq;
; #pragma unroll
;         for (int ai = 0; ai < 2; ++ai)
; #pragma unroll
;             for (int m = 0; m < 4; ++m) {
;                 const int row = row0 + ai * 128 + m * 16; const float rs = row_rstd_q(ssq, row, fq);
;                 float h[8];
; #pragma unroll
;                 for (int n = 0; n < 2; ++n) {
;                     const f32x4 a = acc[ai][0][m][n] * rs, b = acc[ai][1][m][n] * rs;
; #pragma unroll
;                     for (int j = 0; j < 4; ++j) h[4 * n + j] = a[j] * frcp(1.0f + __expf(-a[j])) * b[j];
;                 }
;                 u32x4 w; w.x = pk2(h[0], h[1]); w.y = pk2(h[2], h[3]); w.z = pk2(h[4], h[5]); w.w = pk2(h[6], h[7]);
;                 *(u32x4*)(O + (size_t)row * FF_ + col0) = w;
;             }
.LBB0_1365:
	s_cmp_eq_u32 s100, s6
	s_cbranch_scc1 .Lmy_p9_fast
	s_mov_b32 s100, s6
	v_lshl_add_u32 v152, s6, 8, v1
	v_ashrrev_i32_e32 v153, 31, v152
	v_lshlrev_b64 v[148:149], 6, v[152:153]
	v_lshl_add_u64 v[148:149], v[138:139], 0, v[148:149]
	global_load_dwordx4 v[162:165], v[148:149], off
	global_load_dwordx4 v[194:197], v[148:149], off offset:1024
	global_load_dwordx4 v[198:201], v[148:149], off offset:2048
	global_load_dwordx4 v[202:205], v[148:149], off offset:3072
	s_mov_b64 s[98:99], 0x2000
	v_lshl_add_u64 v[222:223], v[148:149], 0, s[98:99]
	global_load_dwordx4 v[206:209], v[222:223], off
	global_load_dwordx4 v[210:213], v[222:223], off offset:1024
	global_load_dwordx4 v[214:217], v[222:223], off offset:2048
	global_load_dwordx4 v[218:221], v[222:223], off offset:3072
	v_and_b32_e32 v153, 64, v159
	v_xor_b32_e32 v151, 16, v159
	v_add_u32_e32 v169, 64, v153
	v_cmp_lt_i32_e32 vcc, v151, v169
	v_xor_b32_e32 v168, 32, v159
	v_mov_b64_e32 v[148:149], s[26:27]
	v_cndmask_b32_e32 v151, v159, v151, vcc
	v_lshlrev_b32_e32 v153, 2, v151
	v_cmp_lt_i32_e32 vcc, v168, v169
	v_lshl_or_b32 v150, s7, 7, v155
	v_ashrrev_i32_e32 v151, 31, v150
	v_lshlrev_b64 v[150:151], 1, v[150:151]
	s_waitcnt vmcnt(0)
	v_mov_b32_e32 v166, v163
	v_mov_b32_e32 v167, v164
	v_mov_b32_e32 v163, v165
	v_pk_add_f32 v[162:163], v[166:167], v[162:163]
	v_or_b32_e32 v166, 16, v152
	v_add_f32_e32 v163, v162, v163
	ds_bpermute_b32 v164, v153, v163
	v_cndmask_b32_e32 v162, v159, v168, vcc
	v_lshlrev_b32_e32 v162, 2, v162
	s_waitcnt lgkmcnt(0)
	v_add_f32_e32 v163, v163, v164
	ds_bpermute_b32 v167, v162, v163
	v_mad_i64_i32 v[164:165], s[6:7], v152, s60, v[148:149]
	v_lshl_add_u64 v[164:165], v[164:165], 0, v[150:151]
	s_waitcnt lgkmcnt(0)
	v_add_f32_e32 v163, v163, v167
	v_fmamk_f32 v163, v163, 0x3a800000, v160
	v_mul_f32_e32 v167, 0x4f800000, v163
	v_cmp_gt_f32_e32 vcc, s59, v163
	s_nop 1
	v_cndmask_b32_e32 v163, v163, v167, vcc
	v_sqrt_f32_e32 v170, v163
	v_ashrrev_i32_e32 v167, 31, v166
	v_lshlrev_b64 v[168:169], 6, v[166:167]
	v_lshl_add_u64 v[168:169], v[138:139], 0, v[168:169]
	v_add_u32_e32 v167, -1, v170
	v_add_u32_e32 v171, 1, v170
	v_fma_f32 v172, -v167, v170, v163
	v_fma_f32 v173, -v171, v170, v163
	v_cmp_ge_f32_e64 s[6:7], 0, v172
	s_nop 1
	v_cndmask_b32_e64 v167, v170, v167, s[6:7]
	v_cmp_lt_f32_e64 s[6:7], 0, v173
	s_nop 1
	v_cndmask_b32_e64 v167, v167, v171, s[6:7]
	v_mul_f32_e32 v170, 0x37800000, v167
	v_cndmask_b32_e32 v167, v167, v170, vcc
	v_cmp_class_f32_e32 vcc, v163, v161
	s_nop 1
	v_cndmask_b32_e32 v163, v167, v163, vcc
	v_div_scale_f32 v167, s[6:7], v163, v163, 1.0
	v_rcp_f32_e32 v170, v167
	v_div_scale_f32 v171, vcc, 1.0, v163, 1.0
	v_fma_f32 v172, -v167, v170, 1.0
	v_fmac_f32_e32 v170, v172, v170
	v_mul_f32_e32 v172, v171, v170
	v_fma_f32 v173, -v167, v172, v171
	v_fmac_f32_e32 v172, v173, v170
	v_fma_f32 v167, -v167, v172, v171
	v_div_fmas_f32 v167, v167, v170, v172
	v_div_fixup_f32 v170, v167, v163, 1.0
	v_mov_b32_e32 v232, v170
	v_pk_mul_f32 v[126:127], v[126:127], v[170:171] op_sel_hi:[1,0]
	v_pk_mul_f32 v[128:129], v[128:129], v[170:171] op_sel_hi:[1,0]
	v_pk_mul_f32 v[122:123], v[122:123], v[170:171] op_sel_hi:[1,0]
	v_pk_mul_f32 v[124:125], v[124:125], v[170:171] op_sel_hi:[1,0]
	v_pk_mul_f32 v[118:119], v[118:119], v[170:171] op_sel_hi:[1,0]
	v_pk_mul_f32 v[120:121], v[120:121], v[170:171] op_sel_hi:[1,0]
	v_pk_mul_f32 v[114:115], v[114:115], v[170:171] op_sel_hi:[1,0]
	v_pk_mul_f32 v[116:117], v[116:117], v[170:171] op_sel_hi:[1,0]
	v_mul_f32_e32 v163, 0xbfb8aa3b, v126
	v_mul_f32_e32 v167, 0xbfb8aa3b, v127
	v_mul_f32_e32 v170, 0xbfb8aa3b, v128
	v_mul_f32_e32 v171, 0xbfb8aa3b, v129
	v_mul_f32_e32 v172, 0xbfb8aa3b, v122
	v_mul_f32_e32 v173, 0xbfb8aa3b, v123
	v_mul_f32_e32 v174, 0xbfb8aa3b, v124
	v_mul_f32_e32 v175, 0xbfb8aa3b, v125
	v_exp_f32_e32 v163, v163
	v_exp_f32_e32 v167, v167
	v_exp_f32_e32 v170, v170
	v_exp_f32_e32 v171, v171
	v_exp_f32_e32 v172, v172
	v_exp_f32_e32 v173, v173
	v_exp_f32_e32 v174, v174
	v_exp_f32_e32 v175, v175
	v_add_f32_e32 v163, 1.0, v163
	v_add_f32_e32 v167, 1.0, v167
	v_add_f32_e32 v176, 1.0, v170
	v_add_f32_e32 v177, 1.0, v171
	v_add_f32_e32 v178, 1.0, v172
	v_add_f32_e32 v179, 1.0, v173
	v_add_f32_e32 v180, 1.0, v174
	v_add_f32_e32 v181, 1.0, v175
	v_rcp_f32_e32 v170, v163
	v_rcp_f32_e32 v171, v167
	v_rcp_f32_e32 v172, v176
	v_rcp_f32_e32 v173, v177
	v_rcp_f32_e32 v174, v178
	v_rcp_f32_e32 v175, v179
	v_rcp_f32_e32 v176, v180
	v_rcp_f32_e32 v177, v181
	v_pk_mul_f32 v[126:127], v[126:127], v[170:171]
	v_pk_mul_f32 v[128:129], v[128:129], v[172:173]
	v_pk_mul_f32 v[122:123], v[122:123], v[174:175]
	v_pk_mul_f32 v[124:125], v[124:125], v[176:177]
	v_pk_mul_f32 v[118:119], v[118:119], v[126:127]
	v_pk_mul_f32 v[120:121], v[120:121], v[128:129]
	v_pk_mul_f32 v[122:123], v[114:115], v[122:123]
	v_pk_mul_f32 v[124:125], v[116:117], v[124:125]
	v_cvt_pk_bf16_f32 v114, v118, v119
	v_cvt_pk_bf16_f32 v115, v120, v121
	v_cvt_pk_bf16_f32 v116, v122, v123
	v_cvt_pk_bf16_f32 v117, v124, v125
	global_store_dwordx4 v[164:165], v[114:117], off
	s_nop 1
	v_mov_b32_e32 v114, v194
	v_mov_b32_e32 v115, v195
	v_mov_b32_e32 v116, v196
	v_mov_b32_e32 v117, v197
	v_mov_b32_e32 v118, v115
	v_mov_b32_e32 v119, v116
	v_mov_b32_e32 v115, v117
	v_pk_add_f32 v[114:115], v[118:119], v[114:115]
	v_mad_i64_i32 v[116:117], s[6:7], v166, s60, v[148:149]
	v_add_f32_e32 v114, v114, v115
	ds_bpermute_b32 v115, v153, v114
	v_lshl_add_u64 v[116:117], v[116:117], 0, v[150:151]
	s_waitcnt lgkmcnt(0)
	v_add_f32_e32 v115, v114, v115
	ds_bpermute_b32 v118, v162, v115
	v_or_b32_e32 v114, 32, v152
	s_waitcnt lgkmcnt(0)
; __device__ __forceinline__ unsigned pk2(float lo, float hi) { const f32x2 v = {lo, hi}; const bf16x2_t b = __builtin_convertvector(v, bf16x2_t); return __builtin_bit_cast(unsigned, b); }
; __device__ __forceinline__ float row_rstd_q(const float* ssq, int row, int fq) {
;     const f32x4 a = ((const f32x4*)(ssq + (size_t)row * 16))[fq];
;     float s = (a[0] + a[1]) + (a[2] + a[3]);
;     s += __shfl_xor(s, 16); s += __shfl_xor(s, 32);
;     return 1.0f / sqrtf(s * (1.0f / 1024.0f) + 1e-6f);
; }
; __device__ __forceinline__ float frcp(float x) { return __builtin_amdgcn_rcpf(x); }
; __device__ __forceinline__ float gelu_erf(float v) {
;     const float av = fabsf(v), t = frcp(av * 0.2316418882f + 1.0f);
;     float qq = t * 0.5307027145f + (-0.7265760135f); qq = qq * t + 0.7107068705f; qq = qq * t + (-0.142248368f); qq = qq * t + 0.127414796f; qq = qq * t;
;     const float e = __builtin_amdgcn_exp2f((v * v) * (-0.72134752044f));
;     const float m = v * (qq * e);
;     return v < 0.f ? m : v - m;
; }
; __device__ __forceinline__ float sigmoidf_(float x) { return frcp(1.0f + __expf(-x)); }
; __device__ __forceinline__ float tanhf_(float x) { return 1.0f - 2.0f * frcp(1.0f + __expf(2.0f * x)); }
;     __device__ __forceinline__ void operator()(const f32x4 (&acc)[2][2][4][2], const Unit& u, int wr, int wc, int fr, int fq) const {
;         const int row0 = u.pm * 256 + wr * 64 + fr, col0 = u.pn * 128 + wc * 32 + 8 * fq;
; #pragma unroll
;         for (int ai = 0; ai < 2; ++ai)
; #pragma unroll
;             for (int m = 0; m < 4; ++m) {
;                 const int row = row0 + ai * 128 + m * 16; const float rs = row_rstd_q(ssq, row, fq);
;                 float h[8];
; #pragma unroll
;                 for (int n = 0; n < 2; ++n) {
;                     const f32x4 a = acc[ai][0][m][n] * rs, b = acc[ai][1][m][n] * rs;
; #pragma unroll
;                     for (int j = 0; j < 4; ++j) h[4 * n + j] = a[j] * frcp(1.0f + __expf(-a[j])) * b[j];
;                 }
;                 u32x4 w; w.x = pk2(h[0], h[1]); w.y = pk2(h[2], h[3]); w.z = pk2(h[4], h[5]); w.w = pk2(h[6], h[7]);
;                 *(u32x4*)(O + (size_t)row * FF_ + col0) = w;
;             }
	v_add_f32_e32 v115, v115, v118
	v_fmamk_f32 v115, v115, 0x3a800000, v160
	v_mul_f32_e32 v118, 0x4f800000, v115
	v_cmp_gt_f32_e32 vcc, s59, v115
	s_nop 1
	v_cndmask_b32_e32 v120, v115, v118, vcc
	v_sqrt_f32_e32 v121, v120
	v_ashrrev_i32_e32 v115, 31, v114
	v_lshlrev_b64 v[118:119], 6, v[114:115]
	v_lshl_add_u64 v[118:119], v[138:139], 0, v[118:119]
	v_add_u32_e32 v115, -1, v121
	v_add_u32_e32 v122, 1, v121
	v_fma_f32 v123, -v115, v121, v120
	v_fma_f32 v124, -v122, v121, v120
	v_cmp_ge_f32_e64 s[6:7], 0, v123
	s_nop 1
	v_cndmask_b32_e64 v115, v121, v115, s[6:7]
	v_cmp_lt_f32_e64 s[6:7], 0, v124
	s_nop 1
	v_cndmask_b32_e64 v115, v115, v122, s[6:7]
	v_mul_f32_e32 v121, 0x37800000, v115
	v_cndmask_b32_e32 v115, v115, v121, vcc
	v_cmp_class_f32_e32 vcc, v120, v161
	s_nop 1
	v_cndmask_b32_e32 v115, v115, v120, vcc
	v_div_scale_f32 v120, s[6:7], v115, v115, 1.0
	v_rcp_f32_e32 v121, v120
	v_div_scale_f32 v122, vcc, 1.0, v115, 1.0
	v_fma_f32 v123, -v120, v121, 1.0
	v_fmac_f32_e32 v121, v123, v121
	v_mul_f32_e32 v123, v122, v121
	v_fma_f32 v124, -v120, v123, v122
	v_fmac_f32_e32 v123, v124, v121
	v_fma_f32 v120, -v120, v123, v122
	v_div_fmas_f32 v120, v120, v121, v123
	v_div_fixup_f32 v120, v120, v115, 1.0
	v_mov_b32_e32 v233, v120
	v_pk_mul_f32 v[110:111], v[110:111], v[120:121] op_sel_hi:[1,0]
	v_pk_mul_f32 v[112:113], v[112:113], v[120:121] op_sel_hi:[1,0]
	v_pk_mul_f32 v[106:107], v[106:107], v[120:121] op_sel_hi:[1,0]
	v_pk_mul_f32 v[108:109], v[108:109], v[120:121] op_sel_hi:[1,0]
	v_pk_mul_f32 v[102:103], v[102:103], v[120:121] op_sel_hi:[1,0]
	v_pk_mul_f32 v[104:105], v[104:105], v[120:121] op_sel_hi:[1,0]
	v_pk_mul_f32 v[98:99], v[98:99], v[120:121] op_sel_hi:[1,0]
	v_pk_mul_f32 v[100:101], v[100:101], v[120:121] op_sel_hi:[1,0]
	v_mul_f32_e32 v115, 0xbfb8aa3b, v110
	v_mul_f32_e32 v120, 0xbfb8aa3b, v111
	v_mul_f32_e32 v121, 0xbfb8aa3b, v112
	v_mul_f32_e32 v122, 0xbfb8aa3b, v113
	v_mul_f32_e32 v123, 0xbfb8aa3b, v106
	v_mul_f32_e32 v124, 0xbfb8aa3b, v107
	v_mul_f32_e32 v125, 0xbfb8aa3b, v108
	v_mul_f32_e32 v126, 0xbfb8aa3b, v109
	v_exp_f32_e32 v115, v115
	v_exp_f32_e32 v120, v120
	v_exp_f32_e32 v121, v121
	v_exp_f32_e32 v122, v122
	v_exp_f32_e32 v123, v123
	v_exp_f32_e32 v124, v124
	v_exp_f32_e32 v125, v125
	v_exp_f32_e32 v126, v126
	v_add_f32_e32 v115, 1.0, v115
	v_add_f32_e32 v127, 1.0, v120
	v_add_f32_e32 v128, 1.0, v121
	v_add_f32_e32 v129, 1.0, v122
	v_add_f32_e32 v163, 1.0, v123
	v_add_f32_e32 v164, 1.0, v124
	v_add_f32_e32 v165, 1.0, v125
	v_add_f32_e32 v166, 1.0, v126
	v_rcp_f32_e32 v120, v115
	v_rcp_f32_e32 v121, v127
	v_rcp_f32_e32 v122, v128
	v_rcp_f32_e32 v123, v129
	v_rcp_f32_e32 v124, v163
	v_rcp_f32_e32 v125, v164
	v_rcp_f32_e32 v126, v165
	v_rcp_f32_e32 v127, v166
	v_pk_mul_f32 v[110:111], v[110:111], v[120:121]
	v_pk_mul_f32 v[112:113], v[112:113], v[122:123]
	v_pk_mul_f32 v[106:107], v[106:107], v[124:125]
	v_pk_mul_f32 v[108:109], v[108:109], v[126:127]
	v_pk_mul_f32 v[102:103], v[102:103], v[110:111]
	v_pk_mul_f32 v[104:105], v[104:105], v[112:113]
	v_pk_mul_f32 v[106:107], v[98:99], v[106:107]
	v_pk_mul_f32 v[108:109], v[100:101], v[108:109]
	v_cvt_pk_bf16_f32 v98, v102, v103
	v_cvt_pk_bf16_f32 v99, v104, v105
	v_cvt_pk_bf16_f32 v100, v106, v107
	v_cvt_pk_bf16_f32 v101, v108, v109
	global_store_dwordx4 v[116:117], v[98:101], off
	s_nop 1
	v_mov_b32_e32 v98, v198
	v_mov_b32_e32 v99, v199
	v_mov_b32_e32 v100, v200
	v_mov_b32_e32 v101, v201
	v_mov_b32_e32 v102, v99
	v_mov_b32_e32 v103, v100
	v_mov_b32_e32 v99, v101
	v_pk_add_f32 v[98:99], v[102:103], v[98:99]
	v_mad_i64_i32 v[100:101], s[6:7], v114, s60, v[148:149]
	v_add_f32_e32 v98, v98, v99
	ds_bpermute_b32 v99, v153, v98
	v_lshl_add_u64 v[100:101], v[100:101], 0, v[150:151]
	s_waitcnt lgkmcnt(0)
	v_add_f32_e32 v99, v98, v99
	ds_bpermute_b32 v102, v162, v99
	v_or_b32_e32 v98, 48, v152
	s_waitcnt lgkmcnt(0)
	v_add_f32_e32 v99, v99, v102
	v_fmamk_f32 v99, v99, 0x3a800000, v160
	v_mul_f32_e32 v102, 0x4f800000, v99
	v_cmp_gt_f32_e32 vcc, s59, v99
	s_nop 1
	v_cndmask_b32_e32 v104, v99, v102, vcc
	v_sqrt_f32_e32 v105, v104
	v_ashrrev_i32_e32 v99, 31, v98
	v_lshlrev_b64 v[102:103], 6, v[98:99]
	v_lshl_add_u64 v[102:103], v[138:139], 0, v[102:103]
	v_add_u32_e32 v99, -1, v105
	v_add_u32_e32 v106, 1, v105
	v_fma_f32 v107, -v99, v105, v104
	v_fma_f32 v108, -v106, v105, v104
	v_cmp_ge_f32_e64 s[6:7], 0, v107
	s_nop 1
	v_cndmask_b32_e64 v99, v105, v99, s[6:7]
	v_cmp_lt_f32_e64 s[6:7], 0, v108
	s_nop 1
	v_cndmask_b32_e64 v99, v99, v106, s[6:7]
	v_mul_f32_e32 v105, 0x37800000, v99
	v_cndmask_b32_e32 v99, v99, v105, vcc
	v_cmp_class_f32_e32 vcc, v104, v161
	s_nop 1
	v_cndmask_b32_e32 v99, v99, v104, vcc
	v_div_scale_f32 v104, s[6:7], v99, v99, 1.0
	v_rcp_f32_e32 v105, v104
	v_div_scale_f32 v106, vcc, 1.0, v99, 1.0
	v_fma_f32 v107, -v104, v105, 1.0
	v_fmac_f32_e32 v105, v107, v105
	v_mul_f32_e32 v107, v106, v105
	v_fma_f32 v108, -v104, v107, v106
	v_fmac_f32_e32 v107, v108, v105
	v_fma_f32 v104, -v104, v107, v106
	v_div_fmas_f32 v104, v104, v105, v107
	v_div_fixup_f32 v104, v104, v99, 1.0
	v_mov_b32_e32 v234, v104
	v_pk_mul_f32 v[94:95], v[94:95], v[104:105] op_sel_hi:[1,0]
	v_pk_mul_f32 v[96:97], v[96:97], v[104:105] op_sel_hi:[1,0]
	v_pk_mul_f32 v[90:91], v[90:91], v[104:105] op_sel_hi:[1,0]
	v_pk_mul_f32 v[92:93], v[92:93], v[104:105] op_sel_hi:[1,0]
	v_pk_mul_f32 v[86:87], v[86:87], v[104:105] op_sel_hi:[1,0]
	v_pk_mul_f32 v[88:89], v[88:89], v[104:105] op_sel_hi:[1,0]
	v_pk_mul_f32 v[82:83], v[82:83], v[104:105] op_sel_hi:[1,0]
	v_pk_mul_f32 v[84:85], v[84:85], v[104:105] op_sel_hi:[1,0]
	v_mul_f32_e32 v99, 0xbfb8aa3b, v94
	v_mul_f32_e32 v104, 0xbfb8aa3b, v95
; __device__ __forceinline__ unsigned pk2(float lo, float hi) { const f32x2 v = {lo, hi}; const bf16x2_t b = __builtin_convertvector(v, bf16x2_t); return __builtin_bit_cast(unsigned, b); }
; __device__ __forceinline__ float row_rstd_q(const float* ssq, int row, int fq) {
;     const f32x4 a = ((const f32x4*)(ssq + (size_t)row * 16))[fq];
;     float s = (a[0] + a[1]) + (a[2] + a[3]);
;     s += __shfl_xor(s, 16); s += __shfl_xor(s, 32);
;     return 1.0f / sqrtf(s * (1.0f / 1024.0f) + 1e-6f);
; }
; __device__ __forceinline__ float frcp(float x) { return __builtin_amdgcn_rcpf(x); }
; __device__ __forceinline__ float gelu_erf(float v) {
;     const float av = fabsf(v), t = frcp(av * 0.2316418882f + 1.0f);
;     float qq = t * 0.5307027145f + (-0.7265760135f); qq = qq * t + 0.7107068705f; qq = qq * t + (-0.142248368f); qq = qq * t + 0.127414796f; qq = qq * t;
;     const float e = __builtin_amdgcn_exp2f((v * v) * (-0.72134752044f));
;     const float m = v * (qq * e);
;     return v < 0.f ? m : v - m;
; }
; __device__ __forceinline__ float sigmoidf_(float x) { return frcp(1.0f + __expf(-x)); }
; __device__ __forceinline__ float tanhf_(float x) { return 1.0f - 2.0f * frcp(1.0f + __expf(2.0f * x)); }
;     __device__ __forceinline__ void operator()(const f32x4 (&acc)[2][2][4][2], const Unit& u, int wr, int wc, int fr, int fq) const {
;         const int row0 = u.pm * 256 + wr * 64 + fr, col0 = u.pn * 128 + wc * 32 + 8 * fq;
; #pragma unroll
;         for (int ai = 0; ai < 2; ++ai)
; #pragma unroll
;             for (int m = 0; m < 4; ++m) {
;                 const int row = row0 + ai * 128 + m * 16; const float rs = row_rstd_q(ssq, row, fq);
;                 float h[8];
; #pragma unroll
;                 for (int n = 0; n < 2; ++n) {
;                     const f32x4 a = acc[ai][0][m][n] * rs, b = acc[ai][1][m][n] * rs;
; #pragma unroll
;                     for (int j = 0; j < 4; ++j) h[4 * n + j] = a[j] * frcp(1.0f + __expf(-a[j])) * b[j];
;                 }
;                 u32x4 w; w.x = pk2(h[0], h[1]); w.y = pk2(h[2], h[3]); w.z = pk2(h[4], h[5]); w.w = pk2(h[6], h[7]);
;                 *(u32x4*)(O + (size_t)row * FF_ + col0) = w;
;             }
	v_mul_f32_e32 v105, 0xbfb8aa3b, v96
	v_mul_f32_e32 v106, 0xbfb8aa3b, v97
	v_mul_f32_e32 v107, 0xbfb8aa3b, v90
	v_mul_f32_e32 v108, 0xbfb8aa3b, v91
	v_mul_f32_e32 v109, 0xbfb8aa3b, v92
	v_mul_f32_e32 v110, 0xbfb8aa3b, v93
	v_exp_f32_e32 v99, v99
	v_exp_f32_e32 v104, v104
	v_exp_f32_e32 v105, v105
	v_exp_f32_e32 v106, v106
	v_exp_f32_e32 v107, v107
	v_exp_f32_e32 v108, v108
	v_exp_f32_e32 v109, v109
	v_exp_f32_e32 v110, v110
	v_add_f32_e32 v99, 1.0, v99
	v_add_f32_e32 v111, 1.0, v104
	v_add_f32_e32 v112, 1.0, v105
	v_add_f32_e32 v113, 1.0, v106
	v_add_f32_e32 v114, 1.0, v107
	v_add_f32_e32 v115, 1.0, v108
	v_add_f32_e32 v116, 1.0, v109
	v_add_f32_e32 v117, 1.0, v110
	v_rcp_f32_e32 v104, v99
	v_rcp_f32_e32 v105, v111
	v_rcp_f32_e32 v106, v112
	v_rcp_f32_e32 v107, v113
	v_rcp_f32_e32 v108, v114
	v_rcp_f32_e32 v109, v115
	v_rcp_f32_e32 v110, v116
	v_rcp_f32_e32 v111, v117
	v_pk_mul_f32 v[94:95], v[94:95], v[104:105]
	v_pk_mul_f32 v[96:97], v[96:97], v[106:107]
	v_pk_mul_f32 v[90:91], v[90:91], v[108:109]
	v_pk_mul_f32 v[92:93], v[92:93], v[110:111]
	v_pk_mul_f32 v[86:87], v[86:87], v[94:95]
	v_pk_mul_f32 v[88:89], v[88:89], v[96:97]
	v_pk_mul_f32 v[90:91], v[82:83], v[90:91]
	v_pk_mul_f32 v[92:93], v[84:85], v[92:93]
	v_cvt_pk_bf16_f32 v82, v86, v87
	v_cvt_pk_bf16_f32 v83, v88, v89
	v_cvt_pk_bf16_f32 v84, v90, v91
	v_cvt_pk_bf16_f32 v85, v92, v93
	global_store_dwordx4 v[100:101], v[82:85], off
	s_nop 1
	v_mov_b32_e32 v82, v202
	v_mov_b32_e32 v83, v203
	v_mov_b32_e32 v84, v204
	v_mov_b32_e32 v85, v205
	v_mov_b32_e32 v86, v83
	v_mov_b32_e32 v87, v84
	v_mov_b32_e32 v83, v85
	v_pk_add_f32 v[82:83], v[86:87], v[82:83]
	v_mad_i64_i32 v[84:85], s[6:7], v98, s60, v[148:149]
	v_add_f32_e32 v82, v82, v83
	ds_bpermute_b32 v83, v153, v82
	v_lshl_add_u64 v[84:85], v[84:85], 0, v[150:151]
	s_waitcnt lgkmcnt(0)
	v_add_f32_e32 v83, v82, v83
	ds_bpermute_b32 v86, v162, v83
	v_add_u32_e32 v82, 0x80, v152
	s_waitcnt lgkmcnt(0)
	v_add_f32_e32 v83, v83, v86
	v_fmamk_f32 v83, v83, 0x3a800000, v160
	v_mul_f32_e32 v86, 0x4f800000, v83
	v_cmp_gt_f32_e32 vcc, s59, v83
	s_nop 1
	v_cndmask_b32_e32 v88, v83, v86, vcc
	v_sqrt_f32_e32 v89, v88
	v_ashrrev_i32_e32 v83, 31, v82
	v_lshlrev_b64 v[86:87], 6, v[82:83]
	v_lshl_add_u64 v[86:87], v[138:139], 0, v[86:87]
	v_add_u32_e32 v83, -1, v89
	v_add_u32_e32 v90, 1, v89
	v_fma_f32 v91, -v83, v89, v88
	v_fma_f32 v92, -v90, v89, v88
	v_cmp_ge_f32_e64 s[6:7], 0, v91
	s_nop 1
	v_cndmask_b32_e64 v83, v89, v83, s[6:7]
	v_cmp_lt_f32_e64 s[6:7], 0, v92
	s_nop 1
	v_cndmask_b32_e64 v83, v83, v90, s[6:7]
	v_mul_f32_e32 v89, 0x37800000, v83
	v_cndmask_b32_e32 v83, v83, v89, vcc
	v_cmp_class_f32_e32 vcc, v88, v161
	s_nop 1
	v_cndmask_b32_e32 v83, v83, v88, vcc
	v_div_scale_f32 v88, s[6:7], v83, v83, 1.0
	v_rcp_f32_e32 v89, v88
	v_div_scale_f32 v90, vcc, 1.0, v83, 1.0
	v_fma_f32 v91, -v88, v89, 1.0
	v_fmac_f32_e32 v89, v91, v89
	v_mul_f32_e32 v91, v90, v89
	v_fma_f32 v92, -v88, v91, v90
	v_fmac_f32_e32 v91, v92, v89
	v_fma_f32 v88, -v88, v91, v90
	v_div_fmas_f32 v88, v88, v89, v91
	v_div_fixup_f32 v88, v88, v83, 1.0
	v_mov_b32_e32 v235, v88
	v_pk_mul_f32 v[78:79], v[78:79], v[88:89] op_sel_hi:[1,0]
	v_pk_mul_f32 v[80:81], v[80:81], v[88:89] op_sel_hi:[1,0]
	v_pk_mul_f32 v[74:75], v[74:75], v[88:89] op_sel_hi:[1,0]
	v_pk_mul_f32 v[76:77], v[76:77], v[88:89] op_sel_hi:[1,0]
	v_pk_mul_f32 v[70:71], v[70:71], v[88:89] op_sel_hi:[1,0]
	v_pk_mul_f32 v[72:73], v[72:73], v[88:89] op_sel_hi:[1,0]
	v_pk_mul_f32 v[66:67], v[66:67], v[88:89] op_sel_hi:[1,0]
	v_pk_mul_f32 v[68:69], v[68:69], v[88:89] op_sel_hi:[1,0]
	v_mul_f32_e32 v83, 0xbfb8aa3b, v78
	v_mul_f32_e32 v88, 0xbfb8aa3b, v79
	v_mul_f32_e32 v89, 0xbfb8aa3b, v80
	v_mul_f32_e32 v90, 0xbfb8aa3b, v81
	v_mul_f32_e32 v91, 0xbfb8aa3b, v74
	v_mul_f32_e32 v92, 0xbfb8aa3b, v75
	v_mul_f32_e32 v93, 0xbfb8aa3b, v76
	v_mul_f32_e32 v94, 0xbfb8aa3b, v77
	v_exp_f32_e32 v83, v83
	v_exp_f32_e32 v88, v88
	v_exp_f32_e32 v89, v89
	v_exp_f32_e32 v90, v90
	v_exp_f32_e32 v91, v91
	v_exp_f32_e32 v92, v92
	v_exp_f32_e32 v93, v93
	v_exp_f32_e32 v94, v94
	v_add_f32_e32 v83, 1.0, v83
	v_add_f32_e32 v95, 1.0, v88
	v_add_f32_e32 v96, 1.0, v89
	v_add_f32_e32 v97, 1.0, v90
	v_add_f32_e32 v98, 1.0, v91
	v_add_f32_e32 v99, 1.0, v92
	v_add_f32_e32 v100, 1.0, v93
	v_add_f32_e32 v101, 1.0, v94
	v_rcp_f32_e32 v88, v83
	v_rcp_f32_e32 v89, v95
	v_rcp_f32_e32 v90, v96
	v_rcp_f32_e32 v91, v97
	v_rcp_f32_e32 v92, v98
	v_rcp_f32_e32 v93, v99
	v_rcp_f32_e32 v94, v100
	v_rcp_f32_e32 v95, v101
	v_pk_mul_f32 v[78:79], v[78:79], v[88:89]
	v_pk_mul_f32 v[80:81], v[80:81], v[90:91]
	v_pk_mul_f32 v[74:75], v[74:75], v[92:93]
	v_pk_mul_f32 v[76:77], v[76:77], v[94:95]
	v_pk_mul_f32 v[70:71], v[70:71], v[78:79]
	v_pk_mul_f32 v[72:73], v[72:73], v[80:81]
	v_pk_mul_f32 v[74:75], v[66:67], v[74:75]
	v_pk_mul_f32 v[76:77], v[68:69], v[76:77]
	v_cvt_pk_bf16_f32 v66, v70, v71
	v_cvt_pk_bf16_f32 v67, v72, v73
	v_cvt_pk_bf16_f32 v68, v74, v75
	v_cvt_pk_bf16_f32 v69, v76, v77
	global_store_dwordx4 v[84:85], v[66:69], off
	s_nop 1
	v_mov_b32_e32 v66, v206
	v_mov_b32_e32 v67, v207
	v_mov_b32_e32 v68, v208
	v_mov_b32_e32 v69, v209
	v_mov_b32_e32 v70, v67
	v_mov_b32_e32 v71, v68
	v_mov_b32_e32 v67, v69
	v_pk_add_f32 v[66:67], v[70:71], v[66:67]
	v_mad_i64_i32 v[68:69], s[6:7], v82, s60, v[148:149]
	v_add_f32_e32 v66, v66, v67
	ds_bpermute_b32 v67, v153, v66
	v_lshl_add_u64 v[68:69], v[68:69], 0, v[150:151]
	s_waitcnt lgkmcnt(0)
	v_add_f32_e32 v67, v66, v67
	ds_bpermute_b32 v70, v162, v67
	v_add_u32_e32 v66, 0x90, v152
	s_waitcnt lgkmcnt(0)
; __device__ __forceinline__ unsigned pk2(float lo, float hi) { const f32x2 v = {lo, hi}; const bf16x2_t b = __builtin_convertvector(v, bf16x2_t); return __builtin_bit_cast(unsigned, b); }
; __device__ __forceinline__ float row_rstd_q(const float* ssq, int row, int fq) {
;     const f32x4 a = ((const f32x4*)(ssq + (size_t)row * 16))[fq];
;     float s = (a[0] + a[1]) + (a[2] + a[3]);
;     s += __shfl_xor(s, 16); s += __shfl_xor(s, 32);
;     return 1.0f / sqrtf(s * (1.0f / 1024.0f) + 1e-6f);
; }
; __device__ __forceinline__ float frcp(float x) { return __builtin_amdgcn_rcpf(x); }
; __device__ __forceinline__ float gelu_erf(float v) {
;     const float av = fabsf(v), t = frcp(av * 0.2316418882f + 1.0f);
;     float qq = t * 0.5307027145f + (-0.7265760135f); qq = qq * t + 0.7107068705f; qq = qq * t + (-0.142248368f); qq = qq * t + 0.127414796f; qq = qq * t;
;     const float e = __builtin_amdgcn_exp2f((v * v) * (-0.72134752044f));
;     const float m = v * (qq * e);
;     return v < 0.f ? m : v - m;
; }
; __device__ __forceinline__ float sigmoidf_(float x) { return frcp(1.0f + __expf(-x)); }
; __device__ __forceinline__ float tanhf_(float x) { return 1.0f - 2.0f * frcp(1.0f + __expf(2.0f * x)); }
;     __device__ __forceinline__ void operator()(const f32x4 (&acc)[2][2][4][2], const Unit& u, int wr, int wc, int fr, int fq) const {
;         const int row0 = u.pm * 256 + wr * 64 + fr, col0 = u.pn * 128 + wc * 32 + 8 * fq;
; #pragma unroll
;         for (int ai = 0; ai < 2; ++ai)
; #pragma unroll
;             for (int m = 0; m < 4; ++m) {
;                 const int row = row0 + ai * 128 + m * 16; const float rs = row_rstd_q(ssq, row, fq);
;                 float h[8];
; #pragma unroll
;                 for (int n = 0; n < 2; ++n) {
;                     const f32x4 a = acc[ai][0][m][n] * rs, b = acc[ai][1][m][n] * rs;
; #pragma unroll
;                     for (int j = 0; j < 4; ++j) h[4 * n + j] = a[j] * frcp(1.0f + __expf(-a[j])) * b[j];
;                 }
;                 u32x4 w; w.x = pk2(h[0], h[1]); w.y = pk2(h[2], h[3]); w.z = pk2(h[4], h[5]); w.w = pk2(h[6], h[7]);
;                 *(u32x4*)(O + (size_t)row * FF_ + col0) = w;
;             }
	v_add_f32_e32 v67, v67, v70
	v_fmamk_f32 v67, v67, 0x3a800000, v160
	v_mul_f32_e32 v70, 0x4f800000, v67
	v_cmp_gt_f32_e32 vcc, s59, v67
	s_nop 1
	v_cndmask_b32_e32 v72, v67, v70, vcc
	v_sqrt_f32_e32 v73, v72
	v_ashrrev_i32_e32 v67, 31, v66
	v_lshlrev_b64 v[70:71], 6, v[66:67]
	v_lshl_add_u64 v[70:71], v[138:139], 0, v[70:71]
	v_add_u32_e32 v67, -1, v73
	v_add_u32_e32 v74, 1, v73
	v_fma_f32 v75, -v67, v73, v72
	v_fma_f32 v76, -v74, v73, v72
	v_cmp_ge_f32_e64 s[6:7], 0, v75
	s_nop 1
	v_cndmask_b32_e64 v67, v73, v67, s[6:7]
	v_cmp_lt_f32_e64 s[6:7], 0, v76
	s_nop 1
	v_cndmask_b32_e64 v67, v67, v74, s[6:7]
	v_mul_f32_e32 v73, 0x37800000, v67
	v_cndmask_b32_e32 v67, v67, v73, vcc
	v_cmp_class_f32_e32 vcc, v72, v161
	s_nop 1
	v_cndmask_b32_e32 v67, v67, v72, vcc
	v_div_scale_f32 v72, s[6:7], v67, v67, 1.0
	v_rcp_f32_e32 v73, v72
	v_div_scale_f32 v74, vcc, 1.0, v67, 1.0
	v_fma_f32 v75, -v72, v73, 1.0
	v_fmac_f32_e32 v73, v75, v73
	v_mul_f32_e32 v75, v74, v73
	v_fma_f32 v76, -v72, v75, v74
	v_fmac_f32_e32 v75, v76, v73
	v_fma_f32 v72, -v72, v75, v74
	v_div_fmas_f32 v72, v72, v73, v75
	v_div_fixup_f32 v72, v72, v67, 1.0
	v_mov_b32_e32 v236, v72
	v_pk_mul_f32 v[62:63], v[62:63], v[72:73] op_sel_hi:[1,0]
	v_pk_mul_f32 v[64:65], v[64:65], v[72:73] op_sel_hi:[1,0]
	v_pk_mul_f32 v[58:59], v[58:59], v[72:73] op_sel_hi:[1,0]
	v_pk_mul_f32 v[60:61], v[60:61], v[72:73] op_sel_hi:[1,0]
	v_pk_mul_f32 v[54:55], v[54:55], v[72:73] op_sel_hi:[1,0]
	v_pk_mul_f32 v[56:57], v[56:57], v[72:73] op_sel_hi:[1,0]
	v_pk_mul_f32 v[50:51], v[50:51], v[72:73] op_sel_hi:[1,0]
	v_pk_mul_f32 v[52:53], v[52:53], v[72:73] op_sel_hi:[1,0]
	v_mul_f32_e32 v67, 0xbfb8aa3b, v62
	v_mul_f32_e32 v72, 0xbfb8aa3b, v63
	v_mul_f32_e32 v73, 0xbfb8aa3b, v64
	v_mul_f32_e32 v74, 0xbfb8aa3b, v65
	v_mul_f32_e32 v75, 0xbfb8aa3b, v58
	v_mul_f32_e32 v76, 0xbfb8aa3b, v59
	v_mul_f32_e32 v77, 0xbfb8aa3b, v60
	v_mul_f32_e32 v78, 0xbfb8aa3b, v61
	v_exp_f32_e32 v67, v67
	v_exp_f32_e32 v72, v72
	v_exp_f32_e32 v73, v73
	v_exp_f32_e32 v74, v74
	v_exp_f32_e32 v75, v75
	v_exp_f32_e32 v76, v76
	v_exp_f32_e32 v77, v77
	v_exp_f32_e32 v78, v78
	v_add_f32_e32 v67, 1.0, v67
	v_add_f32_e32 v79, 1.0, v72
	v_add_f32_e32 v80, 1.0, v73
	v_add_f32_e32 v81, 1.0, v74
	v_add_f32_e32 v82, 1.0, v75
	v_add_f32_e32 v83, 1.0, v76
	v_add_f32_e32 v84, 1.0, v77
	v_add_f32_e32 v85, 1.0, v78
	v_rcp_f32_e32 v72, v67
	v_rcp_f32_e32 v73, v79
	v_rcp_f32_e32 v74, v80
	v_rcp_f32_e32 v75, v81
	v_rcp_f32_e32 v76, v82
	v_rcp_f32_e32 v77, v83
	v_rcp_f32_e32 v78, v84
	v_rcp_f32_e32 v79, v85
	v_pk_mul_f32 v[62:63], v[62:63], v[72:73]
	v_pk_mul_f32 v[64:65], v[64:65], v[74:75]
	v_pk_mul_f32 v[58:59], v[58:59], v[76:77]
	v_pk_mul_f32 v[60:61], v[60:61], v[78:79]
	v_pk_mul_f32 v[54:55], v[54:55], v[62:63]
	v_pk_mul_f32 v[56:57], v[56:57], v[64:65]
	v_pk_mul_f32 v[58:59], v[50:51], v[58:59]
	v_pk_mul_f32 v[60:61], v[52:53], v[60:61]
	v_cvt_pk_bf16_f32 v50, v54, v55
	v_cvt_pk_bf16_f32 v51, v56, v57
	v_cvt_pk_bf16_f32 v52, v58, v59
	v_cvt_pk_bf16_f32 v53, v60, v61
	global_store_dwordx4 v[68:69], v[50:53], off
	s_nop 1
	v_mov_b32_e32 v50, v210
	v_mov_b32_e32 v51, v211
	v_mov_b32_e32 v52, v212
	v_mov_b32_e32 v53, v213
	v_mov_b32_e32 v54, v51
	v_mov_b32_e32 v55, v52
	v_mov_b32_e32 v51, v53
	v_pk_add_f32 v[50:51], v[54:55], v[50:51]
	v_mad_i64_i32 v[52:53], s[6:7], v66, s60, v[148:149]
	v_add_f32_e32 v50, v50, v51
	ds_bpermute_b32 v51, v153, v50
	v_lshl_add_u64 v[52:53], v[52:53], 0, v[150:151]
	s_waitcnt lgkmcnt(0)
	v_add_f32_e32 v51, v50, v51
	ds_bpermute_b32 v54, v162, v51
	v_add_u32_e32 v50, 0xa0, v152
	s_waitcnt lgkmcnt(0)
	v_add_f32_e32 v51, v51, v54
	v_fmamk_f32 v51, v51, 0x3a800000, v160
	v_mul_f32_e32 v54, 0x4f800000, v51
	v_cmp_gt_f32_e32 vcc, s59, v51
	s_nop 1
	v_cndmask_b32_e32 v56, v51, v54, vcc
	v_sqrt_f32_e32 v57, v56
	v_ashrrev_i32_e32 v51, 31, v50
	v_lshlrev_b64 v[54:55], 6, v[50:51]
	v_lshl_add_u64 v[54:55], v[138:139], 0, v[54:55]
	v_add_u32_e32 v51, -1, v57
	v_add_u32_e32 v58, 1, v57
	v_fma_f32 v59, -v51, v57, v56
	v_fma_f32 v60, -v58, v57, v56
	v_cmp_ge_f32_e64 s[6:7], 0, v59
	s_nop 1
	v_cndmask_b32_e64 v51, v57, v51, s[6:7]
	v_cmp_lt_f32_e64 s[6:7], 0, v60
	s_nop 1
	v_cndmask_b32_e64 v51, v51, v58, s[6:7]
	v_mul_f32_e32 v57, 0x37800000, v51
	v_cndmask_b32_e32 v51, v51, v57, vcc
	v_cmp_class_f32_e32 vcc, v56, v161
	s_nop 1
	v_cndmask_b32_e32 v51, v51, v56, vcc
	v_div_scale_f32 v56, s[6:7], v51, v51, 1.0
	v_rcp_f32_e32 v57, v56
	v_div_scale_f32 v58, vcc, 1.0, v51, 1.0
	v_fma_f32 v59, -v56, v57, 1.0
	v_fmac_f32_e32 v57, v59, v57
	v_mul_f32_e32 v59, v58, v57
	v_fma_f32 v60, -v56, v59, v58
	v_fmac_f32_e32 v59, v60, v57
	v_fma_f32 v56, -v56, v59, v58
	v_div_fmas_f32 v56, v56, v57, v59
	v_div_fixup_f32 v56, v56, v51, 1.0
	v_mov_b32_e32 v237, v56
	v_pk_mul_f32 v[46:47], v[46:47], v[56:57] op_sel_hi:[1,0]
	v_pk_mul_f32 v[48:49], v[48:49], v[56:57] op_sel_hi:[1,0]
	v_pk_mul_f32 v[42:43], v[42:43], v[56:57] op_sel_hi:[1,0]
	v_pk_mul_f32 v[44:45], v[44:45], v[56:57] op_sel_hi:[1,0]
	v_pk_mul_f32 v[38:39], v[38:39], v[56:57] op_sel_hi:[1,0]
	v_pk_mul_f32 v[40:41], v[40:41], v[56:57] op_sel_hi:[1,0]
	v_pk_mul_f32 v[34:35], v[34:35], v[56:57] op_sel_hi:[1,0]
	v_pk_mul_f32 v[36:37], v[36:37], v[56:57] op_sel_hi:[1,0]
	v_mul_f32_e32 v51, 0xbfb8aa3b, v46
	v_mul_f32_e32 v56, 0xbfb8aa3b, v47
	v_mul_f32_e32 v57, 0xbfb8aa3b, v48
	v_mul_f32_e32 v58, 0xbfb8aa3b, v49
	v_mul_f32_e32 v59, 0xbfb8aa3b, v42
	v_mul_f32_e32 v60, 0xbfb8aa3b, v43
	v_mul_f32_e32 v61, 0xbfb8aa3b, v44
	v_mul_f32_e32 v62, 0xbfb8aa3b, v45
	v_exp_f32_e32 v51, v51
	v_exp_f32_e32 v56, v56
	v_exp_f32_e32 v57, v57
	v_exp_f32_e32 v58, v58
	v_exp_f32_e32 v59, v59
	v_exp_f32_e32 v60, v60
	v_exp_f32_e32 v61, v61
	v_exp_f32_e32 v62, v62
	v_add_f32_e32 v51, 1.0, v51
	v_add_f32_e32 v63, 1.0, v56
	v_add_f32_e32 v64, 1.0, v57
	v_add_f32_e32 v65, 1.0, v58
	v_add_f32_e32 v66, 1.0, v59
	v_add_f32_e32 v67, 1.0, v60
	v_add_f32_e32 v68, 1.0, v61
	v_add_f32_e32 v69, 1.0, v62
	v_rcp_f32_e32 v56, v51
	v_rcp_f32_e32 v57, v63
	v_rcp_f32_e32 v58, v64
	v_rcp_f32_e32 v59, v65
	v_rcp_f32_e32 v60, v66
	v_rcp_f32_e32 v61, v67
	v_rcp_f32_e32 v62, v68
	v_rcp_f32_e32 v63, v69
	v_pk_mul_f32 v[46:47], v[46:47], v[56:57]
	v_pk_mul_f32 v[48:49], v[48:49], v[58:59]
	v_pk_mul_f32 v[42:43], v[42:43], v[60:61]
	v_pk_mul_f32 v[44:45], v[44:45], v[62:63]
	v_pk_mul_f32 v[38:39], v[38:39], v[46:47]
	v_pk_mul_f32 v[40:41], v[40:41], v[48:49]
	v_pk_mul_f32 v[42:43], v[34:35], v[42:43]
	v_pk_mul_f32 v[44:45], v[36:37], v[44:45]
	v_cvt_pk_bf16_f32 v34, v38, v39
	v_cvt_pk_bf16_f32 v35, v40, v41
	v_cvt_pk_bf16_f32 v36, v42, v43
	v_cvt_pk_bf16_f32 v37, v44, v45
	global_store_dwordx4 v[52:53], v[34:37], off
	s_nop 1
	v_mov_b32_e32 v34, v214
	v_mov_b32_e32 v35, v215
	v_mov_b32_e32 v36, v216
	v_mov_b32_e32 v37, v217
	v_mov_b32_e32 v38, v35
	v_mov_b32_e32 v39, v36
	v_mov_b32_e32 v35, v37
	v_pk_add_f32 v[34:35], v[38:39], v[34:35]
	v_mad_i64_i32 v[36:37], s[6:7], v50, s60, v[148:149]
	v_add_f32_e32 v34, v34, v35
	ds_bpermute_b32 v35, v153, v34
	v_lshl_add_u64 v[36:37], v[36:37], 0, v[150:151]
	s_waitcnt lgkmcnt(0)
; __device__ __forceinline__ unsigned pk2(float lo, float hi) { const f32x2 v = {lo, hi}; const bf16x2_t b = __builtin_convertvector(v, bf16x2_t); return __builtin_bit_cast(unsigned, b); }
; __device__ __forceinline__ float row_rstd_q(const float* ssq, int row, int fq) {
;     const f32x4 a = ((const f32x4*)(ssq + (size_t)row * 16))[fq];
;     float s = (a[0] + a[1]) + (a[2] + a[3]);
;     s += __shfl_xor(s, 16); s += __shfl_xor(s, 32);
;     return 1.0f / sqrtf(s * (1.0f / 1024.0f) + 1e-6f);
; }
; __device__ __forceinline__ float frcp(float x) { return __builtin_amdgcn_rcpf(x); }
; __device__ __forceinline__ float gelu_erf(float v) {
;     const float av = fabsf(v), t = frcp(av * 0.2316418882f + 1.0f);
;     float qq = t * 0.5307027145f + (-0.7265760135f); qq = qq * t + 0.7107068705f; qq = qq * t + (-0.142248368f); qq = qq * t + 0.127414796f; qq = qq * t;
;     const float e = __builtin_amdgcn_exp2f((v * v) * (-0.72134752044f));
;     const float m = v * (qq * e);
;     return v < 0.f ? m : v - m;
; }
; __device__ __forceinline__ float sigmoidf_(float x) { return frcp(1.0f + __expf(-x)); }
; __device__ __forceinline__ float tanhf_(float x) { return 1.0f - 2.0f * frcp(1.0f + __expf(2.0f * x)); }
;     __device__ __forceinline__ void operator()(const f32x4 (&acc)[2][2][4][2], const Unit& u, int wr, int wc, int fr, int fq) const {
;         const int row0 = u.pm * 256 + wr * 64 + fr, col0 = u.pn * 128 + wc * 32 + 8 * fq;
; #pragma unroll
;         for (int ai = 0; ai < 2; ++ai)
; #pragma unroll
;             for (int m = 0; m < 4; ++m) {
;                 const int row = row0 + ai * 128 + m * 16; const float rs = row_rstd_q(ssq, row, fq);
;                 float h[8];
; #pragma unroll
;                 for (int n = 0; n < 2; ++n) {
;                     const f32x4 a = acc[ai][0][m][n] * rs, b = acc[ai][1][m][n] * rs;
; #pragma unroll
;                     for (int j = 0; j < 4; ++j) h[4 * n + j] = a[j] * frcp(1.0f + __expf(-a[j])) * b[j];
;                 }
;                 u32x4 w; w.x = pk2(h[0], h[1]); w.y = pk2(h[2], h[3]); w.z = pk2(h[4], h[5]); w.w = pk2(h[6], h[7]);
;                 *(u32x4*)(O + (size_t)row * FF_ + col0) = w;
;             }
	v_add_f32_e32 v35, v34, v35
	ds_bpermute_b32 v38, v162, v35
	v_add_u32_e32 v34, 0xb0, v152
	s_waitcnt lgkmcnt(0)
	v_add_f32_e32 v35, v35, v38
	v_fmamk_f32 v35, v35, 0x3a800000, v160
	v_mul_f32_e32 v38, 0x4f800000, v35
	v_cmp_gt_f32_e32 vcc, s59, v35
	s_nop 1
	v_cndmask_b32_e32 v40, v35, v38, vcc
	v_sqrt_f32_e32 v41, v40
	v_ashrrev_i32_e32 v35, 31, v34
	v_lshlrev_b64 v[38:39], 6, v[34:35]
	v_lshl_add_u64 v[38:39], v[138:139], 0, v[38:39]
	v_add_u32_e32 v35, -1, v41
	v_add_u32_e32 v42, 1, v41
	v_fma_f32 v43, -v35, v41, v40
	v_fma_f32 v44, -v42, v41, v40
	v_cmp_ge_f32_e64 s[6:7], 0, v43
	s_nop 1
	v_cndmask_b32_e64 v35, v41, v35, s[6:7]
	v_cmp_lt_f32_e64 s[6:7], 0, v44
	s_nop 1
	v_cndmask_b32_e64 v35, v35, v42, s[6:7]
	v_mul_f32_e32 v41, 0x37800000, v35
	v_cndmask_b32_e32 v35, v35, v41, vcc
	v_cmp_class_f32_e32 vcc, v40, v161
	s_nop 1
	v_cndmask_b32_e32 v35, v35, v40, vcc
	v_div_scale_f32 v40, s[6:7], v35, v35, 1.0
	v_rcp_f32_e32 v41, v40
	v_div_scale_f32 v42, vcc, 1.0, v35, 1.0
	v_fma_f32 v43, -v40, v41, 1.0
	v_fmac_f32_e32 v41, v43, v41
	v_mul_f32_e32 v43, v42, v41
	v_fma_f32 v44, -v40, v43, v42
	v_fmac_f32_e32 v43, v44, v41
	v_fma_f32 v40, -v40, v43, v42
	v_div_fmas_f32 v40, v40, v41, v43
	v_div_fixup_f32 v40, v40, v35, 1.0
	v_mov_b32_e32 v238, v40
	v_pk_mul_f32 v[30:31], v[30:31], v[40:41] op_sel_hi:[1,0]
	v_pk_mul_f32 v[32:33], v[32:33], v[40:41] op_sel_hi:[1,0]
	v_pk_mul_f32 v[26:27], v[26:27], v[40:41] op_sel_hi:[1,0]
	v_pk_mul_f32 v[28:29], v[28:29], v[40:41] op_sel_hi:[1,0]
	v_pk_mul_f32 v[22:23], v[22:23], v[40:41] op_sel_hi:[1,0]
	v_pk_mul_f32 v[24:25], v[24:25], v[40:41] op_sel_hi:[1,0]
	v_pk_mul_f32 v[18:19], v[18:19], v[40:41] op_sel_hi:[1,0]
	v_pk_mul_f32 v[20:21], v[20:21], v[40:41] op_sel_hi:[1,0]
	v_mul_f32_e32 v35, 0xbfb8aa3b, v30
	v_mul_f32_e32 v40, 0xbfb8aa3b, v31
	v_mul_f32_e32 v41, 0xbfb8aa3b, v32
	v_mul_f32_e32 v42, 0xbfb8aa3b, v33
	v_mul_f32_e32 v43, 0xbfb8aa3b, v26
	v_mul_f32_e32 v44, 0xbfb8aa3b, v27
	v_mul_f32_e32 v45, 0xbfb8aa3b, v28
	v_mul_f32_e32 v46, 0xbfb8aa3b, v29
	v_exp_f32_e32 v35, v35
	v_exp_f32_e32 v40, v40
	v_exp_f32_e32 v41, v41
	v_exp_f32_e32 v42, v42
	v_exp_f32_e32 v43, v43
	v_exp_f32_e32 v44, v44
	v_exp_f32_e32 v45, v45
	v_exp_f32_e32 v46, v46
	v_add_f32_e32 v35, 1.0, v35
	v_add_f32_e32 v47, 1.0, v40
	v_add_f32_e32 v48, 1.0, v41
	v_add_f32_e32 v49, 1.0, v42
	v_add_f32_e32 v50, 1.0, v43
	v_add_f32_e32 v51, 1.0, v44
	v_add_f32_e32 v52, 1.0, v45
	v_add_f32_e32 v53, 1.0, v46
	v_rcp_f32_e32 v40, v35
	v_rcp_f32_e32 v41, v47
	v_rcp_f32_e32 v42, v48
	v_rcp_f32_e32 v43, v49
	v_rcp_f32_e32 v44, v50
	v_rcp_f32_e32 v45, v51
	v_rcp_f32_e32 v46, v52
	v_rcp_f32_e32 v47, v53
	v_pk_mul_f32 v[30:31], v[30:31], v[40:41]
	v_pk_mul_f32 v[32:33], v[32:33], v[42:43]
	v_pk_mul_f32 v[26:27], v[26:27], v[44:45]
	v_pk_mul_f32 v[28:29], v[28:29], v[46:47]
	v_pk_mul_f32 v[22:23], v[22:23], v[30:31]
	v_pk_mul_f32 v[24:25], v[24:25], v[32:33]
	v_pk_mul_f32 v[26:27], v[18:19], v[26:27]
	v_pk_mul_f32 v[28:29], v[20:21], v[28:29]
	v_cvt_pk_bf16_f32 v18, v22, v23
	v_cvt_pk_bf16_f32 v19, v24, v25
	v_cvt_pk_bf16_f32 v20, v26, v27
	v_cvt_pk_bf16_f32 v21, v28, v29
	global_store_dwordx4 v[36:37], v[18:21], off
	s_nop 1
	v_mov_b32_e32 v18, v218
	v_mov_b32_e32 v19, v219
	v_mov_b32_e32 v20, v220
	v_mov_b32_e32 v21, v221
	v_mov_b32_e32 v22, v19
	v_mov_b32_e32 v23, v20
	v_mov_b32_e32 v19, v21
	v_pk_add_f32 v[18:19], v[22:23], v[18:19]
	s_nop 0
	v_add_f32_e32 v18, v18, v19
	ds_bpermute_b32 v19, v153, v18
	s_waitcnt lgkmcnt(0)
	v_add_f32_e32 v18, v18, v19
	ds_bpermute_b32 v19, v162, v18
	s_waitcnt lgkmcnt(0)
	v_add_f32_e32 v18, v18, v19
	v_fmamk_f32 v18, v18, 0x3a800000, v160
	v_mul_f32_e32 v19, 0x4f800000, v18
	v_cmp_gt_f32_e32 vcc, s59, v18
	s_nop 1
	v_cndmask_b32_e32 v20, v18, v19, vcc
	v_sqrt_f32_e32 v21, v20
	v_mad_i64_i32 v[18:19], s[6:7], v34, s60, v[148:149]
	v_lshl_add_u64 v[18:19], v[18:19], 0, v[150:151]
	v_add_u32_e32 v22, -1, v21
	v_add_u32_e32 v23, 1, v21
	v_fma_f32 v24, -v22, v21, v20
	v_fma_f32 v25, -v23, v21, v20
	v_cmp_ge_f32_e64 s[6:7], 0, v24
	s_nop 1
	v_cndmask_b32_e64 v21, v21, v22, s[6:7]
	v_cmp_lt_f32_e64 s[6:7], 0, v25
	s_nop 1
	v_cndmask_b32_e64 v21, v21, v23, s[6:7]
	v_mul_f32_e32 v22, 0x37800000, v21
	v_cndmask_b32_e32 v21, v21, v22, vcc
	v_cmp_class_f32_e32 vcc, v20, v161
	s_nop 1
	v_cndmask_b32_e32 v20, v21, v20, vcc
	v_div_scale_f32 v21, s[6:7], v20, v20, 1.0
	v_rcp_f32_e32 v22, v21
	v_div_scale_f32 v23, vcc, 1.0, v20, 1.0
	v_fma_f32 v24, -v21, v22, 1.0
	v_fmac_f32_e32 v22, v24, v22
	v_mul_f32_e32 v24, v23, v22
	v_fma_f32 v25, -v21, v24, v23
	v_fmac_f32_e32 v24, v25, v22
	v_fma_f32 v21, -v21, v24, v23
	v_div_fmas_f32 v21, v21, v22, v24
	v_div_fixup_f32 v20, v21, v20, 1.0
	v_mov_b32_e32 v239, v20
	v_pk_mul_f32 v[14:15], v[14:15], v[20:21] op_sel_hi:[1,0]
	v_pk_mul_f32 v[16:17], v[16:17], v[20:21] op_sel_hi:[1,0]
	v_pk_mul_f32 v[10:11], v[10:11], v[20:21] op_sel_hi:[1,0]
	v_pk_mul_f32 v[12:13], v[12:13], v[20:21] op_sel_hi:[1,0]
	v_pk_mul_f32 v[6:7], v[6:7], v[20:21] op_sel_hi:[1,0]
	v_pk_mul_f32 v[8:9], v[8:9], v[20:21] op_sel_hi:[1,0]
	v_pk_mul_f32 v[2:3], v[2:3], v[20:21] op_sel_hi:[1,0]
	v_pk_mul_f32 v[4:5], v[4:5], v[20:21] op_sel_hi:[1,0]
	v_mul_f32_e32 v20, 0xbfb8aa3b, v14
	v_mul_f32_e32 v21, 0xbfb8aa3b, v15
	v_mul_f32_e32 v22, 0xbfb8aa3b, v16
	v_mul_f32_e32 v23, 0xbfb8aa3b, v17
	v_mul_f32_e32 v24, 0xbfb8aa3b, v10
	v_mul_f32_e32 v25, 0xbfb8aa3b, v11
	v_mul_f32_e32 v26, 0xbfb8aa3b, v12
	v_mul_f32_e32 v27, 0xbfb8aa3b, v13
	v_exp_f32_e32 v20, v20
	v_exp_f32_e32 v21, v21
	v_exp_f32_e32 v22, v22
	v_exp_f32_e32 v23, v23
	v_exp_f32_e32 v24, v24
	v_exp_f32_e32 v25, v25
	v_exp_f32_e32 v26, v26
	v_exp_f32_e32 v27, v27
	v_add_f32_e32 v20, 1.0, v20
	v_add_f32_e32 v21, 1.0, v21
	v_add_f32_e32 v22, 1.0, v22
	v_add_f32_e32 v23, 1.0, v23
	v_add_f32_e32 v24, 1.0, v24
	v_add_f32_e32 v25, 1.0, v25
	v_add_f32_e32 v26, 1.0, v26
	v_add_f32_e32 v27, 1.0, v27
	v_rcp_f32_e32 v20, v20
	v_rcp_f32_e32 v21, v21
	v_rcp_f32_e32 v22, v22
	v_rcp_f32_e32 v23, v23
	v_rcp_f32_e32 v24, v24
	v_rcp_f32_e32 v25, v25
	v_rcp_f32_e32 v26, v26
	v_rcp_f32_e32 v27, v27
	v_pk_mul_f32 v[14:15], v[14:15], v[20:21]
	v_pk_mul_f32 v[16:17], v[16:17], v[22:23]
	v_pk_mul_f32 v[10:11], v[10:11], v[24:25]
	v_pk_mul_f32 v[12:13], v[12:13], v[26:27]
	v_pk_mul_f32 v[6:7], v[6:7], v[14:15]
	v_pk_mul_f32 v[8:9], v[8:9], v[16:17]
	v_pk_mul_f32 v[10:11], v[2:3], v[10:11]
	v_pk_mul_f32 v[12:13], v[4:5], v[12:13]
	s_andn2_b64 vcc, exec, s[0:1]
	v_cvt_pk_bf16_f32 v2, v6, v7
	v_cvt_pk_bf16_f32 v3, v8, v9
	v_cvt_pk_bf16_f32 v4, v10, v11
	v_cvt_pk_bf16_f32 v5, v12, v13
	s_mov_b64 s[0:1], -1
	global_store_dwordx4 v[18:19], v[2:5], off
	s_branch .Lmy_p9_join
; __device__ __forceinline__ unsigned pk2(float lo, float hi) { const f32x2 v = {lo, hi}; const bf16x2_t b = __builtin_convertvector(v, bf16x2_t); return __builtin_bit_cast(unsigned, b); }
; __device__ __forceinline__ float frcp(float x) { return __builtin_amdgcn_rcpf(x); }
;     __device__ __forceinline__ void operator()(const f32x4 (&acc)[2][2][4][2], const Unit& u, int wr, int wc, int fr, int fq) const {
;         const int row0 = u.pm * 256 + wr * 64 + fr, col0 = u.pn * 128 + wc * 32 + 8 * fq;
; #pragma unroll
;         for (int ai = 0; ai < 2; ++ai)
; #pragma unroll
;             for (int m = 0; m < 4; ++m) {
;                 const int row = row0 + ai * 128 + m * 16; const float rs = row_rstd_q(ssq, row, fq);
;                 float h[8];
; #pragma unroll
;                 for (int n = 0; n < 2; ++n) {
;                     const f32x4 a = acc[ai][0][m][n] * rs, b = acc[ai][1][m][n] * rs;
; #pragma unroll
;                     for (int j = 0; j < 4; ++j) h[4 * n + j] = a[j] * frcp(1.0f + __expf(-a[j])) * b[j];
;                 }
;                 u32x4 w; w.x = pk2(h[0], h[1]); w.y = pk2(h[2], h[3]); w.z = pk2(h[4], h[5]); w.w = pk2(h[6], h[7]);
;                 *(u32x4*)(O + (size_t)row * FF_ + col0) = w;
;             }
.Lmy_p9_fast:
	v_lshl_add_u32 v152, s6, 8, v1
	v_mov_b64_e32 v[148:149], s[26:27]
	v_lshl_or_b32 v150, s7, 7, v155
	v_ashrrev_i32_e32 v151, 31, v150
	v_lshlrev_b64 v[150:151], 1, v[150:151]
	v_or_b32_e32 v166, 16, v152
	s_waitcnt lgkmcnt(0)
	v_mad_i64_i32 v[164:165], s[6:7], v152, s60, v[148:149]
	v_lshl_add_u64 v[164:165], v[164:165], 0, v[150:151]
	s_waitcnt lgkmcnt(0)
	s_nop 1
	s_nop 1
	s_nop 1
	s_nop 1
	v_mov_b32_e32 v170, v232
	v_pk_mul_f32 v[126:127], v[126:127], v[170:171] op_sel_hi:[1,0]
	v_pk_mul_f32 v[128:129], v[128:129], v[170:171] op_sel_hi:[1,0]
	v_pk_mul_f32 v[122:123], v[122:123], v[170:171] op_sel_hi:[1,0]
	v_pk_mul_f32 v[124:125], v[124:125], v[170:171] op_sel_hi:[1,0]
	v_pk_mul_f32 v[118:119], v[118:119], v[170:171] op_sel_hi:[1,0]
	v_pk_mul_f32 v[120:121], v[120:121], v[170:171] op_sel_hi:[1,0]
	v_pk_mul_f32 v[114:115], v[114:115], v[170:171] op_sel_hi:[1,0]
	v_pk_mul_f32 v[116:117], v[116:117], v[170:171] op_sel_hi:[1,0]
	v_mul_f32_e32 v163, 0xbfb8aa3b, v126
	v_mul_f32_e32 v167, 0xbfb8aa3b, v127
	v_mul_f32_e32 v170, 0xbfb8aa3b, v128
	v_mul_f32_e32 v171, 0xbfb8aa3b, v129
	v_mul_f32_e32 v172, 0xbfb8aa3b, v122
	v_mul_f32_e32 v173, 0xbfb8aa3b, v123
	v_mul_f32_e32 v174, 0xbfb8aa3b, v124
	v_mul_f32_e32 v175, 0xbfb8aa3b, v125
	v_exp_f32_e32 v163, v163
	v_exp_f32_e32 v167, v167
	v_exp_f32_e32 v170, v170
	v_exp_f32_e32 v171, v171
	v_exp_f32_e32 v172, v172
	v_exp_f32_e32 v173, v173
	v_exp_f32_e32 v174, v174
	v_exp_f32_e32 v175, v175
	v_add_f32_e32 v163, 1.0, v163
	v_add_f32_e32 v167, 1.0, v167
	v_add_f32_e32 v176, 1.0, v170
	v_add_f32_e32 v177, 1.0, v171
	v_add_f32_e32 v178, 1.0, v172
	v_add_f32_e32 v179, 1.0, v173
	v_add_f32_e32 v180, 1.0, v174
	v_add_f32_e32 v181, 1.0, v175
	v_rcp_f32_e32 v170, v163
	v_rcp_f32_e32 v171, v167
	v_rcp_f32_e32 v172, v176
	v_rcp_f32_e32 v173, v177
	v_rcp_f32_e32 v174, v178
	v_rcp_f32_e32 v175, v179
	v_rcp_f32_e32 v176, v180
	v_rcp_f32_e32 v177, v181
	v_pk_mul_f32 v[126:127], v[126:127], v[170:171]
	v_pk_mul_f32 v[128:129], v[128:129], v[172:173]
	v_pk_mul_f32 v[122:123], v[122:123], v[174:175]
	v_pk_mul_f32 v[124:125], v[124:125], v[176:177]
	v_pk_mul_f32 v[118:119], v[118:119], v[126:127]
	v_pk_mul_f32 v[120:121], v[120:121], v[128:129]
	v_pk_mul_f32 v[122:123], v[114:115], v[122:123]
	v_pk_mul_f32 v[124:125], v[116:117], v[124:125]
	v_cvt_pk_bf16_f32 v114, v118, v119
	v_cvt_pk_bf16_f32 v115, v120, v121
	v_cvt_pk_bf16_f32 v116, v122, v123
	v_cvt_pk_bf16_f32 v117, v124, v125
	global_store_dwordx4 v[164:165], v[114:117], off
	s_nop 1
	v_mad_i64_i32 v[116:117], s[6:7], v166, s60, v[148:149]
	v_lshl_add_u64 v[116:117], v[116:117], 0, v[150:151]
	s_waitcnt lgkmcnt(0)
	v_or_b32_e32 v114, 32, v152
	s_waitcnt lgkmcnt(0)
	s_nop 1
	s_nop 1
	s_nop 1
	s_nop 1
	v_mov_b32_e32 v120, v233
	v_pk_mul_f32 v[110:111], v[110:111], v[120:121] op_sel_hi:[1,0]
	v_pk_mul_f32 v[112:113], v[112:113], v[120:121] op_sel_hi:[1,0]
	v_pk_mul_f32 v[106:107], v[106:107], v[120:121] op_sel_hi:[1,0]
	v_pk_mul_f32 v[108:109], v[108:109], v[120:121] op_sel_hi:[1,0]
	v_pk_mul_f32 v[102:103], v[102:103], v[120:121] op_sel_hi:[1,0]
	v_pk_mul_f32 v[104:105], v[104:105], v[120:121] op_sel_hi:[1,0]
	v_pk_mul_f32 v[98:99], v[98:99], v[120:121] op_sel_hi:[1,0]
	v_pk_mul_f32 v[100:101], v[100:101], v[120:121] op_sel_hi:[1,0]
	v_mul_f32_e32 v115, 0xbfb8aa3b, v110
	v_mul_f32_e32 v120, 0xbfb8aa3b, v111
	v_mul_f32_e32 v121, 0xbfb8aa3b, v112
	v_mul_f32_e32 v122, 0xbfb8aa3b, v113
	v_mul_f32_e32 v123, 0xbfb8aa3b, v106
	v_mul_f32_e32 v124, 0xbfb8aa3b, v107
	v_mul_f32_e32 v125, 0xbfb8aa3b, v108
	v_mul_f32_e32 v126, 0xbfb8aa3b, v109
	v_exp_f32_e32 v115, v115
	v_exp_f32_e32 v120, v120
	v_exp_f32_e32 v121, v121
	v_exp_f32_e32 v122, v122
	v_exp_f32_e32 v123, v123
	v_exp_f32_e32 v124, v124
	v_exp_f32_e32 v125, v125
	v_exp_f32_e32 v126, v126
	v_add_f32_e32 v115, 1.0, v115
	v_add_f32_e32 v127, 1.0, v120
	v_add_f32_e32 v128, 1.0, v121
	v_add_f32_e32 v129, 1.0, v122
	v_add_f32_e32 v163, 1.0, v123
	v_add_f32_e32 v164, 1.0, v124
	v_add_f32_e32 v165, 1.0, v125
	v_add_f32_e32 v166, 1.0, v126
	v_rcp_f32_e32 v120, v115
	v_rcp_f32_e32 v121, v127
	v_rcp_f32_e32 v122, v128
	v_rcp_f32_e32 v123, v129
	v_rcp_f32_e32 v124, v163
	v_rcp_f32_e32 v125, v164
	v_rcp_f32_e32 v126, v165
	v_rcp_f32_e32 v127, v166
	v_pk_mul_f32 v[110:111], v[110:111], v[120:121]
	v_pk_mul_f32 v[112:113], v[112:113], v[122:123]
	v_pk_mul_f32 v[106:107], v[106:107], v[124:125]
	v_pk_mul_f32 v[108:109], v[108:109], v[126:127]
	v_pk_mul_f32 v[102:103], v[102:103], v[110:111]
	v_pk_mul_f32 v[104:105], v[104:105], v[112:113]
	v_pk_mul_f32 v[106:107], v[98:99], v[106:107]
	v_pk_mul_f32 v[108:109], v[100:101], v[108:109]
	v_cvt_pk_bf16_f32 v98, v102, v103
	v_cvt_pk_bf16_f32 v99, v104, v105
	v_cvt_pk_bf16_f32 v100, v106, v107
	v_cvt_pk_bf16_f32 v101, v108, v109
	global_store_dwordx4 v[116:117], v[98:101], off
	s_nop 1
	v_mad_i64_i32 v[100:101], s[6:7], v114, s60, v[148:149]
	v_lshl_add_u64 v[100:101], v[100:101], 0, v[150:151]
	s_waitcnt lgkmcnt(0)
	v_or_b32_e32 v98, 48, v152
	s_waitcnt lgkmcnt(0)
; __device__ __forceinline__ unsigned pk2(float lo, float hi) { const f32x2 v = {lo, hi}; const bf16x2_t b = __builtin_convertvector(v, bf16x2_t); return __builtin_bit_cast(unsigned, b); }
; __device__ __forceinline__ float frcp(float x) { return __builtin_amdgcn_rcpf(x); }
;     __device__ __forceinline__ void operator()(const f32x4 (&acc)[2][2][4][2], const Unit& u, int wr, int wc, int fr, int fq) const {
;         const int row0 = u.pm * 256 + wr * 64 + fr, col0 = u.pn * 128 + wc * 32 + 8 * fq;
; #pragma unroll
;         for (int ai = 0; ai < 2; ++ai)
; #pragma unroll
;             for (int m = 0; m < 4; ++m) {
;                 const int row = row0 + ai * 128 + m * 16; const float rs = row_rstd_q(ssq, row, fq);
;                 float h[8];
; #pragma unroll
;                 for (int n = 0; n < 2; ++n) {
;                     const f32x4 a = acc[ai][0][m][n] * rs, b = acc[ai][1][m][n] * rs;
; #pragma unroll
;                     for (int j = 0; j < 4; ++j) h[4 * n + j] = a[j] * frcp(1.0f + __expf(-a[j])) * b[j];
;                 }
;                 u32x4 w; w.x = pk2(h[0], h[1]); w.y = pk2(h[2], h[3]); w.z = pk2(h[4], h[5]); w.w = pk2(h[6], h[7]);
;                 *(u32x4*)(O + (size_t)row * FF_ + col0) = w;
;             }
	s_nop 1
	s_nop 1
	s_nop 1
	s_nop 1
	v_mov_b32_e32 v104, v234
	v_pk_mul_f32 v[94:95], v[94:95], v[104:105] op_sel_hi:[1,0]
	v_pk_mul_f32 v[96:97], v[96:97], v[104:105] op_sel_hi:[1,0]
	v_pk_mul_f32 v[90:91], v[90:91], v[104:105] op_sel_hi:[1,0]
	v_pk_mul_f32 v[92:93], v[92:93], v[104:105] op_sel_hi:[1,0]
	v_pk_mul_f32 v[86:87], v[86:87], v[104:105] op_sel_hi:[1,0]
	v_pk_mul_f32 v[88:89], v[88:89], v[104:105] op_sel_hi:[1,0]
	v_pk_mul_f32 v[82:83], v[82:83], v[104:105] op_sel_hi:[1,0]
	v_pk_mul_f32 v[84:85], v[84:85], v[104:105] op_sel_hi:[1,0]
	v_mul_f32_e32 v99, 0xbfb8aa3b, v94
	v_mul_f32_e32 v104, 0xbfb8aa3b, v95
	v_mul_f32_e32 v105, 0xbfb8aa3b, v96
	v_mul_f32_e32 v106, 0xbfb8aa3b, v97
	v_mul_f32_e32 v107, 0xbfb8aa3b, v90
	v_mul_f32_e32 v108, 0xbfb8aa3b, v91
	v_mul_f32_e32 v109, 0xbfb8aa3b, v92
	v_mul_f32_e32 v110, 0xbfb8aa3b, v93
	v_exp_f32_e32 v99, v99
	v_exp_f32_e32 v104, v104
	v_exp_f32_e32 v105, v105
	v_exp_f32_e32 v106, v106
	v_exp_f32_e32 v107, v107
	v_exp_f32_e32 v108, v108
	v_exp_f32_e32 v109, v109
	v_exp_f32_e32 v110, v110
	v_add_f32_e32 v99, 1.0, v99
	v_add_f32_e32 v111, 1.0, v104
	v_add_f32_e32 v112, 1.0, v105
	v_add_f32_e32 v113, 1.0, v106
	v_add_f32_e32 v114, 1.0, v107
	v_add_f32_e32 v115, 1.0, v108
	v_add_f32_e32 v116, 1.0, v109
	v_add_f32_e32 v117, 1.0, v110
	v_rcp_f32_e32 v104, v99
	v_rcp_f32_e32 v105, v111
	v_rcp_f32_e32 v106, v112
	v_rcp_f32_e32 v107, v113
	v_rcp_f32_e32 v108, v114
	v_rcp_f32_e32 v109, v115
	v_rcp_f32_e32 v110, v116
	v_rcp_f32_e32 v111, v117
	v_pk_mul_f32 v[94:95], v[94:95], v[104:105]
	v_pk_mul_f32 v[96:97], v[96:97], v[106:107]
	v_pk_mul_f32 v[90:91], v[90:91], v[108:109]
	v_pk_mul_f32 v[92:93], v[92:93], v[110:111]
	v_pk_mul_f32 v[86:87], v[86:87], v[94:95]
	v_pk_mul_f32 v[88:89], v[88:89], v[96:97]
	v_pk_mul_f32 v[90:91], v[82:83], v[90:91]
	v_pk_mul_f32 v[92:93], v[84:85], v[92:93]
	v_cvt_pk_bf16_f32 v82, v86, v87
	v_cvt_pk_bf16_f32 v83, v88, v89
	v_cvt_pk_bf16_f32 v84, v90, v91
	v_cvt_pk_bf16_f32 v85, v92, v93
	global_store_dwordx4 v[100:101], v[82:85], off
	s_nop 1
	v_mad_i64_i32 v[84:85], s[6:7], v98, s60, v[148:149]
	v_lshl_add_u64 v[84:85], v[84:85], 0, v[150:151]
	s_waitcnt lgkmcnt(0)
	v_add_u32_e32 v82, 0x80, v152
	s_waitcnt lgkmcnt(0)
	s_nop 1
	s_nop 1
	s_nop 1
	s_nop 1
	v_mov_b32_e32 v88, v235
	v_pk_mul_f32 v[78:79], v[78:79], v[88:89] op_sel_hi:[1,0]
	v_pk_mul_f32 v[80:81], v[80:81], v[88:89] op_sel_hi:[1,0]
	v_pk_mul_f32 v[74:75], v[74:75], v[88:89] op_sel_hi:[1,0]
	v_pk_mul_f32 v[76:77], v[76:77], v[88:89] op_sel_hi:[1,0]
	v_pk_mul_f32 v[70:71], v[70:71], v[88:89] op_sel_hi:[1,0]
	v_pk_mul_f32 v[72:73], v[72:73], v[88:89] op_sel_hi:[1,0]
	v_pk_mul_f32 v[66:67], v[66:67], v[88:89] op_sel_hi:[1,0]
	v_pk_mul_f32 v[68:69], v[68:69], v[88:89] op_sel_hi:[1,0]
	v_mul_f32_e32 v83, 0xbfb8aa3b, v78
	v_mul_f32_e32 v88, 0xbfb8aa3b, v79
	v_mul_f32_e32 v89, 0xbfb8aa3b, v80
	v_mul_f32_e32 v90, 0xbfb8aa3b, v81
	v_mul_f32_e32 v91, 0xbfb8aa3b, v74
	v_mul_f32_e32 v92, 0xbfb8aa3b, v75
	v_mul_f32_e32 v93, 0xbfb8aa3b, v76
	v_mul_f32_e32 v94, 0xbfb8aa3b, v77
	v_exp_f32_e32 v83, v83
	v_exp_f32_e32 v88, v88
	v_exp_f32_e32 v89, v89
	v_exp_f32_e32 v90, v90
	v_exp_f32_e32 v91, v91
	v_exp_f32_e32 v92, v92
	v_exp_f32_e32 v93, v93
	v_exp_f32_e32 v94, v94
	v_add_f32_e32 v83, 1.0, v83
	v_add_f32_e32 v95, 1.0, v88
	v_add_f32_e32 v96, 1.0, v89
	v_add_f32_e32 v97, 1.0, v90
	v_add_f32_e32 v98, 1.0, v91
	v_add_f32_e32 v99, 1.0, v92
	v_add_f32_e32 v100, 1.0, v93
	v_add_f32_e32 v101, 1.0, v94
	v_rcp_f32_e32 v88, v83
	v_rcp_f32_e32 v89, v95
	v_rcp_f32_e32 v90, v96
	v_rcp_f32_e32 v91, v97
	v_rcp_f32_e32 v92, v98
	v_rcp_f32_e32 v93, v99
	v_rcp_f32_e32 v94, v100
	v_rcp_f32_e32 v95, v101
	v_pk_mul_f32 v[78:79], v[78:79], v[88:89]
	v_pk_mul_f32 v[80:81], v[80:81], v[90:91]
	v_pk_mul_f32 v[74:75], v[74:75], v[92:93]
	v_pk_mul_f32 v[76:77], v[76:77], v[94:95]
	v_pk_mul_f32 v[70:71], v[70:71], v[78:79]
	v_pk_mul_f32 v[72:73], v[72:73], v[80:81]
	v_pk_mul_f32 v[74:75], v[66:67], v[74:75]
	v_pk_mul_f32 v[76:77], v[68:69], v[76:77]
	v_cvt_pk_bf16_f32 v66, v70, v71
	v_cvt_pk_bf16_f32 v67, v72, v73
	v_cvt_pk_bf16_f32 v68, v74, v75
	v_cvt_pk_bf16_f32 v69, v76, v77
	global_store_dwordx4 v[84:85], v[66:69], off
	s_nop 1
	v_mad_i64_i32 v[68:69], s[6:7], v82, s60, v[148:149]
	v_lshl_add_u64 v[68:69], v[68:69], 0, v[150:151]
	s_waitcnt lgkmcnt(0)
	v_add_u32_e32 v66, 0x90, v152
	s_waitcnt lgkmcnt(0)
	s_nop 1
	s_nop 1
	s_nop 1
	s_nop 1
	v_mov_b32_e32 v72, v236
	v_pk_mul_f32 v[62:63], v[62:63], v[72:73] op_sel_hi:[1,0]
	v_pk_mul_f32 v[64:65], v[64:65], v[72:73] op_sel_hi:[1,0]
	v_pk_mul_f32 v[58:59], v[58:59], v[72:73] op_sel_hi:[1,0]
	v_pk_mul_f32 v[60:61], v[60:61], v[72:73] op_sel_hi:[1,0]
	v_pk_mul_f32 v[54:55], v[54:55], v[72:73] op_sel_hi:[1,0]
	v_pk_mul_f32 v[56:57], v[56:57], v[72:73] op_sel_hi:[1,0]
	v_pk_mul_f32 v[50:51], v[50:51], v[72:73] op_sel_hi:[1,0]
	v_pk_mul_f32 v[52:53], v[52:53], v[72:73] op_sel_hi:[1,0]
	v_mul_f32_e32 v67, 0xbfb8aa3b, v62
	v_mul_f32_e32 v72, 0xbfb8aa3b, v63
	v_mul_f32_e32 v73, 0xbfb8aa3b, v64
	v_mul_f32_e32 v74, 0xbfb8aa3b, v65
	v_mul_f32_e32 v75, 0xbfb8aa3b, v58
	v_mul_f32_e32 v76, 0xbfb8aa3b, v59
	v_mul_f32_e32 v77, 0xbfb8aa3b, v60
	v_mul_f32_e32 v78, 0xbfb8aa3b, v61
	v_exp_f32_e32 v67, v67
	v_exp_f32_e32 v72, v72
	v_exp_f32_e32 v73, v73
	v_exp_f32_e32 v74, v74
	v_exp_f32_e32 v75, v75
	v_exp_f32_e32 v76, v76
	v_exp_f32_e32 v77, v77
	v_exp_f32_e32 v78, v78
	v_add_f32_e32 v67, 1.0, v67
	v_add_f32_e32 v79, 1.0, v72
	v_add_f32_e32 v80, 1.0, v73
	v_add_f32_e32 v81, 1.0, v74
	v_add_f32_e32 v82, 1.0, v75
	v_add_f32_e32 v83, 1.0, v76
	v_add_f32_e32 v84, 1.0, v77
	v_add_f32_e32 v85, 1.0, v78
	v_rcp_f32_e32 v72, v67
	v_rcp_f32_e32 v73, v79
	v_rcp_f32_e32 v74, v80
	v_rcp_f32_e32 v75, v81
	v_rcp_f32_e32 v76, v82
	v_rcp_f32_e32 v77, v83
	v_rcp_f32_e32 v78, v84
	v_rcp_f32_e32 v79, v85
	v_pk_mul_f32 v[62:63], v[62:63], v[72:73]
	v_pk_mul_f32 v[64:65], v[64:65], v[74:75]
	v_pk_mul_f32 v[58:59], v[58:59], v[76:77]
	v_pk_mul_f32 v[60:61], v[60:61], v[78:79]
	v_pk_mul_f32 v[54:55], v[54:55], v[62:63]
	v_pk_mul_f32 v[56:57], v[56:57], v[64:65]
	v_pk_mul_f32 v[58:59], v[50:51], v[58:59]
	v_pk_mul_f32 v[60:61], v[52:53], v[60:61]
	v_cvt_pk_bf16_f32 v50, v54, v55
	v_cvt_pk_bf16_f32 v51, v56, v57
	v_cvt_pk_bf16_f32 v52, v58, v59
	v_cvt_pk_bf16_f32 v53, v60, v61
	global_store_dwordx4 v[68:69], v[50:53], off
	s_nop 1
	v_mad_i64_i32 v[52:53], s[6:7], v66, s60, v[148:149]
	v_lshl_add_u64 v[52:53], v[52:53], 0, v[150:151]
	s_waitcnt lgkmcnt(0)
; __device__ __forceinline__ unsigned pk2(float lo, float hi) { const f32x2 v = {lo, hi}; const bf16x2_t b = __builtin_convertvector(v, bf16x2_t); return __builtin_bit_cast(unsigned, b); }
; __device__ __forceinline__ float frcp(float x) { return __builtin_amdgcn_rcpf(x); }
;     __device__ __forceinline__ void operator()(const f32x4 (&acc)[2][2][4][2], const Unit& u, int wr, int wc, int fr, int fq) const {
;         const int row0 = u.pm * 256 + wr * 64 + fr, col0 = u.pn * 128 + wc * 32 + 8 * fq;
; #pragma unroll
;         for (int ai = 0; ai < 2; ++ai)
; #pragma unroll
;             for (int m = 0; m < 4; ++m) {
;                 const int row = row0 + ai * 128 + m * 16; const float rs = row_rstd_q(ssq, row, fq);
;                 float h[8];
; #pragma unroll
;                 for (int n = 0; n < 2; ++n) {
;                     const f32x4 a = acc[ai][0][m][n] * rs, b = acc[ai][1][m][n] * rs;
; #pragma unroll
;                     for (int j = 0; j < 4; ++j) h[4 * n + j] = a[j] * frcp(1.0f + __expf(-a[j])) * b[j];
;                 }
;                 u32x4 w; w.x = pk2(h[0], h[1]); w.y = pk2(h[2], h[3]); w.z = pk2(h[4], h[5]); w.w = pk2(h[6], h[7]);
;                 *(u32x4*)(O + (size_t)row * FF_ + col0) = w;
;             }
	v_add_u32_e32 v50, 0xa0, v152
	s_waitcnt lgkmcnt(0)
	s_nop 1
	s_nop 1
	s_nop 1
	s_nop 1
	v_mov_b32_e32 v56, v237
	v_pk_mul_f32 v[46:47], v[46:47], v[56:57] op_sel_hi:[1,0]
	v_pk_mul_f32 v[48:49], v[48:49], v[56:57] op_sel_hi:[1,0]
	v_pk_mul_f32 v[42:43], v[42:43], v[56:57] op_sel_hi:[1,0]
	v_pk_mul_f32 v[44:45], v[44:45], v[56:57] op_sel_hi:[1,0]
	v_pk_mul_f32 v[38:39], v[38:39], v[56:57] op_sel_hi:[1,0]
	v_pk_mul_f32 v[40:41], v[40:41], v[56:57] op_sel_hi:[1,0]
	v_pk_mul_f32 v[34:35], v[34:35], v[56:57] op_sel_hi:[1,0]
	v_pk_mul_f32 v[36:37], v[36:37], v[56:57] op_sel_hi:[1,0]
	v_mul_f32_e32 v51, 0xbfb8aa3b, v46
	v_mul_f32_e32 v56, 0xbfb8aa3b, v47
	v_mul_f32_e32 v57, 0xbfb8aa3b, v48
	v_mul_f32_e32 v58, 0xbfb8aa3b, v49
	v_mul_f32_e32 v59, 0xbfb8aa3b, v42
	v_mul_f32_e32 v60, 0xbfb8aa3b, v43
	v_mul_f32_e32 v61, 0xbfb8aa3b, v44
	v_mul_f32_e32 v62, 0xbfb8aa3b, v45
	v_exp_f32_e32 v51, v51
	v_exp_f32_e32 v56, v56
	v_exp_f32_e32 v57, v57
	v_exp_f32_e32 v58, v58
	v_exp_f32_e32 v59, v59
	v_exp_f32_e32 v60, v60
	v_exp_f32_e32 v61, v61
	v_exp_f32_e32 v62, v62
	v_add_f32_e32 v51, 1.0, v51
	v_add_f32_e32 v63, 1.0, v56
	v_add_f32_e32 v64, 1.0, v57
	v_add_f32_e32 v65, 1.0, v58
	v_add_f32_e32 v66, 1.0, v59
	v_add_f32_e32 v67, 1.0, v60
	v_add_f32_e32 v68, 1.0, v61
	v_add_f32_e32 v69, 1.0, v62
	v_rcp_f32_e32 v56, v51
	v_rcp_f32_e32 v57, v63
	v_rcp_f32_e32 v58, v64
	v_rcp_f32_e32 v59, v65
	v_rcp_f32_e32 v60, v66
	v_rcp_f32_e32 v61, v67
	v_rcp_f32_e32 v62, v68
	v_rcp_f32_e32 v63, v69
	v_pk_mul_f32 v[46:47], v[46:47], v[56:57]
	v_pk_mul_f32 v[48:49], v[48:49], v[58:59]
	v_pk_mul_f32 v[42:43], v[42:43], v[60:61]
	v_pk_mul_f32 v[44:45], v[44:45], v[62:63]
	v_pk_mul_f32 v[38:39], v[38:39], v[46:47]
	v_pk_mul_f32 v[40:41], v[40:41], v[48:49]
	v_pk_mul_f32 v[42:43], v[34:35], v[42:43]
	v_pk_mul_f32 v[44:45], v[36:37], v[44:45]
	v_cvt_pk_bf16_f32 v34, v38, v39
	v_cvt_pk_bf16_f32 v35, v40, v41
	v_cvt_pk_bf16_f32 v36, v42, v43
	v_cvt_pk_bf16_f32 v37, v44, v45
	global_store_dwordx4 v[52:53], v[34:37], off
	s_nop 1
	v_mad_i64_i32 v[36:37], s[6:7], v50, s60, v[148:149]
	v_lshl_add_u64 v[36:37], v[36:37], 0, v[150:151]
	s_waitcnt lgkmcnt(0)
	v_add_u32_e32 v34, 0xb0, v152
	s_waitcnt lgkmcnt(0)
	s_nop 1
	s_nop 1
	s_nop 1
	s_nop 1
	v_mov_b32_e32 v40, v238
	v_pk_mul_f32 v[30:31], v[30:31], v[40:41] op_sel_hi:[1,0]
	v_pk_mul_f32 v[32:33], v[32:33], v[40:41] op_sel_hi:[1,0]
	v_pk_mul_f32 v[26:27], v[26:27], v[40:41] op_sel_hi:[1,0]
	v_pk_mul_f32 v[28:29], v[28:29], v[40:41] op_sel_hi:[1,0]
	v_pk_mul_f32 v[22:23], v[22:23], v[40:41] op_sel_hi:[1,0]
	v_pk_mul_f32 v[24:25], v[24:25], v[40:41] op_sel_hi:[1,0]
	v_pk_mul_f32 v[18:19], v[18:19], v[40:41] op_sel_hi:[1,0]
	v_pk_mul_f32 v[20:21], v[20:21], v[40:41] op_sel_hi:[1,0]
	v_mul_f32_e32 v35, 0xbfb8aa3b, v30
	v_mul_f32_e32 v40, 0xbfb8aa3b, v31
	v_mul_f32_e32 v41, 0xbfb8aa3b, v32
	v_mul_f32_e32 v42, 0xbfb8aa3b, v33
	v_mul_f32_e32 v43, 0xbfb8aa3b, v26
	v_mul_f32_e32 v44, 0xbfb8aa3b, v27
	v_mul_f32_e32 v45, 0xbfb8aa3b, v28
	v_mul_f32_e32 v46, 0xbfb8aa3b, v29
	v_exp_f32_e32 v35, v35
	v_exp_f32_e32 v40, v40
	v_exp_f32_e32 v41, v41
	v_exp_f32_e32 v42, v42
	v_exp_f32_e32 v43, v43
	v_exp_f32_e32 v44, v44
	v_exp_f32_e32 v45, v45
	v_exp_f32_e32 v46, v46
	v_add_f32_e32 v35, 1.0, v35
	v_add_f32_e32 v47, 1.0, v40
	v_add_f32_e32 v48, 1.0, v41
	v_add_f32_e32 v49, 1.0, v42
	v_add_f32_e32 v50, 1.0, v43
	v_add_f32_e32 v51, 1.0, v44
	v_add_f32_e32 v52, 1.0, v45
	v_add_f32_e32 v53, 1.0, v46
	v_rcp_f32_e32 v40, v35
	v_rcp_f32_e32 v41, v47
	v_rcp_f32_e32 v42, v48
	v_rcp_f32_e32 v43, v49
	v_rcp_f32_e32 v44, v50
	v_rcp_f32_e32 v45, v51
	v_rcp_f32_e32 v46, v52
	v_rcp_f32_e32 v47, v53
	v_pk_mul_f32 v[30:31], v[30:31], v[40:41]
	v_pk_mul_f32 v[32:33], v[32:33], v[42:43]
	v_pk_mul_f32 v[26:27], v[26:27], v[44:45]
	v_pk_mul_f32 v[28:29], v[28:29], v[46:47]
	v_pk_mul_f32 v[22:23], v[22:23], v[30:31]
	v_pk_mul_f32 v[24:25], v[24:25], v[32:33]
	v_pk_mul_f32 v[26:27], v[18:19], v[26:27]
	v_pk_mul_f32 v[28:29], v[20:21], v[28:29]
	v_cvt_pk_bf16_f32 v18, v22, v23
	v_cvt_pk_bf16_f32 v19, v24, v25
	v_cvt_pk_bf16_f32 v20, v26, v27
	v_cvt_pk_bf16_f32 v21, v28, v29
	global_store_dwordx4 v[36:37], v[18:21], off
	s_nop 1
	s_nop 0
	s_waitcnt lgkmcnt(0)
	s_waitcnt lgkmcnt(0)
	s_nop 1
	v_mad_i64_i32 v[18:19], s[6:7], v34, s60, v[148:149]
	v_lshl_add_u64 v[18:19], v[18:19], 0, v[150:151]
	s_nop 1
	s_nop 1
	s_nop 1
	v_mov_b32_e32 v20, v239
	v_pk_mul_f32 v[14:15], v[14:15], v[20:21] op_sel_hi:[1,0]
	v_pk_mul_f32 v[16:17], v[16:17], v[20:21] op_sel_hi:[1,0]
	v_pk_mul_f32 v[10:11], v[10:11], v[20:21] op_sel_hi:[1,0]
	v_pk_mul_f32 v[12:13], v[12:13], v[20:21] op_sel_hi:[1,0]
	v_pk_mul_f32 v[6:7], v[6:7], v[20:21] op_sel_hi:[1,0]
	v_pk_mul_f32 v[8:9], v[8:9], v[20:21] op_sel_hi:[1,0]
	v_pk_mul_f32 v[2:3], v[2:3], v[20:21] op_sel_hi:[1,0]
	v_pk_mul_f32 v[4:5], v[4:5], v[20:21] op_sel_hi:[1,0]
	v_mul_f32_e32 v20, 0xbfb8aa3b, v14
	v_mul_f32_e32 v21, 0xbfb8aa3b, v15
	v_mul_f32_e32 v22, 0xbfb8aa3b, v16
	v_mul_f32_e32 v23, 0xbfb8aa3b, v17
	v_mul_f32_e32 v24, 0xbfb8aa3b, v10
	v_mul_f32_e32 v25, 0xbfb8aa3b, v11
	v_mul_f32_e32 v26, 0xbfb8aa3b, v12
	v_mul_f32_e32 v27, 0xbfb8aa3b, v13
	v_exp_f32_e32 v20, v20
	v_exp_f32_e32 v21, v21
	v_exp_f32_e32 v22, v22
	v_exp_f32_e32 v23, v23
	v_exp_f32_e32 v24, v24
	v_exp_f32_e32 v25, v25
	v_exp_f32_e32 v26, v26
	v_exp_f32_e32 v27, v27
	v_add_f32_e32 v20, 1.0, v20
	v_add_f32_e32 v21, 1.0, v21
	v_add_f32_e32 v22, 1.0, v22
	v_add_f32_e32 v23, 1.0, v23
	v_add_f32_e32 v24, 1.0, v24
	v_add_f32_e32 v25, 1.0, v25
	v_add_f32_e32 v26, 1.0, v26
	v_add_f32_e32 v27, 1.0, v27
	v_rcp_f32_e32 v20, v20
	v_rcp_f32_e32 v21, v21
	v_rcp_f32_e32 v22, v22
	v_rcp_f32_e32 v23, v23
	v_rcp_f32_e32 v24, v24
	v_rcp_f32_e32 v25, v25
	v_rcp_f32_e32 v26, v26
	v_rcp_f32_e32 v27, v27
	v_pk_mul_f32 v[14:15], v[14:15], v[20:21]
	v_pk_mul_f32 v[16:17], v[16:17], v[22:23]
	v_pk_mul_f32 v[10:11], v[10:11], v[24:25]
	v_pk_mul_f32 v[12:13], v[12:13], v[26:27]
	v_pk_mul_f32 v[6:7], v[6:7], v[14:15]
	v_pk_mul_f32 v[8:9], v[8:9], v[16:17]
	v_pk_mul_f32 v[10:11], v[2:3], v[10:11]
	v_pk_mul_f32 v[12:13], v[4:5], v[12:13]
	s_andn2_b64 vcc, exec, s[0:1]
	v_cvt_pk_bf16_f32 v2, v6, v7
	v_cvt_pk_bf16_f32 v3, v8, v9
	v_cvt_pk_bf16_f32 v4, v10, v11
	v_cvt_pk_bf16_f32 v5, v12, v13
	s_mov_b64 s[0:1], -1
	global_store_dwordx4 v[18:19], v[2:5], off
	s_nop 1
.Lmy_p9_join:
	s_cbranch_vccnz .LBB0_1358
	s_andn2_b64 vcc, exec, s[10:11]
	s_cbranch_vccnz .LBB0_1357
	s_barrier
	s_branch .LBB0_1357
